# in-proj: 48 leftover tiles run as 192 quarter units (separate quarter K-loop copy); log-forget scans spread over workgroups 192-255 (up to 3 waves each) instead of 20 full workgroups
# speedup vs baseline: 1.0167x; 1.0167x over previous
; DI void scan_unit(const Params& p, int su) {
;     const int lane = threadIdx.x & 63, wave = threadIdx.x >> 6;
;     const int seq = su * NW + wave;
;     const int e0 = lane * 65;
;     float vals[65];
;     if (seq < 32) {
;         const int b = seq >> 3, h = seq & 7;
;         const float* src = p.out + O_PBL + (size_t)b * LP * 8 + h;
;         float* dst = p.c2p + (size_t)seq * LPAD;
; #pragma unroll
;         for (int i = 0; i < 65; ++i) { const int e = e0 + i; vals[i] = src[(size_t)(e < LP ? e : LP - 1) * 8]; }
;         float s = 0.f;
; #pragma unroll
;         for (int i = 0; i < 65; ++i) s += (e0 + i < LP) ? vals[i] : 0.f;
;         float incl = s;
; #pragma unroll
;         for (int o = 1; o < 64; o <<= 1) { const float t = __shfl_up(incl, o); if (lane >= o) incl += t; }
;         float run = incl - s;
; #pragma unroll
;         for (int i = 0; i < 65; ++i) { const int e = e0 + i; if (e < LP) { run += vals[i]; dst[e] = run * LOG2E; } else dst[e] = 0.f; }
;     } else {
;         const int sq = seq - 32, bb = sq >> 3, h = sq & 7;
;         const float* src0 = p.cbl + (size_t)bb * PAST * 8 + h;
;         const float* src1 = p.out + O_SBL + (size_t)bb * DSQ * 8 + h;
;         float* dst = p.c2s + (size_t)sq * LSK;
; #pragma unroll
;         for (int i = 0; i < 65; ++i) {
;             const int e = e0 + i, ec = e < LSK ? e : LSK - 1;
;             const float* pe = ec < PAST ? src0 + (size_t)ec * 8 : src1 + (size_t)(ec - PAST) * 8;
;             vals[i] = *pe;
;         }
; __global__ void __launch_bounds__(512, 2) hymba_mega(Params p) {
;     ...
;         const int su = (int)gridDim.x - 1 - (int)blockIdx.x;
;         if (su < 20) scan_unit(p, su);
.LBB0_115:
	s_or_b64 exec, exec, s[4:5]
	s_waitcnt lgkmcnt(0)
	s_barrier
	s_load_dword s33, s[0:1], 0xc8
	s_add_u32 s44, s0, 0xc8
	s_addc_u32 s45, s1, 0
	s_not_b32 s0, s2
	v_lshrrev_b32_e32 v166, 6, v138
	s_waitcnt lgkmcnt(0)
	s_add_i32 s0, s33, s0
	s_cmp_gt_i32 s0, 63
	s_cbranch_scc1 .LBB0_127
	v_and_b32_e32 v10, 63, v138
	v_lshl_add_u32 v6, v166, 6, s0
	s_nop 1
	v_readfirstlane_b32 s1, v6
	s_nop 0
	s_cmpk_gt_u32 s1, 0x9f
	s_cbranch_scc1 .LBB0_127
	v_mul_u32_u24_e32 v1, 0x41, v10
	v_cmp_lt_i32_e32 vcc, 31, v6
	v_lshlrev_b32_e32 v4, 2, v6
	v_lshlrev_b32_e32 v44, 5, v1
	s_and_saveexec_b64 s[0:1], vcc
	s_xor_b64 s[4:5], exec, s[0:1]
	s_cbranch_execz .LBB0_120
	v_subrev_u32_e32 v11, 32, v6
	v_lshrrev_b32_e32 v2, 3, v11
	v_mov_b32_e32 v3, 0
	v_lshlrev_b64 v[6:7], 17, v[2:3]
	v_lshl_add_u64 v[6:7], s[88:89], 0, v[6:7]
	v_and_b32_e32 v8, 28, v4
	v_mov_b32_e32 v9, v3
	v_lshl_add_u64 v[4:5], v[6:7], 0, v[8:9]
	v_lshlrev_b64 v[6:7], 10, v[2:3]
	v_mul_u32_u24_e32 v2, 0x208, v10
	v_lshl_add_u64 v[6:7], s[54:55], 0, v[6:7]
	v_lshlrev_b32_e32 v2, 2, v2
	v_lshl_add_u64 v[6:7], v[6:7], 0, v[8:9]
	s_mov_b64 s[0:1], 0xc700800
	v_lshl_add_u64 v[8:9], v[4:5], 0, v[2:3]
	v_lshl_add_u64 v[14:15], v[6:7], 0, s[0:1]
	v_lshl_add_u64 v[16:17], v[8:9], 0, 32
	v_cmp_eq_u32_e32 vcc, 63, v10
	v_add_u32_e32 v2, 64, v44
	s_mov_b64 s[0:1], 0xc700820
	v_cndmask_b32_e32 v15, v17, v15, vcc
	v_cndmask_b32_e32 v14, v16, v14, vcc
	global_load_dword v13, v[14:15], off
	v_lshl_add_u64 v[14:15], v[4:5], 0, v[2:3]
	v_lshl_add_u64 v[16:17], v[6:7], 0, s[0:1]
	s_mov_b64 s[0:1], 0x60
	v_cndmask_b32_e32 v15, v15, v17, vcc
	v_cndmask_b32_e32 v14, v14, v16, vcc
	v_lshl_add_u64 v[16:17], v[8:9], 0, s[0:1]
	s_mov_b64 s[0:1], 0xc700840
	v_lshl_add_u64 v[18:19], v[6:7], 0, s[0:1]
	v_cndmask_b32_e32 v17, v17, v19, vcc
	v_cndmask_b32_e32 v16, v16, v18, vcc
	v_add_u32_e32 v2, 0x80, v44
	s_mov_b64 s[0:1], 0xc700860
	global_load_dword v14, v[14:15], off
	v_lshl_add_u64 v[18:19], v[6:7], 0, s[0:1]
	global_load_dword v15, v[16:17], off
	v_lshl_add_u64 v[16:17], v[4:5], 0, v[2:3]
	s_mov_b64 s[0:1], 0xa0
	v_cndmask_b32_e32 v17, v17, v19, vcc
	v_cndmask_b32_e32 v16, v16, v18, vcc
	v_lshl_add_u64 v[18:19], v[8:9], 0, s[0:1]
	s_mov_b64 s[0:1], 0xc700880
	v_lshl_add_u64 v[20:21], v[6:7], 0, s[0:1]
	v_cndmask_b32_e32 v19, v19, v21, vcc
	v_cndmask_b32_e32 v18, v18, v20, vcc
	v_add_u32_e32 v2, 0xc0, v44
	s_mov_b64 s[0:1], 0xc7008a0
	global_load_dword v16, v[16:17], off
	v_lshl_add_u64 v[20:21], v[6:7], 0, s[0:1]
	global_load_dword v17, v[18:19], off
	v_lshl_add_u64 v[18:19], v[4:5], 0, v[2:3]
	s_mov_b64 s[0:1], 0xe0
	v_cndmask_b32_e32 v19, v19, v21, vcc
	v_cndmask_b32_e32 v18, v18, v20, vcc
	v_lshl_add_u64 v[20:21], v[8:9], 0, s[0:1]
	s_mov_b64 s[0:1], 0xc7008c0
	v_lshl_add_u64 v[22:23], v[6:7], 0, s[0:1]
	v_cndmask_b32_e32 v21, v21, v23, vcc
	v_cndmask_b32_e32 v20, v20, v22, vcc
	v_add_u32_e32 v2, 0x100, v44
	s_mov_b64 s[0:1], 0xc7008e0
	global_load_dword v18, v[18:19], off
	v_lshl_add_u64 v[22:23], v[6:7], 0, s[0:1]
	global_load_dword v19, v[20:21], off
	v_lshl_add_u64 v[20:21], v[4:5], 0, v[2:3]
	s_mov_b64 s[0:1], 0x120
	v_cndmask_b32_e32 v21, v21, v23, vcc
	v_cndmask_b32_e32 v20, v20, v22, vcc
	v_lshl_add_u64 v[22:23], v[8:9], 0, s[0:1]
	s_mov_b64 s[0:1], 0xc700900
	v_lshl_add_u64 v[24:25], v[6:7], 0, s[0:1]
	v_cndmask_b32_e32 v23, v23, v25, vcc
	v_cndmask_b32_e32 v22, v22, v24, vcc
	v_add_u32_e32 v2, 0x140, v44
	s_mov_b64 s[0:1], 0xc700920
	global_load_dword v20, v[20:21], off
	v_lshl_add_u64 v[24:25], v[6:7], 0, s[0:1]
	global_load_dword v21, v[22:23], off
	v_lshl_add_u64 v[22:23], v[4:5], 0, v[2:3]
	s_mov_b64 s[0:1], 0x160
	v_cndmask_b32_e32 v23, v23, v25, vcc
	v_cndmask_b32_e32 v22, v22, v24, vcc
	v_lshl_add_u64 v[24:25], v[8:9], 0, s[0:1]
	s_mov_b64 s[0:1], 0xc700940
	v_lshl_add_u64 v[26:27], v[6:7], 0, s[0:1]
	v_cndmask_b32_e32 v25, v25, v27, vcc
	v_cndmask_b32_e32 v24, v24, v26, vcc
	v_add_u32_e32 v2, 0x180, v44
	s_mov_b64 s[0:1], 0xc700960
	global_load_dword v22, v[22:23], off
	v_lshl_add_u64 v[26:27], v[6:7], 0, s[0:1]
	global_load_dword v23, v[24:25], off
	v_lshl_add_u64 v[24:25], v[4:5], 0, v[2:3]
	s_mov_b64 s[0:1], 0x1a0
	v_cndmask_b32_e32 v25, v25, v27, vcc
	v_cndmask_b32_e32 v24, v24, v26, vcc
	v_lshl_add_u64 v[26:27], v[8:9], 0, s[0:1]
	s_mov_b64 s[0:1], 0xc700980
	v_lshl_add_u64 v[28:29], v[6:7], 0, s[0:1]
	v_cndmask_b32_e32 v27, v27, v29, vcc
	v_cndmask_b32_e32 v26, v26, v28, vcc
	v_add_u32_e32 v2, 0x1c0, v44
	s_mov_b64 s[0:1], 0xc7009a0
	global_load_dword v24, v[24:25], off
	v_lshl_add_u64 v[28:29], v[6:7], 0, s[0:1]
	global_load_dword v25, v[26:27], off
	v_lshl_add_u64 v[26:27], v[4:5], 0, v[2:3]
	s_mov_b64 s[0:1], 0x1e0
	v_cndmask_b32_e32 v27, v27, v29, vcc
	v_cndmask_b32_e32 v26, v26, v28, vcc
	v_lshl_add_u64 v[28:29], v[8:9], 0, s[0:1]
	s_mov_b64 s[0:1], 0xc7009c0
	v_lshl_add_u64 v[30:31], v[6:7], 0, s[0:1]
	v_cndmask_b32_e32 v29, v29, v31, vcc
	v_cndmask_b32_e32 v28, v28, v30, vcc
	v_add_u32_e32 v2, 0x200, v44
	s_mov_b64 s[0:1], 0xc7009e0
	global_load_dword v26, v[26:27], off
	v_lshl_add_u64 v[30:31], v[6:7], 0, s[0:1]
	global_load_dword v27, v[28:29], off
	v_lshl_add_u64 v[28:29], v[4:5], 0, v[2:3]
	s_mov_b64 s[0:1], 0x220
	v_cndmask_b32_e32 v29, v29, v31, vcc
	v_cndmask_b32_e32 v28, v28, v30, vcc
	v_lshl_add_u64 v[30:31], v[8:9], 0, s[0:1]
	s_mov_b64 s[0:1], 0xc700a00
	v_lshl_add_u64 v[32:33], v[6:7], 0, s[0:1]
	v_cndmask_b32_e32 v31, v31, v33, vcc
	v_cndmask_b32_e32 v30, v30, v32, vcc
	v_add_u32_e32 v2, 0x240, v44
	s_mov_b64 s[0:1], 0xc700a20
	global_load_dword v28, v[28:29], off
	v_lshl_add_u64 v[32:33], v[6:7], 0, s[0:1]
	global_load_dword v29, v[30:31], off
; DI void scan_unit(const Params& p, int su) {
;     ...
; #pragma unroll
;         for (int i = 0; i < 65; ++i) {
;             const int e = e0 + i, ec = e < LSK ? e : LSK - 1;
;             const float* pe = ec < PAST ? src0 + (size_t)ec * 8 : src1 + (size_t)(ec - PAST) * 8;
;             vals[i] = *pe;
;         }
	v_lshl_add_u64 v[30:31], v[4:5], 0, v[2:3]
	s_mov_b64 s[0:1], 0x260
	v_cndmask_b32_e32 v31, v31, v33, vcc
	v_cndmask_b32_e32 v30, v30, v32, vcc
	v_lshl_add_u64 v[32:33], v[8:9], 0, s[0:1]
	s_mov_b64 s[0:1], 0xc700a40
	v_lshl_add_u64 v[34:35], v[6:7], 0, s[0:1]
	v_cndmask_b32_e32 v33, v33, v35, vcc
	v_cndmask_b32_e32 v32, v32, v34, vcc
	v_add_u32_e32 v2, 0x280, v44
	s_mov_b64 s[0:1], 0xc700a60
	global_load_dword v30, v[30:31], off
	v_lshl_add_u64 v[34:35], v[6:7], 0, s[0:1]
	global_load_dword v31, v[32:33], off
	v_lshl_add_u64 v[32:33], v[4:5], 0, v[2:3]
	s_mov_b64 s[0:1], 0x2a0
	v_cndmask_b32_e32 v33, v33, v35, vcc
	v_cndmask_b32_e32 v32, v32, v34, vcc
	v_lshl_add_u64 v[34:35], v[8:9], 0, s[0:1]
	s_mov_b64 s[0:1], 0xc700a80
	v_lshl_add_u64 v[36:37], v[6:7], 0, s[0:1]
	v_cndmask_b32_e32 v35, v35, v37, vcc
	v_cndmask_b32_e32 v34, v34, v36, vcc
	v_add_u32_e32 v2, 0x2c0, v44
	s_mov_b64 s[0:1], 0xc700aa0
	global_load_dword v32, v[32:33], off
	v_lshl_add_u64 v[36:37], v[6:7], 0, s[0:1]
	global_load_dword v33, v[34:35], off
	v_lshl_add_u64 v[34:35], v[4:5], 0, v[2:3]
	s_mov_b64 s[0:1], 0x2e0
	v_cndmask_b32_e32 v35, v35, v37, vcc
	v_cndmask_b32_e32 v34, v34, v36, vcc
	v_lshl_add_u64 v[36:37], v[8:9], 0, s[0:1]
	s_mov_b64 s[0:1], 0xc700ac0
	v_lshl_add_u64 v[38:39], v[6:7], 0, s[0:1]
	v_cndmask_b32_e32 v37, v37, v39, vcc
	v_cndmask_b32_e32 v36, v36, v38, vcc
	v_add_u32_e32 v2, 0x300, v44
	s_mov_b64 s[0:1], 0xc700ae0
	global_load_dword v34, v[34:35], off
	v_lshl_add_u64 v[38:39], v[6:7], 0, s[0:1]
	global_load_dword v35, v[36:37], off
	v_lshl_add_u64 v[36:37], v[4:5], 0, v[2:3]
	s_mov_b64 s[0:1], 0x320
	v_cndmask_b32_e32 v37, v37, v39, vcc
	v_cndmask_b32_e32 v36, v36, v38, vcc
	v_lshl_add_u64 v[38:39], v[8:9], 0, s[0:1]
	s_mov_b64 s[0:1], 0xc700b00
	v_lshl_add_u64 v[40:41], v[6:7], 0, s[0:1]
	v_cndmask_b32_e32 v39, v39, v41, vcc
	v_cndmask_b32_e32 v38, v38, v40, vcc
	v_add_u32_e32 v2, 0x340, v44
	s_mov_b64 s[0:1], 0xc700b20
	global_load_dword v36, v[36:37], off
	v_lshl_add_u64 v[40:41], v[6:7], 0, s[0:1]
	global_load_dword v37, v[38:39], off
	v_lshl_add_u64 v[38:39], v[4:5], 0, v[2:3]
	s_mov_b64 s[0:1], 0x360
	v_cndmask_b32_e32 v39, v39, v41, vcc
	v_cndmask_b32_e32 v38, v38, v40, vcc
	v_lshl_add_u64 v[40:41], v[8:9], 0, s[0:1]
	s_mov_b64 s[0:1], 0xc700b40
	v_lshl_add_u64 v[42:43], v[6:7], 0, s[0:1]
	v_cndmask_b32_e32 v41, v41, v43, vcc
	v_cndmask_b32_e32 v40, v40, v42, vcc
	v_add_u32_e32 v2, 0x380, v44
	s_mov_b64 s[0:1], 0xc700b60
	global_load_dword v38, v[38:39], off
	v_lshl_add_u64 v[42:43], v[6:7], 0, s[0:1]
	global_load_dword v39, v[40:41], off
	v_lshl_add_u64 v[40:41], v[4:5], 0, v[2:3]
	s_mov_b64 s[0:1], 0x3a0
	v_cndmask_b32_e32 v41, v41, v43, vcc
	v_cndmask_b32_e32 v40, v40, v42, vcc
	v_lshl_add_u64 v[42:43], v[8:9], 0, s[0:1]
	s_mov_b64 s[0:1], 0xc700b80
	v_lshl_add_u64 v[46:47], v[6:7], 0, s[0:1]
	s_mov_b64 s[0:1], 0xc700ba0
	v_cndmask_b32_e32 v43, v43, v47, vcc
	v_cndmask_b32_e32 v42, v42, v46, vcc
	v_add_u32_e32 v2, 0x3c0, v44
	v_lshl_add_u64 v[46:47], v[6:7], 0, s[0:1]
	s_mov_b64 s[0:1], 0x3e0
	global_load_dword v12, v[8:9], off
	v_lshl_add_u64 v[8:9], v[8:9], 0, s[0:1]
	global_load_dword v40, v[40:41], off
	s_mov_b64 s[0:1], 0xc700bc0
	global_load_dword v41, v[42:43], off
	v_lshl_add_u64 v[42:43], v[4:5], 0, v[2:3]
	v_add_u32_e32 v2, 0x400, v44
	v_cndmask_b32_e32 v43, v43, v47, vcc
	v_cndmask_b32_e32 v42, v42, v46, vcc
	v_lshl_add_u64 v[46:47], v[6:7], 0, s[0:1]
	v_lshl_add_u64 v[44:45], v[4:5], 0, v[2:3]
	s_mov_b64 s[0:1], 0xc700be0
	v_add_u32_e32 v2, 33, v1
	v_lshl_add_u64 v[6:7], v[6:7], 0, s[0:1]
	v_min_u32_e32 v2, 0x101f, v2
	v_cndmask_b32_e32 v9, v9, v47, vcc
	v_cndmask_b32_e32 v8, v8, v46, vcc
	v_cndmask_b32_e32 v45, v45, v7, vcc
	v_cndmask_b32_e32 v44, v44, v6, vcc
	v_lshlrev_b32_e32 v2, 5, v2
	global_load_dword v8, v[8:9], off
	s_mov_b64 s[0:1], 0x440
	global_load_dword v9, v[44:45], off
	v_lshl_add_u64 v[44:45], v[4:5], 0, v[2:3]
	v_min_u32_e32 v2, 0xffd, v1
	v_cndmask_b32_e32 v45, v45, v7, vcc
	v_cndmask_b32_e32 v44, v44, v6, vcc
	v_lshlrev_b32_e32 v2, 5, v2
	global_load_dword v42, v[42:43], off
	s_nop 0
	global_load_dword v43, v[44:45], off
	v_lshl_add_u64 v[44:45], v[4:5], 0, v[2:3]
	v_add_u32_e32 v2, 35, v1
	v_min_u32_e32 v2, 0x101f, v2
	v_lshlrev_b32_e32 v2, 5, v2
	v_lshl_add_u64 v[44:45], v[44:45], 0, s[0:1]
	v_lshl_add_u64 v[46:47], v[4:5], 0, v[2:3]
	v_min_u32_e32 v2, 0xffb, v1
	v_cndmask_b32_e32 v45, v45, v7, vcc
	v_cndmask_b32_e32 v44, v44, v6, vcc
	v_cndmask_b32_e32 v47, v47, v7, vcc
	v_cndmask_b32_e32 v46, v46, v6, vcc
	v_lshlrev_b32_e32 v2, 5, v2
	global_load_dword v44, v[44:45], off
	s_mov_b64 s[0:1], 0x480
	global_load_dword v45, v[46:47], off
	v_lshl_add_u64 v[46:47], v[4:5], 0, v[2:3]
	v_add_u32_e32 v2, 37, v1
	v_min_u32_e32 v2, 0x101f, v2
	v_lshlrev_b32_e32 v2, 5, v2
	v_lshl_add_u64 v[46:47], v[46:47], 0, s[0:1]
	v_lshl_add_u64 v[48:49], v[4:5], 0, v[2:3]
	v_min_u32_e32 v2, 0xff9, v1
	v_cndmask_b32_e32 v47, v47, v7, vcc
	v_cndmask_b32_e32 v46, v46, v6, vcc
	v_cndmask_b32_e32 v49, v49, v7, vcc
	v_cndmask_b32_e32 v48, v48, v6, vcc
	v_lshlrev_b32_e32 v2, 5, v2
	global_load_dword v46, v[46:47], off
	s_mov_b64 s[0:1], 0x4c0
	global_load_dword v47, v[48:49], off
	v_lshl_add_u64 v[48:49], v[4:5], 0, v[2:3]
	v_add_u32_e32 v2, 39, v1
	v_min_u32_e32 v2, 0x101f, v2
	v_lshlrev_b32_e32 v2, 5, v2
	v_lshl_add_u64 v[48:49], v[48:49], 0, s[0:1]
	v_lshl_add_u64 v[50:51], v[4:5], 0, v[2:3]
	v_min_u32_e32 v2, 0xff7, v1
	v_cndmask_b32_e32 v49, v49, v7, vcc
	v_cndmask_b32_e32 v48, v48, v6, vcc
	v_cndmask_b32_e32 v51, v51, v7, vcc
	v_cndmask_b32_e32 v50, v50, v6, vcc
	v_lshlrev_b32_e32 v2, 5, v2
	global_load_dword v48, v[48:49], off
; DI void scan_unit(const Params& p, int su) {
;     ...
; #pragma unroll
;         for (int i = 0; i < 65; ++i) {
;             const int e = e0 + i, ec = e < LSK ? e : LSK - 1;
;             const float* pe = ec < PAST ? src0 + (size_t)ec * 8 : src1 + (size_t)(ec - PAST) * 8;
;             vals[i] = *pe;
;         }
	s_mov_b64 s[0:1], 0x500
	global_load_dword v49, v[50:51], off
	v_lshl_add_u64 v[50:51], v[4:5], 0, v[2:3]
	v_add_u32_e32 v2, 41, v1
	v_min_u32_e32 v2, 0x101f, v2
	v_lshlrev_b32_e32 v2, 5, v2
	v_lshl_add_u64 v[50:51], v[50:51], 0, s[0:1]
	v_lshl_add_u64 v[52:53], v[4:5], 0, v[2:3]
	v_min_u32_e32 v2, 0xff5, v1
	v_cndmask_b32_e32 v51, v51, v7, vcc
	v_cndmask_b32_e32 v50, v50, v6, vcc
	v_cndmask_b32_e32 v53, v53, v7, vcc
	v_cndmask_b32_e32 v52, v52, v6, vcc
	v_lshlrev_b32_e32 v2, 5, v2
	global_load_dword v50, v[50:51], off
	s_mov_b64 s[0:1], 0x540
	global_load_dword v51, v[52:53], off
	v_lshl_add_u64 v[52:53], v[4:5], 0, v[2:3]
	v_add_u32_e32 v2, 43, v1
	v_min_u32_e32 v2, 0x101f, v2
	v_lshlrev_b32_e32 v2, 5, v2
	v_lshl_add_u64 v[52:53], v[52:53], 0, s[0:1]
	v_lshl_add_u64 v[54:55], v[4:5], 0, v[2:3]
	v_min_u32_e32 v2, 0xff3, v1
	v_cndmask_b32_e32 v53, v53, v7, vcc
	v_cndmask_b32_e32 v52, v52, v6, vcc
	v_cndmask_b32_e32 v55, v55, v7, vcc
	v_cndmask_b32_e32 v54, v54, v6, vcc
	v_lshlrev_b32_e32 v2, 5, v2
	global_load_dword v52, v[52:53], off
	s_mov_b64 s[0:1], 0x580
	global_load_dword v53, v[54:55], off
	v_lshl_add_u64 v[54:55], v[4:5], 0, v[2:3]
	v_add_u32_e32 v2, 45, v1
	v_min_u32_e32 v2, 0x101f, v2
	v_lshlrev_b32_e32 v2, 5, v2
	v_lshl_add_u64 v[54:55], v[54:55], 0, s[0:1]
	v_lshl_add_u64 v[56:57], v[4:5], 0, v[2:3]
	v_min_u32_e32 v2, 0xff1, v1
	v_cndmask_b32_e32 v55, v55, v7, vcc
	v_cndmask_b32_e32 v54, v54, v6, vcc
	v_cndmask_b32_e32 v57, v57, v7, vcc
	v_cndmask_b32_e32 v56, v56, v6, vcc
	v_lshlrev_b32_e32 v2, 5, v2
	global_load_dword v54, v[54:55], off
	s_mov_b64 s[0:1], 0x5c0
	global_load_dword v55, v[56:57], off
	v_lshl_add_u64 v[56:57], v[4:5], 0, v[2:3]
	v_add_u32_e32 v2, 47, v1
	v_min_u32_e32 v2, 0x101f, v2
	v_lshlrev_b32_e32 v2, 5, v2
	v_lshl_add_u64 v[56:57], v[56:57], 0, s[0:1]
	v_lshl_add_u64 v[58:59], v[4:5], 0, v[2:3]
	v_min_u32_e32 v2, 0xfef, v1
	v_cndmask_b32_e32 v57, v57, v7, vcc
	v_cndmask_b32_e32 v56, v56, v6, vcc
	v_cndmask_b32_e32 v59, v59, v7, vcc
	v_cndmask_b32_e32 v58, v58, v6, vcc
	v_lshlrev_b32_e32 v2, 5, v2
	global_load_dword v56, v[56:57], off
	s_mov_b64 s[0:1], 0x600
	global_load_dword v57, v[58:59], off
	v_lshl_add_u64 v[58:59], v[4:5], 0, v[2:3]
	v_add_u32_e32 v2, 49, v1
	v_min_u32_e32 v2, 0x101f, v2
	v_lshlrev_b32_e32 v2, 5, v2
	v_lshl_add_u64 v[58:59], v[58:59], 0, s[0:1]
	v_lshl_add_u64 v[60:61], v[4:5], 0, v[2:3]
	v_min_u32_e32 v2, 0xfed, v1
	v_cndmask_b32_e32 v59, v59, v7, vcc
	v_cndmask_b32_e32 v58, v58, v6, vcc
	v_cndmask_b32_e32 v61, v61, v7, vcc
	v_cndmask_b32_e32 v60, v60, v6, vcc
	v_lshlrev_b32_e32 v2, 5, v2
	global_load_dword v58, v[58:59], off
	s_mov_b64 s[0:1], 0x640
	global_load_dword v59, v[60:61], off
	v_lshl_add_u64 v[60:61], v[4:5], 0, v[2:3]
	v_add_u32_e32 v2, 51, v1
	v_min_u32_e32 v2, 0x101f, v2
	v_lshlrev_b32_e32 v2, 5, v2
	v_lshl_add_u64 v[60:61], v[60:61], 0, s[0:1]
	v_lshl_add_u64 v[62:63], v[4:5], 0, v[2:3]
	v_min_u32_e32 v2, 0xfeb, v1
	v_cndmask_b32_e32 v61, v61, v7, vcc
	v_cndmask_b32_e32 v60, v60, v6, vcc
	v_cndmask_b32_e32 v63, v63, v7, vcc
	v_cndmask_b32_e32 v62, v62, v6, vcc
	v_lshlrev_b32_e32 v2, 5, v2
	global_load_dword v60, v[60:61], off
	s_mov_b64 s[0:1], 0x680
	global_load_dword v61, v[62:63], off
	v_lshl_add_u64 v[62:63], v[4:5], 0, v[2:3]
	v_add_u32_e32 v2, 53, v1
	v_min_u32_e32 v2, 0x101f, v2
	v_lshlrev_b32_e32 v2, 5, v2
	v_lshl_add_u64 v[62:63], v[62:63], 0, s[0:1]
	v_lshl_add_u64 v[64:65], v[4:5], 0, v[2:3]
	v_min_u32_e32 v2, 0xfe9, v1
	v_cndmask_b32_e32 v63, v63, v7, vcc
	v_cndmask_b32_e32 v62, v62, v6, vcc
	v_cndmask_b32_e32 v65, v65, v7, vcc
	v_cndmask_b32_e32 v64, v64, v6, vcc
	v_lshlrev_b32_e32 v2, 5, v2
	global_load_dword v62, v[62:63], off
	s_mov_b64 s[0:1], 0x6c0
	global_load_dword v63, v[64:65], off
	v_lshl_add_u64 v[64:65], v[4:5], 0, v[2:3]
	v_add_u32_e32 v2, 55, v1
	v_min_u32_e32 v2, 0x101f, v2
	v_lshlrev_b32_e32 v2, 5, v2
	v_lshl_add_u64 v[64:65], v[64:65], 0, s[0:1]
	v_lshl_add_u64 v[66:67], v[4:5], 0, v[2:3]
	v_min_u32_e32 v2, 0xfe7, v1
	v_cndmask_b32_e32 v65, v65, v7, vcc
	v_cndmask_b32_e32 v64, v64, v6, vcc
	v_cndmask_b32_e32 v67, v67, v7, vcc
	v_cndmask_b32_e32 v66, v66, v6, vcc
	v_lshlrev_b32_e32 v2, 5, v2
	global_load_dword v64, v[64:65], off
	s_mov_b64 s[0:1], 0x700
	global_load_dword v65, v[66:67], off
	v_lshl_add_u64 v[66:67], v[4:5], 0, v[2:3]
	v_add_u32_e32 v2, 57, v1
	v_min_u32_e32 v2, 0x101f, v2
	v_lshlrev_b32_e32 v2, 5, v2
	v_lshl_add_u64 v[66:67], v[66:67], 0, s[0:1]
	v_lshl_add_u64 v[68:69], v[4:5], 0, v[2:3]
	v_min_u32_e32 v2, 0xfe5, v1
	v_cndmask_b32_e32 v67, v67, v7, vcc
	v_cndmask_b32_e32 v66, v66, v6, vcc
	v_cndmask_b32_e32 v69, v69, v7, vcc
	v_cndmask_b32_e32 v68, v68, v6, vcc
	v_lshlrev_b32_e32 v2, 5, v2
	global_load_dword v66, v[66:67], off
	s_mov_b64 s[0:1], 0x740
	global_load_dword v67, v[68:69], off
	v_lshl_add_u64 v[68:69], v[4:5], 0, v[2:3]
	v_add_u32_e32 v2, 59, v1
	v_min_u32_e32 v2, 0x101f, v2
	v_lshlrev_b32_e32 v2, 5, v2
	v_lshl_add_u64 v[68:69], v[68:69], 0, s[0:1]
	v_lshl_add_u64 v[70:71], v[4:5], 0, v[2:3]
	v_min_u32_e32 v2, 0xfe3, v1
	v_cndmask_b32_e32 v69, v69, v7, vcc
	v_cndmask_b32_e32 v68, v68, v6, vcc
	v_cndmask_b32_e32 v71, v71, v7, vcc
	v_cndmask_b32_e32 v70, v70, v6, vcc
	v_lshlrev_b32_e32 v2, 5, v2
	global_load_dword v68, v[68:69], off
	s_mov_b64 s[0:1], 0x780
	global_load_dword v69, v[70:71], off
	v_lshl_add_u64 v[70:71], v[4:5], 0, v[2:3]
	v_add_u32_e32 v2, 61, v1
	v_min_u32_e32 v2, 0x101f, v2
	v_lshlrev_b32_e32 v2, 5, v2
	v_lshl_add_u64 v[70:71], v[70:71], 0, s[0:1]
	v_lshl_add_u64 v[72:73], v[4:5], 0, v[2:3]
	v_min_u32_e32 v2, 0xfe1, v1
	v_cndmask_b32_e32 v71, v71, v7, vcc
	v_cndmask_b32_e32 v70, v70, v6, vcc
	v_cndmask_b32_e32 v73, v73, v7, vcc
	v_cndmask_b32_e32 v72, v72, v6, vcc
	v_lshlrev_b32_e32 v2, 5, v2
	global_load_dword v70, v[70:71], off
	s_mov_b64 s[0:1], 0x7c0
	global_load_dword v71, v[72:73], off
	v_lshl_add_u64 v[72:73], v[4:5], 0, v[2:3]
	v_add_u32_e32 v2, 63, v1
	v_min_u32_e32 v2, 0x101f, v2
	v_lshlrev_b32_e32 v2, 5, v2
	v_lshl_add_u64 v[74:75], v[4:5], 0, v[2:3]
	v_min_u32_e32 v2, 0xfdf, v1
	v_lshl_add_u64 v[72:73], v[72:73], 0, s[0:1]
	v_lshlrev_b32_e32 v2, 5, v2
	v_cndmask_b32_e32 v73, v73, v7, vcc
	v_cndmask_b32_e32 v72, v72, v6, vcc
	v_lshl_add_u64 v[4:5], v[4:5], 0, v[2:3]
	s_mov_b64 s[0:1], 0x800
	global_load_dword v72, v[72:73], off
	v_cndmask_b32_e32 v75, v75, v7, vcc
	v_cndmask_b32_e32 v74, v74, v6, vcc
	v_lshl_add_u64 v[4:5], v[4:5], 0, s[0:1]
	global_load_dword v73, v[74:75], off
	v_cndmask_b32_e32 v5, v5, v7, vcc
	v_cndmask_b32_e32 v4, v4, v6, vcc
	global_load_dword v4, v[4:5], off
	s_waitcnt vmcnt(37)
; DI void scan_unit(const Params& p, int su) {
;     ...
;         float s = 0.f;
; #pragma unroll
;         for (int i = 0; i < 65; ++i) s += (e0 + i < LSK) ? vals[i] : 0.f;
;         float incl = s;
; #pragma unroll
;         for (int o = 1; o < 64; o <<= 1) { const float t = __shfl_up(incl, o); if (lane >= o) incl += t; }
	v_add_f32_e32 v2, 0, v12
	v_add_f32_e32 v2, v2, v13
	v_add_f32_e32 v2, v2, v14
	v_add_f32_e32 v2, v2, v15
	v_add_f32_e32 v2, v2, v16
	v_add_f32_e32 v2, v2, v17
	v_add_f32_e32 v2, v2, v18
	v_add_f32_e32 v2, v2, v19
	v_add_f32_e32 v2, v2, v20
	v_add_f32_e32 v2, v2, v21
	v_add_f32_e32 v2, v2, v22
	v_add_f32_e32 v2, v2, v23
	v_add_f32_e32 v2, v2, v24
	v_add_f32_e32 v2, v2, v25
	v_add_f32_e32 v2, v2, v26
	v_add_f32_e32 v2, v2, v27
	v_add_f32_e32 v2, v2, v28
	v_add_f32_e32 v2, v2, v29
	v_add_f32_e32 v2, v2, v30
	v_add_f32_e32 v2, v2, v31
	v_add_f32_e32 v2, v2, v32
	v_add_f32_e32 v2, v2, v33
	v_add_f32_e32 v2, v2, v34
	v_add_f32_e32 v2, v2, v35
	v_add_f32_e32 v2, v2, v36
	v_add_f32_e32 v2, v2, v37
	v_add_f32_e32 v2, v2, v38
	v_add_f32_e32 v2, v2, v39
	s_waitcnt vmcnt(36)
	v_add_f32_e32 v2, v2, v40
	s_waitcnt vmcnt(35)
	v_add_f32_e32 v2, v2, v41
	s_waitcnt vmcnt(32)
	v_add_f32_e32 v2, v2, v42
	v_add_f32_e32 v2, v2, v8
	v_add_f32_e32 v2, v2, v9
	s_waitcnt vmcnt(31)
	v_cndmask_b32_e64 v5, v43, 0, vcc
	v_add_f32_e32 v2, v2, v5
	s_waitcnt vmcnt(30)
	v_cndmask_b32_e64 v5, v44, 0, vcc
	v_add_f32_e32 v2, v2, v5
	s_waitcnt vmcnt(29)
	v_cndmask_b32_e64 v5, v45, 0, vcc
	v_add_f32_e32 v2, v2, v5
	s_waitcnt vmcnt(28)
	v_cndmask_b32_e64 v5, v46, 0, vcc
	v_add_f32_e32 v2, v2, v5
	s_waitcnt vmcnt(27)
	v_cndmask_b32_e64 v5, v47, 0, vcc
	v_add_f32_e32 v2, v2, v5
	s_waitcnt vmcnt(26)
	v_cndmask_b32_e64 v5, v48, 0, vcc
	v_add_f32_e32 v2, v2, v5
	s_waitcnt vmcnt(25)
	v_cndmask_b32_e64 v5, v49, 0, vcc
	v_add_f32_e32 v2, v2, v5
	s_waitcnt vmcnt(24)
	v_cndmask_b32_e64 v5, v50, 0, vcc
	v_add_f32_e32 v2, v2, v5
	s_waitcnt vmcnt(23)
	v_cndmask_b32_e64 v5, v51, 0, vcc
	v_add_f32_e32 v2, v2, v5
	s_waitcnt vmcnt(22)
	v_cndmask_b32_e64 v5, v52, 0, vcc
	v_add_f32_e32 v2, v2, v5
	s_waitcnt vmcnt(21)
	v_cndmask_b32_e64 v5, v53, 0, vcc
	v_add_f32_e32 v2, v2, v5
	s_waitcnt vmcnt(20)
	v_cndmask_b32_e64 v5, v54, 0, vcc
	v_add_f32_e32 v2, v2, v5
	s_waitcnt vmcnt(19)
	v_cndmask_b32_e64 v5, v55, 0, vcc
	v_add_f32_e32 v2, v2, v5
	s_waitcnt vmcnt(18)
	v_cndmask_b32_e64 v5, v56, 0, vcc
	v_add_f32_e32 v2, v2, v5
	s_waitcnt vmcnt(17)
	v_cndmask_b32_e64 v5, v57, 0, vcc
	v_add_f32_e32 v2, v2, v5
	s_waitcnt vmcnt(16)
	v_cndmask_b32_e64 v5, v58, 0, vcc
	v_add_f32_e32 v2, v2, v5
	s_waitcnt vmcnt(15)
	v_cndmask_b32_e64 v5, v59, 0, vcc
	v_add_f32_e32 v2, v2, v5
	s_waitcnt vmcnt(14)
	v_cndmask_b32_e64 v5, v60, 0, vcc
	v_add_f32_e32 v2, v2, v5
	s_waitcnt vmcnt(13)
	v_cndmask_b32_e64 v5, v61, 0, vcc
	v_add_f32_e32 v2, v2, v5
	s_waitcnt vmcnt(12)
	v_cndmask_b32_e64 v5, v62, 0, vcc
	v_add_f32_e32 v2, v2, v5
	s_waitcnt vmcnt(11)
	v_cndmask_b32_e64 v5, v63, 0, vcc
	v_add_f32_e32 v2, v2, v5
	s_waitcnt vmcnt(10)
	v_cndmask_b32_e64 v5, v64, 0, vcc
	v_add_f32_e32 v2, v2, v5
	s_waitcnt vmcnt(9)
	v_cndmask_b32_e64 v5, v65, 0, vcc
	v_add_f32_e32 v2, v2, v5
	s_waitcnt vmcnt(8)
	v_cndmask_b32_e64 v5, v66, 0, vcc
	v_add_f32_e32 v2, v2, v5
	s_waitcnt vmcnt(7)
	v_cndmask_b32_e64 v5, v67, 0, vcc
	v_add_f32_e32 v2, v2, v5
	s_waitcnt vmcnt(6)
	v_cndmask_b32_e64 v5, v68, 0, vcc
	v_add_f32_e32 v2, v2, v5
	s_waitcnt vmcnt(5)
	v_cndmask_b32_e64 v5, v69, 0, vcc
	v_add_f32_e32 v2, v2, v5
	s_waitcnt vmcnt(4)
	v_cndmask_b32_e64 v5, v70, 0, vcc
	v_add_f32_e32 v2, v2, v5
	s_waitcnt vmcnt(3)
	v_cndmask_b32_e64 v5, v71, 0, vcc
	v_add_f32_e32 v2, v2, v5
	s_waitcnt vmcnt(2)
	v_cndmask_b32_e64 v5, v72, 0, vcc
	v_add_f32_e32 v2, v2, v5
	s_waitcnt vmcnt(1)
	v_cndmask_b32_e64 v5, v73, 0, vcc
	v_add_f32_e32 v2, v2, v5
	s_waitcnt vmcnt(0)
	v_cndmask_b32_e64 v5, v4, 0, vcc
	v_add_f32_e32 v2, v2, v5
	v_mbcnt_lo_u32_b32 v5, -1, 0
	v_mbcnt_hi_u32_b32 v5, -1, v5
	v_and_b32_e32 v6, 64, v5
	v_add_u32_e32 v7, -1, v5
	v_cmp_lt_i32_e32 vcc, v7, v6
	v_add_u32_e32 v74, -2, v5
	v_cmp_gt_u32_e64 s[0:1], 16, v10
	v_cndmask_b32_e32 v7, v7, v5, vcc
	v_lshlrev_b32_e32 v7, 2, v7
	ds_bpermute_b32 v7, v7, v2
	v_cmp_eq_u32_e32 vcc, 0, v10
	s_waitcnt lgkmcnt(0)
	v_add_f32_e32 v7, v2, v7
	v_cndmask_b32_e32 v7, v7, v2, vcc
	v_cmp_lt_i32_e32 vcc, v74, v6
	s_nop 1
	v_cndmask_b32_e32 v74, v74, v5, vcc
	v_lshlrev_b32_e32 v74, 2, v74
	ds_bpermute_b32 v74, v74, v7
	v_cmp_gt_u32_e32 vcc, 2, v10
	s_waitcnt lgkmcnt(0)
	v_add_f32_e32 v74, v7, v74
	v_cndmask_b32_e32 v7, v74, v7, vcc
	v_add_u32_e32 v74, -4, v5
	v_cmp_lt_i32_e32 vcc, v74, v6
	s_nop 1
	v_cndmask_b32_e32 v74, v74, v5, vcc
	v_lshlrev_b32_e32 v74, 2, v74
	ds_bpermute_b32 v74, v74, v7
	v_cmp_gt_u32_e32 vcc, 4, v10
	s_waitcnt lgkmcnt(0)
	v_add_f32_e32 v74, v7, v74
	v_cndmask_b32_e32 v7, v74, v7, vcc
	v_add_u32_e32 v74, -8, v5
	v_cmp_lt_i32_e32 vcc, v74, v6
	s_nop 1
	v_cndmask_b32_e32 v74, v74, v5, vcc
	v_lshlrev_b32_e32 v74, 2, v74
	ds_bpermute_b32 v74, v74, v7
	v_cmp_gt_u32_e32 vcc, 8, v10
	s_waitcnt lgkmcnt(0)
	v_add_f32_e32 v74, v7, v74
	v_cndmask_b32_e32 v7, v74, v7, vcc
	v_add_u32_e32 v74, -16, v5
	v_cmp_lt_i32_e32 vcc, v74, v6
	s_nop 1
	v_cndmask_b32_e32 v74, v74, v5, vcc
	v_lshlrev_b32_e32 v74, 2, v74
	ds_bpermute_b32 v74, v74, v7
	v_cmp_ne_u32_e32 vcc, 63, v10
	s_waitcnt lgkmcnt(0)
; DI void scan_unit(const Params& p, int su) {
;     ...
;         for (int o = 1; o < 64; o <<= 1) { const float t = __shfl_up(incl, o); if (lane >= o) incl += t; }
;         float run = incl - s;
; #pragma unroll
;         for (int i = 0; i < 65; ++i) { const int e = e0 + i; if (e < LSK) { run += vals[i]; dst[e] = run * LOG2E; } }
	v_add_f32_e32 v74, v7, v74
	v_cndmask_b32_e64 v74, v74, v7, s[0:1]
	v_subrev_u32_e32 v7, 32, v5
	v_cmp_lt_i32_e64 s[0:1], v7, v6
	s_nop 1
	v_cndmask_b32_e64 v5, v7, v5, s[0:1]
	v_lshlrev_b32_e32 v5, 2, v5
	ds_bpermute_b32 v5, v5, v74
	s_movk_i32 s0, 0x4080
	v_mov_b64_e32 v[6:7], s[74:75]
	v_mad_u64_u32 v[6:7], s[0:1], v11, s0, v[6:7]
	s_waitcnt lgkmcnt(0)
	v_add_f32_e32 v5, v74, v5
	v_cmp_gt_u32_e64 s[0:1], 32, v10
	s_nop 1
	v_cndmask_b32_e64 v5, v5, v74, s[0:1]
	v_sub_f32_e32 v5, v5, v2
	v_lshlrev_b32_e32 v2, 2, v1
	v_lshl_add_u64 v[2:3], v[6:7], 0, v[2:3]
	v_add_f32_e32 v6, v12, v5
	v_add_f32_e32 v7, v13, v6
	s_mov_b32 s0, 0x3fb8aa3b
	v_pk_mul_f32 v[10:11], v[6:7], s[0:1] op_sel_hi:[1,0]
	v_add_f32_e32 v6, v14, v7
	v_add_f32_e32 v7, v15, v6
	v_pk_mul_f32 v[12:13], v[6:7], s[0:1] op_sel_hi:[1,0]
	v_add_f32_e32 v6, v16, v7
	v_add_f32_e32 v7, v17, v6
	global_store_dwordx4 v[2:3], v[10:13], off
	s_nop 1
	v_pk_mul_f32 v[10:11], v[6:7], s[0:1] op_sel_hi:[1,0]
	v_add_f32_e32 v6, v18, v7
	v_add_f32_e32 v7, v19, v6
	v_pk_mul_f32 v[12:13], v[6:7], s[0:1] op_sel_hi:[1,0]
	v_add_f32_e32 v6, v20, v7
	v_add_f32_e32 v7, v21, v6
	global_store_dwordx4 v[2:3], v[10:13], off offset:16
	s_nop 1
	v_pk_mul_f32 v[10:11], v[6:7], s[0:1] op_sel_hi:[1,0]
	v_add_f32_e32 v6, v22, v7
	v_add_f32_e32 v7, v23, v6
	v_pk_mul_f32 v[12:13], v[6:7], s[0:1] op_sel_hi:[1,0]
	v_add_f32_e32 v6, v24, v7
	v_add_f32_e32 v7, v25, v6
	global_store_dwordx4 v[2:3], v[10:13], off offset:32
	s_nop 1
	v_pk_mul_f32 v[10:11], v[6:7], s[0:1] op_sel_hi:[1,0]
	v_add_f32_e32 v6, v26, v7
	v_add_f32_e32 v7, v27, v6
	v_pk_mul_f32 v[12:13], v[6:7], s[0:1] op_sel_hi:[1,0]
	v_add_f32_e32 v6, v28, v7
	v_add_f32_e32 v7, v29, v6
	global_store_dwordx4 v[2:3], v[10:13], off offset:48
	s_nop 1
	v_pk_mul_f32 v[10:11], v[6:7], s[0:1] op_sel_hi:[1,0]
	v_add_f32_e32 v6, v30, v7
	v_add_f32_e32 v7, v31, v6
	v_pk_mul_f32 v[12:13], v[6:7], s[0:1] op_sel_hi:[1,0]
	v_add_f32_e32 v6, v32, v7
	v_add_f32_e32 v7, v33, v6
	global_store_dwordx4 v[2:3], v[10:13], off offset:64
	s_nop 1
	v_pk_mul_f32 v[10:11], v[6:7], s[0:1] op_sel_hi:[1,0]
	v_add_f32_e32 v6, v34, v7
	v_add_f32_e32 v7, v35, v6
	v_pk_mul_f32 v[12:13], v[6:7], s[0:1] op_sel_hi:[1,0]
	v_add_f32_e32 v6, v36, v7
	v_add_f32_e32 v7, v37, v6
	global_store_dwordx4 v[2:3], v[10:13], off offset:80
	s_nop 1
	v_pk_mul_f32 v[10:11], v[6:7], s[0:1] op_sel_hi:[1,0]
	v_add_f32_e32 v6, v38, v7
	v_add_f32_e32 v7, v39, v6
	v_pk_mul_f32 v[12:13], v[6:7], s[0:1] op_sel_hi:[1,0]
	v_add_f32_e32 v6, v40, v7
	v_add_f32_e32 v7, v41, v6
	global_store_dwordx4 v[2:3], v[10:13], off offset:96
	s_nop 1
	v_pk_mul_f32 v[10:11], v[6:7], s[0:1] op_sel_hi:[1,0]
	v_add_f32_e32 v6, v42, v7
	v_add_f32_e32 v7, v8, v6
	v_add_f32_e32 v1, v9, v7
	v_pk_mul_f32 v[12:13], v[6:7], s[0:1] op_sel_hi:[1,0]
	v_mul_f32_e32 v5, 0x3fb8aa3b, v1
	global_store_dwordx4 v[2:3], v[10:13], off offset:112
	global_store_dword v[2:3], v5, off offset:128
	s_and_saveexec_b64 s[6:7], vcc
	s_cbranch_execz .LBB0_119
	v_add_f32_e32 v8, v43, v1
	v_add_f32_e32 v9, v44, v8
	v_add_f32_e32 v10, v45, v9
	v_add_f32_e32 v11, v46, v10
	v_pk_mul_f32 v[6:7], v[8:9], s[0:1] op_sel_hi:[1,0]
	v_pk_mul_f32 v[8:9], v[10:11], s[0:1] op_sel_hi:[1,0]
	global_store_dwordx4 v[2:3], v[6:9], off offset:132
	s_nop 1
	v_add_f32_e32 v8, v47, v11
	v_add_f32_e32 v9, v48, v8
	v_add_f32_e32 v10, v49, v9
	v_add_f32_e32 v11, v50, v10
	v_pk_mul_f32 v[6:7], v[8:9], s[0:1] op_sel_hi:[1,0]
	v_pk_mul_f32 v[8:9], v[10:11], s[0:1] op_sel_hi:[1,0]
	global_store_dwordx4 v[2:3], v[6:9], off offset:148
	s_nop 1
	v_add_f32_e32 v8, v51, v11
	v_add_f32_e32 v9, v52, v8
	v_add_f32_e32 v10, v53, v9
	v_add_f32_e32 v11, v54, v10
	v_pk_mul_f32 v[6:7], v[8:9], s[0:1] op_sel_hi:[1,0]
	v_pk_mul_f32 v[8:9], v[10:11], s[0:1] op_sel_hi:[1,0]
	global_store_dwordx4 v[2:3], v[6:9], off offset:164
	s_nop 1
	v_add_f32_e32 v8, v55, v11
	v_add_f32_e32 v9, v56, v8
	v_add_f32_e32 v10, v57, v9
	v_add_f32_e32 v11, v58, v10
	v_pk_mul_f32 v[6:7], v[8:9], s[0:1] op_sel_hi:[1,0]
	v_pk_mul_f32 v[8:9], v[10:11], s[0:1] op_sel_hi:[1,0]
	global_store_dwordx4 v[2:3], v[6:9], off offset:180
	s_nop 1
	v_add_f32_e32 v8, v59, v11
	v_add_f32_e32 v9, v60, v8
	v_add_f32_e32 v10, v61, v9
	v_add_f32_e32 v11, v62, v10
	v_pk_mul_f32 v[6:7], v[8:9], s[0:1] op_sel_hi:[1,0]
	v_pk_mul_f32 v[8:9], v[10:11], s[0:1] op_sel_hi:[1,0]
	global_store_dwordx4 v[2:3], v[6:9], off offset:196
	s_nop 1
	v_add_f32_e32 v8, v63, v11
	v_add_f32_e32 v9, v64, v8
	v_add_f32_e32 v10, v65, v9
	v_add_f32_e32 v11, v66, v10
	v_pk_mul_f32 v[6:7], v[8:9], s[0:1] op_sel_hi:[1,0]
	v_pk_mul_f32 v[8:9], v[10:11], s[0:1] op_sel_hi:[1,0]
	global_store_dwordx4 v[2:3], v[6:9], off offset:212
	s_nop 1
	v_add_f32_e32 v8, v67, v11
	v_add_f32_e32 v9, v68, v8
	v_add_f32_e32 v10, v69, v9
	v_add_f32_e32 v11, v70, v10
	v_pk_mul_f32 v[6:7], v[8:9], s[0:1] op_sel_hi:[1,0]
	v_pk_mul_f32 v[8:9], v[10:11], s[0:1] op_sel_hi:[1,0]
	global_store_dwordx4 v[2:3], v[6:9], off offset:228
	s_nop 1
	v_add_f32_e32 v8, v71, v11
	v_add_f32_e32 v9, v72, v8
	v_pk_mul_f32 v[6:7], v[8:9], s[0:1] op_sel_hi:[1,0]
	v_add_f32_e32 v8, v73, v9
	v_add_f32_e32 v9, v4, v8
	v_pk_mul_f32 v[8:9], v[8:9], s[0:1] op_sel_hi:[1,0]
	global_store_dwordx4 v[2:3], v[6:9], off offset:244

; #define PG8_STAGE(bufoff, gbase, voff) do { _Pragma("unroll") for (int _i = 0; _i < 2; ++_i) \
;         __builtin_amdgcn_global_load_lds((const unsigned*)((const char*)(gbase) + (voff)[_i]), (PG8_LAS unsigned*)(lds + (bufoff) + ldsw + _i * 8192), 16, 0, 0); } while (0)
; #define PG8_WAIT_V(n) asm volatile("s_waitcnt vmcnt(" #n ")" ::: "memory")
; #define PG8_BAR __builtin_amdgcn_s_barrier()
; template <class Epi, class Sched, bool ALIGN_EPI = false, bool SP2 = false>
; __device__ __forceinline__ void gemm_phase(PG8_LAS unsigned char* lds, const Gemm g, const Sched& S, const Epi& E) {
;     const int tid = threadIdx.x, wid = __builtin_amdgcn_readfirstlane(tid >> 6), lane = tid & 63, wr = wid >> 2, wc = wid & 3, fr = lane & 15, fq = lane >> 4;
;     const int K = g.K, nt = K / BK;
;     unsigned voffA[2], voffB[2];
; #pragma unroll
;     for (int i = 0; i < 2; ++i) { int R, C; stage_rc(tid * 16 + i * 8192, R, C); const int Rb = Epi::PERM ? ((R & ~31) + perm32(R & 31)) : R;
;         voffA[i] = (unsigned)(R * K + C) * 2u; voffB[i] = (unsigned)(Rb * K + C) * 2u; }
;     const size_t kstep = (size_t)(BK * 2);
;     const size_t hstep = (size_t)HALF * K * 2;
;     const size_t tstep = 2 * hstep;
;     const unsigned ldsw = (unsigned)wid * 1024u;
;     const int aoff = lds_byte(wr * 64 + fr, fq * 8), boff = lds_byte(wc * 32 + fr, fq * 8);
;     ...
;     const char* cA = (const char*)g.A + (size_t)cur.pm * tstep; const char* cB = (const char*)g.Bt + (size_t)cur.pn * tstep;
;     S.a_ready(cur);
;     if constexpr (SP2) {
;         PG8_STAGE(PG8_SB(0, 0), cB, voffB); PG8_STAGE(PG8_SB(0, 1), cB + hstep, voffB); PG8_STAGE(PG8_SA(0, 0), cA, voffA); PG8_STAGE(PG8_SA(0, 1), cA + hstep, voffA);
;         if (wr == 1) PG8_BAR;
;         PG8_WAIT_V(2); PG8_BAR;
;         PG8_STAGE(PG8_SB(1, 0), cB + kstep, voffB); PG8_STAGE(PG8_SA(1, 0), cA + kstep, voffA); PG8_STAGE(PG8_SB(1, 1), cB + hstep + kstep, voffB);
;         PG8_WAIT_V(6); PG8_BAR;
.LBB0_132:
	s_lshl_b32 s15, s15, 5
	s_mov_b64 s[16:17], 0x80
	s_and_b32 s15, s15, 0x60
	s_add_i32 m0, s42, 0x18000
	v_lshl_add_u64 v[8:9], v[8:9], 0, s[16:17]
	s_lshl_b32 s7, s4, 13
	s_lshl_b32 s22, s15, 7
	s_waitcnt vmcnt(2)
	s_barrier
	global_load_lds_dwordx4 v[8:9], off
	v_lshl_add_u64 v[4:5], v[4:5], 0, s[16:17]
	s_add_i32 m0, s42, 0x1a000
	s_add_i32 s48, s42, 0x8000
	s_add_i32 s49, s42, 0xa000
	global_load_lds_dwordx4 v[4:5], off
	v_lshl_add_u64 v[2:3], v[2:3], 0, s[16:17]
	s_mov_b32 m0, s48
	s_add_u32 s20, s10, 0x40080
	global_load_lds_dwordx4 v[2:3], off
	v_lshl_add_u64 v[2:3], v[6:7], 0, s[16:17]
	s_mov_b32 m0, s49
	s_addc_u32 s21, s11, 0
	global_load_lds_dwordx4 v[2:3], off
	s_add_i32 m0, s42, 0x1c000
	v_lshl_add_u64 v[2:3], s[20:21], 0, v[142:143]
	global_load_lds_dwordx4 v[2:3], off
	v_lshl_add_u64 v[2:3], s[20:21], 0, v[146:147]
	s_add_i32 m0, s42, 0x1e000
	v_lshlrev_b32_e32 v4, 2, v173
	global_load_lds_dwordx4 v[2:3], off
	v_lshlrev_b32_e32 v2, 1, v10
	v_lshl_or_b32 v3, v173, 6, v2
	v_and_b32_e32 v4, 32, v4
	v_bitop3_b32 v3, v3, s7, v4 bitop3:0xde
	s_cmpk_lt_u32 s14, 0x100
	v_lshlrev_b32_e32 v4, 8, v138
	s_cselect_b64 s[20:21], -1, 0
	s_ashr_i32 s50, s33, 31
	s_ashr_i32 s51, s2, 31
	v_and_b32_e32 v4, 0x38000, v4
	v_lshlrev_b32_e32 v5, 11, v169
	s_add_u32 s88, s54, 0xc300800
	v_or3_b32 v4, v139, v4, v5
	s_addc_u32 s89, s55, 0
	v_add_u32_e32 v150, v4, v168
	v_lshlrev_b32_e32 v4, 4, v170
	v_lshl_or_b32 v1, s4, 6, v173
	v_or_b32_e32 v2, v2, v171
	s_mov_b32 s4, 0x18000
	s_mov_b32 s7, 0x1c000
	s_waitcnt vmcnt(6)
	s_add_u32 s90, s54, 0x4200000
	v_and_b32_e32 v4, 0x78000, v4
	v_bitop3_b32 v2, s22, v2, v172 bitop3:0xf6
	s_addc_u32 s91, s55, 0
	v_or3_b32 v4, v139, v4, v5
	s_add_i32 s93, s1, 0x100
	s_add_i32 s94, s5, 0x100
	s_add_i32 s99, s4, 0x100
	s_add_i32 s14, s7, 0x100
	v_or_b32_e32 v164, 16, v1
	v_or_b32_e32 v165, 32, v1
	v_or_b32_e32 v174, 48, v1
	v_add_u32_e32 v175, 0x80, v1
	v_add_u32_e32 v176, 0x90, v1
	v_add_u32_e32 v177, 0xa0, v1
	v_add_u32_e32 v178, 0xb0, v1
	v_or_b32_e32 v179, s15, v10
	v_mov_b32_e32 v151, v149
	v_add_u32_e32 v152, v4, v168
	v_mov_b32_e32 v153, v149
	s_mov_b32 s92, 0
	s_mov_b32 s100, 15
	v_mov_b64_e32 v[154:155], 0x430
	v_mov_b64_e32 v[156:157], 0x42f
	v_add_u32_e32 v180, s93, v2
	v_add_u32_e32 v181, s94, v2
	v_add_u32_e32 v182, 0x100, v3
	s_movk_i32 s95, 0x40ff
	s_mov_b32 s96, 0x7e07e07f
	s_movk_i32 s97, 0xefc0
	s_movk_i32 s98, 0x1010
	s_mov_b32 s22, 0x3e38aa3b
	v_add_u32_e32 v183, s99, v2
	v_add_u32_e32 v184, s14, v2
	s_barrier
	s_branch .LBB0_135

;     __host__ __device__ bool next(int i, Unit& u) const {
;         const long L = (long)i * G + c; if (L >= nwg) return false;
;         int wgid = (int)L; { const int q = nwg / NXCD, r = nwg % NXCD, xcd = wgid % NXCD, off = wgid / NXCD; wgid = (xcd < r ? xcd * (q + 1) : r * (q + 1) + (xcd - r) * q) + off; }
;         const int nig = WGM * nN, gid = wgid / nig, fm = gid * WGM, gsz = (nM - fm) < WGM ? (nM - fm) : WGM;
;         u.pm = fm + ((wgid % nig) % gsz); u.pn = (wgid % nig) / gsz; return true;
;     }
; template <class Epi, class Sched, bool ALIGN_EPI = false, bool SP2 = false>
; __device__ __forceinline__ void gemm_phase(PG8_LAS unsigned char* lds, const Gemm g, const Sched& S, const Epi& E) {
;     ...
;     f32x4 acc[2][2][4][2];
; #pragma unroll
;     for (int a = 0; a < 2; ++a)
; #pragma unroll
;         for (int b = 0; b < 2; ++b)
; #pragma unroll
;             for (int m = 0; m < 4; ++m)
; #pragma unroll
;                 for (int n = 0; n < 2; ++n) acc[a][b][m][n] = (f32x4){0.f, 0.f, 0.f, 0.f};
.LBB0_134:
	s_mov_b32 s100, s101
	s_andn2_b64 vcc, exec, s[0:1]
	s_mov_b32 s0, s24
	s_mov_b32 s6, s26
	s_mov_b64 s[10:11], s[30:31]
	s_mov_b64 s[8:9], s[28:29]
	s_cbranch_vccz .LBB0_344
.LBB0_135:
	s_add_i32 s92, s92, 1
	s_mul_i32 s1, s92, s50
	s_mul_hi_u32 s4, s92, s33
	s_add_i32 s4, s4, s1
	s_mul_i32 s1, s92, s33
	s_add_u32 s28, s1, s2
	s_addc_u32 s29, s4, s51
	s_mov_b32 s101, 15
	s_cmp_lg_u32 s92, 4
	s_cbranch_scc1 .Lp1q_hdr_done
	s_and_b32 s1, s2, 7
	s_mul_i32 s1, s1, 24
	s_lshr_b32 s28, s2, 3
	s_add_i32 s1, s1, s28
	s_lshr_b32 s28, s1, 2
	s_add_i32 s28, s28, 0x400
	s_cmp_lt_u32 s2, 0xc0
	s_cselect_b32 s28, s28, 0x7fffffff
	s_mov_b32 s29, 0
	s_and_b32 s1, s1, 3
	s_lshl_b32 s101, 1, s1
.Lp1q_hdr_done:
	v_cmp_gt_i64_e32 vcc, s[28:29], v[156:157]
	v_cmp_lt_i64_e64 s[4:5], s[28:29], v[154:155]
	s_cbranch_vccnz .LBB0_137
	s_ashr_i32 s1, s28, 31
	s_lshr_b32 s1, s1, 29
	s_add_i32 s1, s28, s1
	s_ashr_i32 s7, s1, 3
	s_and_b32 s1, s1, -8
	s_sub_i32 s1, s28, s1
	s_cmp_lt_i32 s1, 0
	s_movk_i32 s15, 0x87
	s_cselect_b32 s15, s15, 0x86
	s_mul_i32 s1, s1, s15
	s_add_i32 s1, s1, s7
	s_ashr_i32 s7, s1, 31
	s_lshr_b32 s7, s7, 25
	s_add_i32 s7, s1, s7
	s_ashr_i32 s15, s7, 7
	s_lshl_b32 s15, s15, 3
	s_sub_i32 s24, 0x43, s15
	s_min_i32 s25, s24, 8
	s_abs_i32 s24, s25
	v_cvt_f32_u32_e32 v2, s24
	s_sub_i32 s27, 0, s24
	s_and_b32 s7, s7, 0xffffff80
	s_sub_i32 s1, s1, s7
	v_rcp_iflag_f32_e32 v2, v2
	s_abs_i32 s7, s1
	s_xor_b32 s26, s1, s25
	s_ashr_i32 s26, s26, 31
	v_mul_f32_e32 v2, 0x4f7ffffe, v2
	v_cvt_u32_f32_e32 v2, v2
	s_nop 0
	v_readfirstlane_b32 s28, v2
	s_mul_i32 s27, s27, s28
	s_mul_hi_u32 s27, s28, s27
	s_add_i32 s28, s28, s27
	s_mul_hi_u32 s27, s7, s28
	s_mul_i32 s28, s27, s24
	s_sub_i32 s7, s7, s28
	s_add_i32 s29, s27, 1
	s_sub_i32 s28, s7, s24
	s_cmp_ge_u32 s7, s24
	s_cselect_b32 s27, s29, s27
	s_cselect_b32 s7, s28, s7
	s_add_i32 s28, s27, 1
	s_cmp_ge_u32 s7, s24
	s_cselect_b32 s7, s28, s27
	s_xor_b32 s7, s7, s26
	s_sub_i32 s24, s7, s26
	s_mul_i32 s7, s24, s25
	s_sub_i32 s1, s1, s7
	s_add_i32 s26, s15, s1
.LBB0_137:
	s_ashr_i32 s27, s26, 31
	s_lshl_b64 s[28:29], s[26:27], 19
	s_add_u32 s28, s66, s28
	s_addc_u32 s29, s67, s29
	s_and_b64 s[30:31], s[4:5], exec
	s_cselect_b32 s1, s29, s9
	s_cselect_b32 s7, s28, s8
	s_ashr_i32 s25, s24, 31
	s_lshl_b64 s[30:31], s[24:25], 19
	s_add_u32 s30, s62, s30
	s_addc_u32 s31, s63, s31
	s_and_b64 s[34:35], s[4:5], exec
	s_cselect_b32 s15, s31, s11
	s_cselect_b32 s25, s30, s10
	s_add_u32 s8, s8, 0x40080
	s_addc_u32 s9, s9, 0
	s_add_u32 s27, s10, 0x100
	v_mov_b32_e32 v2, 0
	s_addc_u32 s36, s11, 0
	s_mov_b32 s37, -2
	v_mov_b32_e32 v3, v2
	v_mov_b32_e32 v4, v2
	v_mov_b32_e32 v5, v2
	v_mov_b32_e32 v6, v2
	v_mov_b32_e32 v7, v2
	v_mov_b32_e32 v8, v2
	v_mov_b32_e32 v9, v2
	v_mov_b32_e32 v18, v2
	v_mov_b32_e32 v19, v2
	v_mov_b32_e32 v20, v2
	v_mov_b32_e32 v21, v2
	v_mov_b32_e32 v22, v2
	v_mov_b32_e32 v23, v2
	v_mov_b32_e32 v24, v2
	v_mov_b32_e32 v25, v2
	v_mov_b32_e32 v34, v2
	v_mov_b32_e32 v35, v2
	v_mov_b32_e32 v36, v2
	v_mov_b32_e32 v37, v2
	v_mov_b32_e32 v38, v2
	v_mov_b32_e32 v39, v2
	v_mov_b32_e32 v40, v2
	v_mov_b32_e32 v41, v2
	v_mov_b32_e32 v50, v2
	v_mov_b32_e32 v51, v2
	v_mov_b32_e32 v52, v2
	v_mov_b32_e32 v53, v2
	v_mov_b32_e32 v54, v2
	v_mov_b32_e32 v55, v2
	v_mov_b32_e32 v56, v2
	v_mov_b32_e32 v57, v2
	v_mov_b32_e32 v10, v2
	v_mov_b32_e32 v11, v2
	v_mov_b32_e32 v12, v2
	v_mov_b32_e32 v13, v2
	v_mov_b32_e32 v14, v2
	v_mov_b32_e32 v15, v2
	v_mov_b32_e32 v16, v2
	v_mov_b32_e32 v17, v2
	v_mov_b32_e32 v26, v2
	v_mov_b32_e32 v27, v2
	v_mov_b32_e32 v28, v2
	v_mov_b32_e32 v29, v2
	v_mov_b32_e32 v30, v2
	v_mov_b32_e32 v31, v2
	v_mov_b32_e32 v32, v2
	v_mov_b32_e32 v33, v2
	v_mov_b32_e32 v42, v2
	v_mov_b32_e32 v43, v2
	v_mov_b32_e32 v44, v2
	v_mov_b32_e32 v45, v2
	v_mov_b32_e32 v46, v2
	v_mov_b32_e32 v47, v2
	v_mov_b32_e32 v48, v2
	v_mov_b32_e32 v49, v2
	v_mov_b32_e32 v58, v2
	v_mov_b32_e32 v59, v2
	v_mov_b32_e32 v60, v2
	v_mov_b32_e32 v61, v2
	v_mov_b32_e32 v62, v2
	v_mov_b32_e32 v63, v2
	v_mov_b32_e32 v64, v2
	v_mov_b32_e32 v65, v2
	v_mov_b32_e32 v66, v2
	v_mov_b32_e32 v67, v2
	v_mov_b32_e32 v68, v2
	v_mov_b32_e32 v69, v2
	v_mov_b32_e32 v70, v2
	v_mov_b32_e32 v71, v2
	v_mov_b32_e32 v72, v2
	v_mov_b32_e32 v73, v2
	v_mov_b32_e32 v82, v2
	v_mov_b32_e32 v83, v2
	v_mov_b32_e32 v84, v2
	v_mov_b32_e32 v85, v2
	v_mov_b32_e32 v86, v2
	v_mov_b32_e32 v87, v2
	v_mov_b32_e32 v88, v2
	v_mov_b32_e32 v89, v2
	v_mov_b32_e32 v98, v2
	v_mov_b32_e32 v99, v2
	v_mov_b32_e32 v100, v2
	v_mov_b32_e32 v101, v2
	v_mov_b32_e32 v102, v2
	v_mov_b32_e32 v103, v2
	v_mov_b32_e32 v104, v2
	v_mov_b32_e32 v105, v2
	v_mov_b32_e32 v114, v2
	v_mov_b32_e32 v115, v2
	v_mov_b32_e32 v116, v2
	v_mov_b32_e32 v117, v2
	v_mov_b32_e32 v118, v2
	v_mov_b32_e32 v119, v2
	v_mov_b32_e32 v120, v2
	v_mov_b32_e32 v121, v2
	v_mov_b32_e32 v74, v2
	v_mov_b32_e32 v75, v2
	v_mov_b32_e32 v76, v2
	v_mov_b32_e32 v77, v2
	v_mov_b32_e32 v78, v2
	v_mov_b32_e32 v79, v2
	v_mov_b32_e32 v80, v2
	v_mov_b32_e32 v81, v2
	v_mov_b32_e32 v90, v2
	v_mov_b32_e32 v91, v2
	v_mov_b32_e32 v92, v2
	v_mov_b32_e32 v93, v2
	v_mov_b32_e32 v94, v2
	v_mov_b32_e32 v95, v2
	v_mov_b32_e32 v96, v2
	v_mov_b32_e32 v97, v2
	v_mov_b32_e32 v106, v2
	v_mov_b32_e32 v107, v2
	v_mov_b32_e32 v108, v2
	v_mov_b32_e32 v109, v2
	v_mov_b32_e32 v110, v2
	v_mov_b32_e32 v111, v2
	v_mov_b32_e32 v112, v2
	v_mov_b32_e32 v113, v2
	v_mov_b32_e32 v122, v2
	v_mov_b32_e32 v123, v2
	v_mov_b32_e32 v124, v2
	v_mov_b32_e32 v125, v2
	v_mov_b32_e32 v126, v2
	v_mov_b32_e32 v127, v2
	v_mov_b32_e32 v128, v2
	v_mov_b32_e32 v129, v2
	s_cmp_eq_u32 s100, 15
	s_cbranch_scc0 .Lp1q_kloop

; #define PG8_BAR __builtin_amdgcn_s_barrier()
; template <class Epi, class Sched, bool ALIGN_EPI = false, bool SP2 = false>
; __device__ __forceinline__ void gemm_phase(PG8_LAS unsigned char* lds, const Gemm g, const Sched& S, const Epi& E) {
;     ...
;         if constexpr (ALIGN_EPI) { if (wr == 0) PG8_BAR; }
;         if constexpr (!Epi::AFTER_DRAIN) { E(acc, cur, wr, wc, fr, fq); S.done(cur); }
;     DI void operator()(const f32x4 (&acc)[2][2][4][2], const pg8::Unit& u, int wr, int wc, int fr, int fq) const {
;     ...
;         const int colt = u.pn * 256, seg = colt >> 9;
;         const bool isq = (seg == 0) || (seg == 4), isg = (seg == 3) || (seg == 7), iskv = !isq && !isg;
;         const int oi = seg == 1 ? 0 : seg == 2 ? 1 : seg == 5 ? 2 : 3;
.Lp1q_kexit:
	s_and_b64 vcc, exec, s[20:21]
	s_cbranch_vccz .LBB0_141
	s_barrier
.LBB0_141:
	s_cmp_eq_u32 s100, 15
	s_cbranch_scc0 .Lp1q_epi
	s_ashr_i32 s1, s0, 1
	s_cmp_lt_i32 s1, 2
	s_cbranch_scc1 .LBB0_145
	s_cmp_eq_u32 s1, 2
	s_mov_b64 s[8:9], -1
	s_cbranch_scc0 .LBB0_144
	s_mov_b64 s[8:9], 0

;     DI void operator()(const f32x4 (&acc)[2][2][4][2], const pg8::Unit& u, int wr, int wc, int fr, int fq) const {
;         const Params& p = *pp;
;         const int colt = u.pn * 256, seg = colt >> 9;
;         const bool isq = (seg == 0) || (seg == 4), isg = (seg == 3) || (seg == 7), iskv = !isq && !isg;
;         const int oi = seg == 1 ? 0 : seg == 2 ? 1 : seg == 5 ? 2 : 3;
; #pragma unroll
;         for (int ai = 0; ai < 2; ++ai)
; #pragma unroll
;             for (int m = 0; m < 4; ++m) {
;                 const int R = u.pm * 256 + ai * 128 + wr * 64 + m * 16 + fr;
;                 float* fo = nullptr;
;                 if (iskv) {
;                     if (R < ROWS_P) { const int b = R / LPAD, t = R - b * LPAD; if (t < LP) fo = p.out + O_PAK + oi * PKV_SZ + ((size_t)b * LP + t) * 512 - seg * 512; }
;                     else fo = p.out + O_SAK + oi * SKV_SZ + (size_t)(R - ROWS_P) * 512 - seg * 512;
;                 }
;                 bf16_t* uo = p.u + (size_t)R * NU;
; #pragma unroll
;                 for (int bj = 0; bj < 2; ++bj) {
;                     const int n = colt + bj * 128 + wc * 32 + 8 * fq;
;                     f32x4 v0 = acc[ai][bj][m][0], v1 = acc[ai][bj][m][1];
;                     if (fo) { *(f32x4*)(fo + n) = v0; *(f32x4*)(fo + n + 4) = v1; }
.Lp1q_epi:
	v_lshl_or_b32 v186, s0, 8, v179
	v_lshlrev_b32_e32 v187, 13, v173
	v_lshl_add_u32 v187, v186, 1, v187
	v_and_b32_e32 v188, 0x1ff, v186
	v_lshlrev_b32_e32 v188, 2, v188
	v_lshl_add_u32 v188, v173, 11, v188
	s_and_b64 s[8:9], s[12:13], exec
	s_cselect_b32 s7, 64, 0
	s_lshl_b32 s1, s6, 8
	s_add_i32 s1, s1, s7
	s_lshr_b32 s15, s0, 1
	s_and_b32 s7, s15, 3
	s_mov_b32 s25, 1
	s_cmp_eq_u32 s7, 0
	s_cselect_b32 s25, 0, s25
	s_cmp_eq_u32 s7, 3
	s_cselect_b32 s25, 2, s25
	s_lshr_b32 s27, s15, 2
	s_lshl_b32 s27, s27, 1
	s_add_i32 s27, s27, s7
	s_add_i32 s27, s27, -1
	s_mul_i32 s7, s27, 0x2020000
	s_add_u32 s34, s90, s7
	s_addc_u32 s35, s91, 0
	s_lshl_b32 s7, s27, 20
	s_add_u32 s36, s88, s7
	s_addc_u32 s37, s89, 0
	s_bitcmp1_b32 s100, 0
	s_cbranch_scc1 .Lp1q_v0
	s_bitcmp1_b32 s100, 1
	s_cbranch_scc1 .Lp1q_v1
	s_bitcmp1_b32 s100, 2
	s_cbranch_scc1 .Lp1q_v2
	s_branch .Lp1q_v3
.Lp1q_v0:
	s_add_i32 s27, s1, 0
	s_lshl_b32 s7, s27, 13
	s_add_u32 s10, s68, s7
	s_addc_u32 s11, s69, 0
	s_cmp_lg_u32 s25, 1
	s_cbranch_scc1 .Lp1q_nokv_0_0
	s_cmp_ge_u32 s27, 0x4100
	s_cbranch_scc1 .Lp1q_smp_0_0
	s_mul_hi_u32 s7, s27, 0x7e07e07f
	s_lshr_b32 s7, s7, 11
	s_mul_i32 s8, s7, 0x1040
	s_sub_i32 s8, s27, s8
	s_cmp_ge_u32 s8, 0x1010
	s_cbranch_scc1 .Lp1q_kvdone_0_0
	s_mul_i32 s7, s7, 0x1010
	s_add_i32 s7, s7, s8
	s_lshl_b32 s7, s7, 11
	s_add_u32 s8, s34, s7
	s_addc_u32 s9, s35, 0
	s_branch .Lp1q_kvst_0_0
.Lp1q_smp_0_0:
	s_sub_i32 s7, s27, 0x4100
	s_lshl_b32 s7, s7, 11
	s_add_u32 s8, s36, s7
	s_addc_u32 s9, s37, 0
.Lp1q_kvst_0_0:
	global_store_dwordx4 v188, v[126:129], s[8:9]
	global_store_dwordx4 v188, v[122:125], s[8:9] offset:16

; DI unsigned pk2(float a, float b) { f32x2 v = {a, b}; bf16x2v r = __builtin_convertvector(v, bf16x2v); return __builtin_bit_cast(unsigned, r); }
;     DI void operator()(const f32x4 (&acc)[2][2][4][2], const pg8::Unit& u, int wr, int wc, int fr, int fq) const {
;     ...
;                 const int R = u.pm * 256 + ai * 128 + wr * 64 + m * 16 + fr;
;                 float* fo = nullptr;
;                 if (iskv) {
;                     if (R < ROWS_P) { const int b = R / LPAD, t = R - b * LPAD; if (t < LP) fo = p.out + O_PAK + oi * PKV_SZ + ((size_t)b * LP + t) * 512 - seg * 512; }
;                     else fo = p.out + O_SAK + oi * SKV_SZ + (size_t)(R - ROWS_P) * 512 - seg * 512;
;                 }
;                 bf16_t* uo = p.u + (size_t)R * NU;
; #pragma unroll
;                 for (int bj = 0; bj < 2; ++bj) {
;                     const int n = colt + bj * 128 + wc * 32 + 8 * fq;
;                     f32x4 v0 = acc[ai][bj][m][0], v1 = acc[ai][bj][m][1];
;                     if (fo) { *(f32x4*)(fo + n) = v0; *(f32x4*)(fo + n + 4) = v1; }
;                     if (isq) { v0 = v0 * QSCALE; v1 = v1 * QSCALE; }
;                     else if (isg) {
; #pragma unroll
;                         for (int j = 0; j < 4; ++j) { v0[j] = v0[j] / (1.0f + __expf(-v0[j])); v1[j] = v1[j] / (1.0f + __expf(-v1[j])); }
;                     }
;                     *(u32x4*)(uo + n) = (u32x4){pk2(v0[0], v0[1]), pk2(v0[2], v0[3]), pk2(v1[0], v1[1]), pk2(v1[2], v1[3])};
;                 }
.Lp1q_nokv_0_0:
	s_cmp_eq_u32 s25, 2
	s_cbranch_scc1 .Lp1q_gate_0_0
	v_pk_mul_f32 v[126:127], v[126:127], s[22:23] op_sel_hi:[1,0]
	v_pk_mul_f32 v[128:129], v[128:129], s[22:23] op_sel_hi:[1,0]
	v_pk_mul_f32 v[122:123], v[122:123], s[22:23] op_sel_hi:[1,0]
	v_pk_mul_f32 v[124:125], v[124:125], s[22:23] op_sel_hi:[1,0]
	s_branch .Lp1q_cvt_0_0
.Lp1q_gate_0_0:
	v_mul_f32_e32 v194, 0xbfb8aa3b, v126
	v_exp_f32_e32 v194, v194
	s_nop 0
	v_add_f32_e32 v194, 1.0, v194
	v_div_scale_f32 v195, s[38:39], v194, v194, v126
	v_rcp_f32_e32 v196, v195
	s_nop 0
	v_fma_f32 v197, -v195, v196, 1.0
	v_fmac_f32_e32 v196, v197, v196
	v_div_scale_f32 v197, vcc, v126, v194, v126
	v_mul_f32_e32 v198, v197, v196
	v_fma_f32 v199, -v195, v198, v197
	v_fmac_f32_e32 v198, v199, v196
	v_fma_f32 v195, -v195, v198, v197
	v_div_fmas_f32 v195, v195, v196, v198
	v_div_fixup_f32 v126, v195, v194, v126
	v_mul_f32_e32 v194, 0xbfb8aa3b, v127
	v_exp_f32_e32 v194, v194
	s_nop 0
	v_add_f32_e32 v194, 1.0, v194
	v_div_scale_f32 v195, s[38:39], v194, v194, v127
	v_rcp_f32_e32 v196, v195
	s_nop 0
	v_fma_f32 v197, -v195, v196, 1.0
	v_fmac_f32_e32 v196, v197, v196
	v_div_scale_f32 v197, vcc, v127, v194, v127
	v_mul_f32_e32 v198, v197, v196
	v_fma_f32 v199, -v195, v198, v197
	v_fmac_f32_e32 v198, v199, v196
	v_fma_f32 v195, -v195, v198, v197
	v_div_fmas_f32 v195, v195, v196, v198
	v_div_fixup_f32 v127, v195, v194, v127
	v_mul_f32_e32 v194, 0xbfb8aa3b, v128
	v_exp_f32_e32 v194, v194
	s_nop 0
	v_add_f32_e32 v194, 1.0, v194
	v_div_scale_f32 v195, s[38:39], v194, v194, v128
	v_rcp_f32_e32 v196, v195
	s_nop 0
	v_fma_f32 v197, -v195, v196, 1.0
	v_fmac_f32_e32 v196, v197, v196
	v_div_scale_f32 v197, vcc, v128, v194, v128
	v_mul_f32_e32 v198, v197, v196
	v_fma_f32 v199, -v195, v198, v197
	v_fmac_f32_e32 v198, v199, v196
	v_fma_f32 v195, -v195, v198, v197
	v_div_fmas_f32 v195, v195, v196, v198
	v_div_fixup_f32 v128, v195, v194, v128
	v_mul_f32_e32 v194, 0xbfb8aa3b, v129
	v_exp_f32_e32 v194, v194
	s_nop 0
	v_add_f32_e32 v194, 1.0, v194
	v_div_scale_f32 v195, s[38:39], v194, v194, v129
	v_rcp_f32_e32 v196, v195
	s_nop 0
	v_fma_f32 v197, -v195, v196, 1.0
	v_fmac_f32_e32 v196, v197, v196
	v_div_scale_f32 v197, vcc, v129, v194, v129
	v_mul_f32_e32 v198, v197, v196
	v_fma_f32 v199, -v195, v198, v197
	v_fmac_f32_e32 v198, v199, v196
	v_fma_f32 v195, -v195, v198, v197
	v_div_fmas_f32 v195, v195, v196, v198
	v_div_fixup_f32 v129, v195, v194, v129
	v_mul_f32_e32 v194, 0xbfb8aa3b, v122
	v_exp_f32_e32 v194, v194
	s_nop 0
	v_add_f32_e32 v194, 1.0, v194
	v_div_scale_f32 v195, s[38:39], v194, v194, v122
	v_rcp_f32_e32 v196, v195
	s_nop 0
	v_fma_f32 v197, -v195, v196, 1.0
	v_fmac_f32_e32 v196, v197, v196
	v_div_scale_f32 v197, vcc, v122, v194, v122
	v_mul_f32_e32 v198, v197, v196
	v_fma_f32 v199, -v195, v198, v197
	v_fmac_f32_e32 v198, v199, v196
	v_fma_f32 v195, -v195, v198, v197
	v_div_fmas_f32 v195, v195, v196, v198
	v_div_fixup_f32 v122, v195, v194, v122
	v_mul_f32_e32 v194, 0xbfb8aa3b, v123
	v_exp_f32_e32 v194, v194
	s_nop 0
	v_add_f32_e32 v194, 1.0, v194
	v_div_scale_f32 v195, s[38:39], v194, v194, v123
	v_rcp_f32_e32 v196, v195
	s_nop 0
	v_fma_f32 v197, -v195, v196, 1.0
	v_fmac_f32_e32 v196, v197, v196
	v_div_scale_f32 v197, vcc, v123, v194, v123
	v_mul_f32_e32 v198, v197, v196
	v_fma_f32 v199, -v195, v198, v197
	v_fmac_f32_e32 v198, v199, v196
	v_fma_f32 v195, -v195, v198, v197
	v_div_fmas_f32 v195, v195, v196, v198
	v_div_fixup_f32 v123, v195, v194, v123
	v_mul_f32_e32 v194, 0xbfb8aa3b, v124
	v_exp_f32_e32 v194, v194
	s_nop 0
	v_add_f32_e32 v194, 1.0, v194
	v_div_scale_f32 v195, s[38:39], v194, v194, v124
	v_rcp_f32_e32 v196, v195
	s_nop 0
	v_fma_f32 v197, -v195, v196, 1.0
	v_fmac_f32_e32 v196, v197, v196
	v_div_scale_f32 v197, vcc, v124, v194, v124
	v_mul_f32_e32 v198, v197, v196
	v_fma_f32 v199, -v195, v198, v197
	v_fmac_f32_e32 v198, v199, v196
	v_fma_f32 v195, -v195, v198, v197
	v_div_fmas_f32 v195, v195, v196, v198
	v_div_fixup_f32 v124, v195, v194, v124
	v_mul_f32_e32 v194, 0xbfb8aa3b, v125
	v_exp_f32_e32 v194, v194
	s_nop 0
	v_add_f32_e32 v194, 1.0, v194
	v_div_scale_f32 v195, s[38:39], v194, v194, v125
	v_rcp_f32_e32 v196, v195
	s_nop 0
	v_fma_f32 v197, -v195, v196, 1.0
	v_fmac_f32_e32 v196, v197, v196
	v_div_scale_f32 v197, vcc, v125, v194, v125
	v_mul_f32_e32 v198, v197, v196
	v_fma_f32 v199, -v195, v198, v197
	v_fmac_f32_e32 v198, v199, v196
	v_fma_f32 v195, -v195, v198, v197
	v_div_fmas_f32 v195, v195, v196, v198
	v_div_fixup_f32 v125, v195, v194, v125
.Lp1q_cvt_0_0:
	v_cvt_pk_bf16_f32 v190, v126, v127
	v_cvt_pk_bf16_f32 v191, v128, v129
	v_cvt_pk_bf16_f32 v192, v122, v123
	v_cvt_pk_bf16_f32 v193, v124, v125
	global_store_dwordx4 v187, v[190:193], s[10:11]
	s_nop 1
	s_add_i32 s27, s1, 16
	s_lshl_b32 s7, s27, 13
	s_add_u32 s10, s68, s7
	s_addc_u32 s11, s69, 0
	s_cmp_lg_u32 s25, 1
	s_cbranch_scc1 .Lp1q_nokv_0_1
	s_cmp_ge_u32 s27, 0x4100
	s_cbranch_scc1 .Lp1q_smp_0_1
	s_mul_hi_u32 s7, s27, 0x7e07e07f
	s_lshr_b32 s7, s7, 11
	s_mul_i32 s8, s7, 0x1040
	s_sub_i32 s8, s27, s8
	s_cmp_ge_u32 s8, 0x1010
	s_cbranch_scc1 .Lp1q_kvdone_0_1
	s_mul_i32 s7, s7, 0x1010
	s_add_i32 s7, s7, s8
	s_lshl_b32 s7, s7, 11
	s_add_u32 s8, s34, s7
	s_addc_u32 s9, s35, 0
	s_branch .Lp1q_kvst_0_1

;     DI void operator()(const f32x4 (&acc)[2][2][4][2], const pg8::Unit& u, int wr, int wc, int fr, int fq) const {
;     ...
;                     if (R < ROWS_P) { const int b = R / LPAD, t = R - b * LPAD; if (t < LP) fo = p.out + O_PAK + oi * PKV_SZ + ((size_t)b * LP + t) * 512 - seg * 512; }
;                     else fo = p.out + O_SAK + oi * SKV_SZ + (size_t)(R - ROWS_P) * 512 - seg * 512;
;                 }
;                 bf16_t* uo = p.u + (size_t)R * NU;
; #pragma unroll
;                 for (int bj = 0; bj < 2; ++bj) {
;                     const int n = colt + bj * 128 + wc * 32 + 8 * fq;
;                     f32x4 v0 = acc[ai][bj][m][0], v1 = acc[ai][bj][m][1];
;                     if (fo) { *(f32x4*)(fo + n) = v0; *(f32x4*)(fo + n + 4) = v1; }
.Lp1q_kvst_0_1:
	global_store_dwordx4 v188, v[110:113], s[8:9]
	global_store_dwordx4 v188, v[106:109], s[8:9] offset:16

; DI unsigned pk2(float a, float b) { f32x2 v = {a, b}; bf16x2v r = __builtin_convertvector(v, bf16x2v); return __builtin_bit_cast(unsigned, r); }
;     DI void operator()(const f32x4 (&acc)[2][2][4][2], const pg8::Unit& u, int wr, int wc, int fr, int fq) const {
;     ...
;                 const int R = u.pm * 256 + ai * 128 + wr * 64 + m * 16 + fr;
;                 float* fo = nullptr;
;                 if (iskv) {
;                     if (R < ROWS_P) { const int b = R / LPAD, t = R - b * LPAD; if (t < LP) fo = p.out + O_PAK + oi * PKV_SZ + ((size_t)b * LP + t) * 512 - seg * 512; }
;                     else fo = p.out + O_SAK + oi * SKV_SZ + (size_t)(R - ROWS_P) * 512 - seg * 512;
;                 }
;                 bf16_t* uo = p.u + (size_t)R * NU;
; #pragma unroll
;                 for (int bj = 0; bj < 2; ++bj) {
;                     const int n = colt + bj * 128 + wc * 32 + 8 * fq;
;                     f32x4 v0 = acc[ai][bj][m][0], v1 = acc[ai][bj][m][1];
;                     if (fo) { *(f32x4*)(fo + n) = v0; *(f32x4*)(fo + n + 4) = v1; }
;                     if (isq) { v0 = v0 * QSCALE; v1 = v1 * QSCALE; }
;                     else if (isg) {
; #pragma unroll
;                         for (int j = 0; j < 4; ++j) { v0[j] = v0[j] / (1.0f + __expf(-v0[j])); v1[j] = v1[j] / (1.0f + __expf(-v1[j])); }
;                     }
;                     *(u32x4*)(uo + n) = (u32x4){pk2(v0[0], v0[1]), pk2(v0[2], v0[3]), pk2(v1[0], v1[1]), pk2(v1[2], v1[3])};
;                 }
.Lp1q_nokv_0_1:
	s_cmp_eq_u32 s25, 2
	s_cbranch_scc1 .Lp1q_gate_0_1
	v_pk_mul_f32 v[110:111], v[110:111], s[22:23] op_sel_hi:[1,0]
	v_pk_mul_f32 v[112:113], v[112:113], s[22:23] op_sel_hi:[1,0]
	v_pk_mul_f32 v[106:107], v[106:107], s[22:23] op_sel_hi:[1,0]
	v_pk_mul_f32 v[108:109], v[108:109], s[22:23] op_sel_hi:[1,0]
	s_branch .Lp1q_cvt_0_1
.Lp1q_gate_0_1:
	v_mul_f32_e32 v194, 0xbfb8aa3b, v110
	v_exp_f32_e32 v194, v194
	s_nop 0
	v_add_f32_e32 v194, 1.0, v194
	v_div_scale_f32 v195, s[38:39], v194, v194, v110
	v_rcp_f32_e32 v196, v195
	s_nop 0
	v_fma_f32 v197, -v195, v196, 1.0
	v_fmac_f32_e32 v196, v197, v196
	v_div_scale_f32 v197, vcc, v110, v194, v110
	v_mul_f32_e32 v198, v197, v196
	v_fma_f32 v199, -v195, v198, v197
	v_fmac_f32_e32 v198, v199, v196
	v_fma_f32 v195, -v195, v198, v197
	v_div_fmas_f32 v195, v195, v196, v198
	v_div_fixup_f32 v110, v195, v194, v110
	v_mul_f32_e32 v194, 0xbfb8aa3b, v111
	v_exp_f32_e32 v194, v194
	s_nop 0
	v_add_f32_e32 v194, 1.0, v194
	v_div_scale_f32 v195, s[38:39], v194, v194, v111
	v_rcp_f32_e32 v196, v195
	s_nop 0
	v_fma_f32 v197, -v195, v196, 1.0
	v_fmac_f32_e32 v196, v197, v196
	v_div_scale_f32 v197, vcc, v111, v194, v111
	v_mul_f32_e32 v198, v197, v196
	v_fma_f32 v199, -v195, v198, v197
	v_fmac_f32_e32 v198, v199, v196
	v_fma_f32 v195, -v195, v198, v197
	v_div_fmas_f32 v195, v195, v196, v198
	v_div_fixup_f32 v111, v195, v194, v111
	v_mul_f32_e32 v194, 0xbfb8aa3b, v112
	v_exp_f32_e32 v194, v194
	s_nop 0
	v_add_f32_e32 v194, 1.0, v194
	v_div_scale_f32 v195, s[38:39], v194, v194, v112
	v_rcp_f32_e32 v196, v195
	s_nop 0
	v_fma_f32 v197, -v195, v196, 1.0
	v_fmac_f32_e32 v196, v197, v196
	v_div_scale_f32 v197, vcc, v112, v194, v112
	v_mul_f32_e32 v198, v197, v196
	v_fma_f32 v199, -v195, v198, v197
	v_fmac_f32_e32 v198, v199, v196
	v_fma_f32 v195, -v195, v198, v197
	v_div_fmas_f32 v195, v195, v196, v198
	v_div_fixup_f32 v112, v195, v194, v112
	v_mul_f32_e32 v194, 0xbfb8aa3b, v113
	v_exp_f32_e32 v194, v194
	s_nop 0
	v_add_f32_e32 v194, 1.0, v194
	v_div_scale_f32 v195, s[38:39], v194, v194, v113
	v_rcp_f32_e32 v196, v195
	s_nop 0
	v_fma_f32 v197, -v195, v196, 1.0
	v_fmac_f32_e32 v196, v197, v196
	v_div_scale_f32 v197, vcc, v113, v194, v113
	v_mul_f32_e32 v198, v197, v196
	v_fma_f32 v199, -v195, v198, v197
	v_fmac_f32_e32 v198, v199, v196
	v_fma_f32 v195, -v195, v198, v197
	v_div_fmas_f32 v195, v195, v196, v198
	v_div_fixup_f32 v113, v195, v194, v113
	v_mul_f32_e32 v194, 0xbfb8aa3b, v106
	v_exp_f32_e32 v194, v194
	s_nop 0
	v_add_f32_e32 v194, 1.0, v194
	v_div_scale_f32 v195, s[38:39], v194, v194, v106
	v_rcp_f32_e32 v196, v195
	s_nop 0
	v_fma_f32 v197, -v195, v196, 1.0
	v_fmac_f32_e32 v196, v197, v196
	v_div_scale_f32 v197, vcc, v106, v194, v106
	v_mul_f32_e32 v198, v197, v196
	v_fma_f32 v199, -v195, v198, v197
	v_fmac_f32_e32 v198, v199, v196
	v_fma_f32 v195, -v195, v198, v197
	v_div_fmas_f32 v195, v195, v196, v198
	v_div_fixup_f32 v106, v195, v194, v106
	v_mul_f32_e32 v194, 0xbfb8aa3b, v107
	v_exp_f32_e32 v194, v194
	s_nop 0
	v_add_f32_e32 v194, 1.0, v194
	v_div_scale_f32 v195, s[38:39], v194, v194, v107
	v_rcp_f32_e32 v196, v195
	s_nop 0
	v_fma_f32 v197, -v195, v196, 1.0
	v_fmac_f32_e32 v196, v197, v196
	v_div_scale_f32 v197, vcc, v107, v194, v107
	v_mul_f32_e32 v198, v197, v196
	v_fma_f32 v199, -v195, v198, v197
	v_fmac_f32_e32 v198, v199, v196
	v_fma_f32 v195, -v195, v198, v197
	v_div_fmas_f32 v195, v195, v196, v198
	v_div_fixup_f32 v107, v195, v194, v107
	v_mul_f32_e32 v194, 0xbfb8aa3b, v108
	v_exp_f32_e32 v194, v194
	s_nop 0
	v_add_f32_e32 v194, 1.0, v194
	v_div_scale_f32 v195, s[38:39], v194, v194, v108
	v_rcp_f32_e32 v196, v195
	s_nop 0
	v_fma_f32 v197, -v195, v196, 1.0
	v_fmac_f32_e32 v196, v197, v196
	v_div_scale_f32 v197, vcc, v108, v194, v108
	v_mul_f32_e32 v198, v197, v196
	v_fma_f32 v199, -v195, v198, v197
	v_fmac_f32_e32 v198, v199, v196
	v_fma_f32 v195, -v195, v198, v197
	v_div_fmas_f32 v195, v195, v196, v198
	v_div_fixup_f32 v108, v195, v194, v108
	v_mul_f32_e32 v194, 0xbfb8aa3b, v109
	v_exp_f32_e32 v194, v194
	s_nop 0
	v_add_f32_e32 v194, 1.0, v194
	v_div_scale_f32 v195, s[38:39], v194, v194, v109
	v_rcp_f32_e32 v196, v195
	s_nop 0
	v_fma_f32 v197, -v195, v196, 1.0
	v_fmac_f32_e32 v196, v197, v196
	v_div_scale_f32 v197, vcc, v109, v194, v109
	v_mul_f32_e32 v198, v197, v196
	v_fma_f32 v199, -v195, v198, v197
	v_fmac_f32_e32 v198, v199, v196
	v_fma_f32 v195, -v195, v198, v197
	v_div_fmas_f32 v195, v195, v196, v198
	v_div_fixup_f32 v109, v195, v194, v109
.Lp1q_cvt_0_1:
	v_cvt_pk_bf16_f32 v190, v110, v111
	v_cvt_pk_bf16_f32 v191, v112, v113
	v_cvt_pk_bf16_f32 v192, v106, v107
	v_cvt_pk_bf16_f32 v193, v108, v109
	global_store_dwordx4 v187, v[190:193], s[10:11]
	s_nop 1
	s_add_i32 s27, s1, 32
	s_lshl_b32 s7, s27, 13
	s_add_u32 s10, s68, s7
	s_addc_u32 s11, s69, 0
	s_cmp_lg_u32 s25, 1
	s_cbranch_scc1 .Lp1q_nokv_0_2
	s_cmp_ge_u32 s27, 0x4100
	s_cbranch_scc1 .Lp1q_smp_0_2
	s_mul_hi_u32 s7, s27, 0x7e07e07f
	s_lshr_b32 s7, s7, 11
	s_mul_i32 s8, s7, 0x1040
	s_sub_i32 s8, s27, s8
	s_cmp_ge_u32 s8, 0x1010
	s_cbranch_scc1 .Lp1q_kvdone_0_2
	s_mul_i32 s7, s7, 0x1010
	s_add_i32 s7, s7, s8
	s_lshl_b32 s7, s7, 11
	s_add_u32 s8, s34, s7
	s_addc_u32 s9, s35, 0
	s_branch .Lp1q_kvst_0_2

;     DI void operator()(const f32x4 (&acc)[2][2][4][2], const pg8::Unit& u, int wr, int wc, int fr, int fq) const {
;     ...
;                     if (R < ROWS_P) { const int b = R / LPAD, t = R - b * LPAD; if (t < LP) fo = p.out + O_PAK + oi * PKV_SZ + ((size_t)b * LP + t) * 512 - seg * 512; }
;                     else fo = p.out + O_SAK + oi * SKV_SZ + (size_t)(R - ROWS_P) * 512 - seg * 512;
;                 }
;                 bf16_t* uo = p.u + (size_t)R * NU;
; #pragma unroll
;                 for (int bj = 0; bj < 2; ++bj) {
;                     const int n = colt + bj * 128 + wc * 32 + 8 * fq;
;                     f32x4 v0 = acc[ai][bj][m][0], v1 = acc[ai][bj][m][1];
;                     if (fo) { *(f32x4*)(fo + n) = v0; *(f32x4*)(fo + n + 4) = v1; }
.Lp1q_kvst_0_2:
	global_store_dwordx4 v188, v[94:97], s[8:9]
	global_store_dwordx4 v188, v[90:93], s[8:9] offset:16

; DI unsigned pk2(float a, float b) { f32x2 v = {a, b}; bf16x2v r = __builtin_convertvector(v, bf16x2v); return __builtin_bit_cast(unsigned, r); }
;     DI void operator()(const f32x4 (&acc)[2][2][4][2], const pg8::Unit& u, int wr, int wc, int fr, int fq) const {
;     ...
;                 const int R = u.pm * 256 + ai * 128 + wr * 64 + m * 16 + fr;
;                 float* fo = nullptr;
;                 if (iskv) {
;                     if (R < ROWS_P) { const int b = R / LPAD, t = R - b * LPAD; if (t < LP) fo = p.out + O_PAK + oi * PKV_SZ + ((size_t)b * LP + t) * 512 - seg * 512; }
;                     else fo = p.out + O_SAK + oi * SKV_SZ + (size_t)(R - ROWS_P) * 512 - seg * 512;
;                 }
;                 bf16_t* uo = p.u + (size_t)R * NU;
; #pragma unroll
;                 for (int bj = 0; bj < 2; ++bj) {
;                     const int n = colt + bj * 128 + wc * 32 + 8 * fq;
;                     f32x4 v0 = acc[ai][bj][m][0], v1 = acc[ai][bj][m][1];
;                     if (fo) { *(f32x4*)(fo + n) = v0; *(f32x4*)(fo + n + 4) = v1; }
;                     if (isq) { v0 = v0 * QSCALE; v1 = v1 * QSCALE; }
;                     else if (isg) {
; #pragma unroll
;                         for (int j = 0; j < 4; ++j) { v0[j] = v0[j] / (1.0f + __expf(-v0[j])); v1[j] = v1[j] / (1.0f + __expf(-v1[j])); }
;                     }
;                     *(u32x4*)(uo + n) = (u32x4){pk2(v0[0], v0[1]), pk2(v0[2], v0[3]), pk2(v1[0], v1[1]), pk2(v1[2], v1[3])};
;                 }
.Lp1q_nokv_0_2:
	s_cmp_eq_u32 s25, 2
	s_cbranch_scc1 .Lp1q_gate_0_2
	v_pk_mul_f32 v[94:95], v[94:95], s[22:23] op_sel_hi:[1,0]
	v_pk_mul_f32 v[96:97], v[96:97], s[22:23] op_sel_hi:[1,0]
	v_pk_mul_f32 v[90:91], v[90:91], s[22:23] op_sel_hi:[1,0]
	v_pk_mul_f32 v[92:93], v[92:93], s[22:23] op_sel_hi:[1,0]
	s_branch .Lp1q_cvt_0_2
.Lp1q_gate_0_2:
	v_mul_f32_e32 v194, 0xbfb8aa3b, v94
	v_exp_f32_e32 v194, v194
	s_nop 0
	v_add_f32_e32 v194, 1.0, v194
	v_div_scale_f32 v195, s[38:39], v194, v194, v94
	v_rcp_f32_e32 v196, v195
	s_nop 0
	v_fma_f32 v197, -v195, v196, 1.0
	v_fmac_f32_e32 v196, v197, v196
	v_div_scale_f32 v197, vcc, v94, v194, v94
	v_mul_f32_e32 v198, v197, v196
	v_fma_f32 v199, -v195, v198, v197
	v_fmac_f32_e32 v198, v199, v196
	v_fma_f32 v195, -v195, v198, v197
	v_div_fmas_f32 v195, v195, v196, v198
	v_div_fixup_f32 v94, v195, v194, v94
	v_mul_f32_e32 v194, 0xbfb8aa3b, v95
	v_exp_f32_e32 v194, v194
	s_nop 0
	v_add_f32_e32 v194, 1.0, v194
	v_div_scale_f32 v195, s[38:39], v194, v194, v95
	v_rcp_f32_e32 v196, v195
	s_nop 0
	v_fma_f32 v197, -v195, v196, 1.0
	v_fmac_f32_e32 v196, v197, v196
	v_div_scale_f32 v197, vcc, v95, v194, v95
	v_mul_f32_e32 v198, v197, v196
	v_fma_f32 v199, -v195, v198, v197
	v_fmac_f32_e32 v198, v199, v196
	v_fma_f32 v195, -v195, v198, v197
	v_div_fmas_f32 v195, v195, v196, v198
	v_div_fixup_f32 v95, v195, v194, v95
	v_mul_f32_e32 v194, 0xbfb8aa3b, v96
	v_exp_f32_e32 v194, v194
	s_nop 0
	v_add_f32_e32 v194, 1.0, v194
	v_div_scale_f32 v195, s[38:39], v194, v194, v96
	v_rcp_f32_e32 v196, v195
	s_nop 0
	v_fma_f32 v197, -v195, v196, 1.0
	v_fmac_f32_e32 v196, v197, v196
	v_div_scale_f32 v197, vcc, v96, v194, v96
	v_mul_f32_e32 v198, v197, v196
	v_fma_f32 v199, -v195, v198, v197
	v_fmac_f32_e32 v198, v199, v196
	v_fma_f32 v195, -v195, v198, v197
	v_div_fmas_f32 v195, v195, v196, v198
	v_div_fixup_f32 v96, v195, v194, v96
	v_mul_f32_e32 v194, 0xbfb8aa3b, v97
	v_exp_f32_e32 v194, v194
	s_nop 0
	v_add_f32_e32 v194, 1.0, v194
	v_div_scale_f32 v195, s[38:39], v194, v194, v97
	v_rcp_f32_e32 v196, v195
	s_nop 0
	v_fma_f32 v197, -v195, v196, 1.0
	v_fmac_f32_e32 v196, v197, v196
	v_div_scale_f32 v197, vcc, v97, v194, v97
	v_mul_f32_e32 v198, v197, v196
	v_fma_f32 v199, -v195, v198, v197
	v_fmac_f32_e32 v198, v199, v196
	v_fma_f32 v195, -v195, v198, v197
	v_div_fmas_f32 v195, v195, v196, v198
	v_div_fixup_f32 v97, v195, v194, v97
	v_mul_f32_e32 v194, 0xbfb8aa3b, v90
	v_exp_f32_e32 v194, v194
	s_nop 0
	v_add_f32_e32 v194, 1.0, v194
	v_div_scale_f32 v195, s[38:39], v194, v194, v90
	v_rcp_f32_e32 v196, v195
	s_nop 0
	v_fma_f32 v197, -v195, v196, 1.0
	v_fmac_f32_e32 v196, v197, v196
	v_div_scale_f32 v197, vcc, v90, v194, v90
	v_mul_f32_e32 v198, v197, v196
	v_fma_f32 v199, -v195, v198, v197
	v_fmac_f32_e32 v198, v199, v196
	v_fma_f32 v195, -v195, v198, v197
	v_div_fmas_f32 v195, v195, v196, v198
	v_div_fixup_f32 v90, v195, v194, v90
	v_mul_f32_e32 v194, 0xbfb8aa3b, v91
	v_exp_f32_e32 v194, v194
	s_nop 0
	v_add_f32_e32 v194, 1.0, v194
	v_div_scale_f32 v195, s[38:39], v194, v194, v91
	v_rcp_f32_e32 v196, v195
	s_nop 0
	v_fma_f32 v197, -v195, v196, 1.0
	v_fmac_f32_e32 v196, v197, v196
	v_div_scale_f32 v197, vcc, v91, v194, v91
	v_mul_f32_e32 v198, v197, v196
	v_fma_f32 v199, -v195, v198, v197
	v_fmac_f32_e32 v198, v199, v196
	v_fma_f32 v195, -v195, v198, v197
	v_div_fmas_f32 v195, v195, v196, v198
	v_div_fixup_f32 v91, v195, v194, v91
	v_mul_f32_e32 v194, 0xbfb8aa3b, v92
	v_exp_f32_e32 v194, v194
	s_nop 0
	v_add_f32_e32 v194, 1.0, v194
	v_div_scale_f32 v195, s[38:39], v194, v194, v92
	v_rcp_f32_e32 v196, v195
	s_nop 0
	v_fma_f32 v197, -v195, v196, 1.0
	v_fmac_f32_e32 v196, v197, v196
	v_div_scale_f32 v197, vcc, v92, v194, v92
	v_mul_f32_e32 v198, v197, v196
	v_fma_f32 v199, -v195, v198, v197
	v_fmac_f32_e32 v198, v199, v196
	v_fma_f32 v195, -v195, v198, v197
	v_div_fmas_f32 v195, v195, v196, v198
	v_div_fixup_f32 v92, v195, v194, v92
	v_mul_f32_e32 v194, 0xbfb8aa3b, v93
	v_exp_f32_e32 v194, v194
	s_nop 0
	v_add_f32_e32 v194, 1.0, v194
	v_div_scale_f32 v195, s[38:39], v194, v194, v93
	v_rcp_f32_e32 v196, v195
	s_nop 0
	v_fma_f32 v197, -v195, v196, 1.0
	v_fmac_f32_e32 v196, v197, v196
	v_div_scale_f32 v197, vcc, v93, v194, v93
	v_mul_f32_e32 v198, v197, v196
	v_fma_f32 v199, -v195, v198, v197
	v_fmac_f32_e32 v198, v199, v196
	v_fma_f32 v195, -v195, v198, v197
	v_div_fmas_f32 v195, v195, v196, v198
	v_div_fixup_f32 v93, v195, v194, v93
.Lp1q_cvt_0_2:
	v_cvt_pk_bf16_f32 v190, v94, v95
	v_cvt_pk_bf16_f32 v191, v96, v97
	v_cvt_pk_bf16_f32 v192, v90, v91
	v_cvt_pk_bf16_f32 v193, v92, v93
	global_store_dwordx4 v187, v[190:193], s[10:11]
	s_nop 1
	s_add_i32 s27, s1, 48
	s_lshl_b32 s7, s27, 13
	s_add_u32 s10, s68, s7
	s_addc_u32 s11, s69, 0
	s_cmp_lg_u32 s25, 1
	s_cbranch_scc1 .Lp1q_nokv_0_3
	s_cmp_ge_u32 s27, 0x4100
	s_cbranch_scc1 .Lp1q_smp_0_3
	s_mul_hi_u32 s7, s27, 0x7e07e07f
	s_lshr_b32 s7, s7, 11
	s_mul_i32 s8, s7, 0x1040
	s_sub_i32 s8, s27, s8
	s_cmp_ge_u32 s8, 0x1010
	s_cbranch_scc1 .Lp1q_kvdone_0_3
	s_mul_i32 s7, s7, 0x1010
	s_add_i32 s7, s7, s8
	s_lshl_b32 s7, s7, 11
	s_add_u32 s8, s34, s7
	s_addc_u32 s9, s35, 0
	s_branch .Lp1q_kvst_0_3

;     DI void operator()(const f32x4 (&acc)[2][2][4][2], const pg8::Unit& u, int wr, int wc, int fr, int fq) const {
;     ...
;                     if (R < ROWS_P) { const int b = R / LPAD, t = R - b * LPAD; if (t < LP) fo = p.out + O_PAK + oi * PKV_SZ + ((size_t)b * LP + t) * 512 - seg * 512; }
;                     else fo = p.out + O_SAK + oi * SKV_SZ + (size_t)(R - ROWS_P) * 512 - seg * 512;
;                 }
;                 bf16_t* uo = p.u + (size_t)R * NU;
; #pragma unroll
;                 for (int bj = 0; bj < 2; ++bj) {
;                     const int n = colt + bj * 128 + wc * 32 + 8 * fq;
;                     f32x4 v0 = acc[ai][bj][m][0], v1 = acc[ai][bj][m][1];
;                     if (fo) { *(f32x4*)(fo + n) = v0; *(f32x4*)(fo + n + 4) = v1; }
.Lp1q_kvst_0_3:
	global_store_dwordx4 v188, v[78:81], s[8:9]
	global_store_dwordx4 v188, v[74:77], s[8:9] offset:16

; DI unsigned pk2(float a, float b) { f32x2 v = {a, b}; bf16x2v r = __builtin_convertvector(v, bf16x2v); return __builtin_bit_cast(unsigned, r); }
;     DI void operator()(const f32x4 (&acc)[2][2][4][2], const pg8::Unit& u, int wr, int wc, int fr, int fq) const {
;     ...
;                     if (isq) { v0 = v0 * QSCALE; v1 = v1 * QSCALE; }
;                     else if (isg) {
; #pragma unroll
;                         for (int j = 0; j < 4; ++j) { v0[j] = v0[j] / (1.0f + __expf(-v0[j])); v1[j] = v1[j] / (1.0f + __expf(-v1[j])); }
;                     }
;                     *(u32x4*)(uo + n) = (u32x4){pk2(v0[0], v0[1]), pk2(v0[2], v0[3]), pk2(v1[0], v1[1]), pk2(v1[2], v1[3])};
;                 }
.Lp1q_nokv_0_3:
	s_cmp_eq_u32 s25, 2
	s_cbranch_scc1 .Lp1q_gate_0_3
	v_pk_mul_f32 v[78:79], v[78:79], s[22:23] op_sel_hi:[1,0]
	v_pk_mul_f32 v[80:81], v[80:81], s[22:23] op_sel_hi:[1,0]
	v_pk_mul_f32 v[74:75], v[74:75], s[22:23] op_sel_hi:[1,0]
	v_pk_mul_f32 v[76:77], v[76:77], s[22:23] op_sel_hi:[1,0]
	s_branch .Lp1q_cvt_0_3
.Lp1q_gate_0_3:
	v_mul_f32_e32 v194, 0xbfb8aa3b, v78
	v_exp_f32_e32 v194, v194
	s_nop 0
	v_add_f32_e32 v194, 1.0, v194
	v_div_scale_f32 v195, s[38:39], v194, v194, v78
	v_rcp_f32_e32 v196, v195
	s_nop 0
	v_fma_f32 v197, -v195, v196, 1.0
	v_fmac_f32_e32 v196, v197, v196
	v_div_scale_f32 v197, vcc, v78, v194, v78
	v_mul_f32_e32 v198, v197, v196
	v_fma_f32 v199, -v195, v198, v197
	v_fmac_f32_e32 v198, v199, v196
	v_fma_f32 v195, -v195, v198, v197
	v_div_fmas_f32 v195, v195, v196, v198
	v_div_fixup_f32 v78, v195, v194, v78
	v_mul_f32_e32 v194, 0xbfb8aa3b, v79
	v_exp_f32_e32 v194, v194
	s_nop 0
	v_add_f32_e32 v194, 1.0, v194
	v_div_scale_f32 v195, s[38:39], v194, v194, v79
	v_rcp_f32_e32 v196, v195
	s_nop 0
	v_fma_f32 v197, -v195, v196, 1.0
	v_fmac_f32_e32 v196, v197, v196
	v_div_scale_f32 v197, vcc, v79, v194, v79
	v_mul_f32_e32 v198, v197, v196
	v_fma_f32 v199, -v195, v198, v197
	v_fmac_f32_e32 v198, v199, v196
	v_fma_f32 v195, -v195, v198, v197
	v_div_fmas_f32 v195, v195, v196, v198
	v_div_fixup_f32 v79, v195, v194, v79
	v_mul_f32_e32 v194, 0xbfb8aa3b, v80
	v_exp_f32_e32 v194, v194
	s_nop 0
	v_add_f32_e32 v194, 1.0, v194
	v_div_scale_f32 v195, s[38:39], v194, v194, v80
	v_rcp_f32_e32 v196, v195
	s_nop 0
	v_fma_f32 v197, -v195, v196, 1.0
	v_fmac_f32_e32 v196, v197, v196
	v_div_scale_f32 v197, vcc, v80, v194, v80
	v_mul_f32_e32 v198, v197, v196
	v_fma_f32 v199, -v195, v198, v197
	v_fmac_f32_e32 v198, v199, v196
	v_fma_f32 v195, -v195, v198, v197
	v_div_fmas_f32 v195, v195, v196, v198
	v_div_fixup_f32 v80, v195, v194, v80
	v_mul_f32_e32 v194, 0xbfb8aa3b, v81
	v_exp_f32_e32 v194, v194
	s_nop 0
	v_add_f32_e32 v194, 1.0, v194
	v_div_scale_f32 v195, s[38:39], v194, v194, v81
	v_rcp_f32_e32 v196, v195
	s_nop 0
	v_fma_f32 v197, -v195, v196, 1.0
	v_fmac_f32_e32 v196, v197, v196
	v_div_scale_f32 v197, vcc, v81, v194, v81
	v_mul_f32_e32 v198, v197, v196
	v_fma_f32 v199, -v195, v198, v197
	v_fmac_f32_e32 v198, v199, v196
	v_fma_f32 v195, -v195, v198, v197
	v_div_fmas_f32 v195, v195, v196, v198
	v_div_fixup_f32 v81, v195, v194, v81
	v_mul_f32_e32 v194, 0xbfb8aa3b, v74
	v_exp_f32_e32 v194, v194
	s_nop 0
	v_add_f32_e32 v194, 1.0, v194
	v_div_scale_f32 v195, s[38:39], v194, v194, v74
	v_rcp_f32_e32 v196, v195
	s_nop 0
	v_fma_f32 v197, -v195, v196, 1.0
	v_fmac_f32_e32 v196, v197, v196
	v_div_scale_f32 v197, vcc, v74, v194, v74
	v_mul_f32_e32 v198, v197, v196
	v_fma_f32 v199, -v195, v198, v197
	v_fmac_f32_e32 v198, v199, v196
	v_fma_f32 v195, -v195, v198, v197
	v_div_fmas_f32 v195, v195, v196, v198
	v_div_fixup_f32 v74, v195, v194, v74
	v_mul_f32_e32 v194, 0xbfb8aa3b, v75
	v_exp_f32_e32 v194, v194
	s_nop 0
	v_add_f32_e32 v194, 1.0, v194
	v_div_scale_f32 v195, s[38:39], v194, v194, v75
	v_rcp_f32_e32 v196, v195
	s_nop 0
	v_fma_f32 v197, -v195, v196, 1.0
	v_fmac_f32_e32 v196, v197, v196
	v_div_scale_f32 v197, vcc, v75, v194, v75
	v_mul_f32_e32 v198, v197, v196
	v_fma_f32 v199, -v195, v198, v197
	v_fmac_f32_e32 v198, v199, v196
	v_fma_f32 v195, -v195, v198, v197
	v_div_fmas_f32 v195, v195, v196, v198
	v_div_fixup_f32 v75, v195, v194, v75
	v_mul_f32_e32 v194, 0xbfb8aa3b, v76
	v_exp_f32_e32 v194, v194
	s_nop 0
	v_add_f32_e32 v194, 1.0, v194
	v_div_scale_f32 v195, s[38:39], v194, v194, v76
	v_rcp_f32_e32 v196, v195
	s_nop 0
	v_fma_f32 v197, -v195, v196, 1.0
	v_fmac_f32_e32 v196, v197, v196
	v_div_scale_f32 v197, vcc, v76, v194, v76
	v_mul_f32_e32 v198, v197, v196
	v_fma_f32 v199, -v195, v198, v197
	v_fmac_f32_e32 v198, v199, v196
	v_fma_f32 v195, -v195, v198, v197
	v_div_fmas_f32 v195, v195, v196, v198
	v_div_fixup_f32 v76, v195, v194, v76
	v_mul_f32_e32 v194, 0xbfb8aa3b, v77
	v_exp_f32_e32 v194, v194
	s_nop 0
	v_add_f32_e32 v194, 1.0, v194
	v_div_scale_f32 v195, s[38:39], v194, v194, v77
	v_rcp_f32_e32 v196, v195
	s_nop 0
	v_fma_f32 v197, -v195, v196, 1.0
	v_fmac_f32_e32 v196, v197, v196
	v_div_scale_f32 v197, vcc, v77, v194, v77
	v_mul_f32_e32 v198, v197, v196
	v_fma_f32 v199, -v195, v198, v197
	v_fmac_f32_e32 v198, v199, v196
	v_fma_f32 v195, -v195, v198, v197
	v_div_fmas_f32 v195, v195, v196, v198
	v_div_fixup_f32 v77, v195, v194, v77
.Lp1q_cvt_0_3:
	v_cvt_pk_bf16_f32 v190, v78, v79
	v_cvt_pk_bf16_f32 v191, v80, v81
	v_cvt_pk_bf16_f32 v192, v74, v75
	v_cvt_pk_bf16_f32 v193, v76, v77
	global_store_dwordx4 v187, v[190:193], s[10:11]
	s_nop 1
	s_branch .Lp1q_tail

;     DI void operator()(const f32x4 (&acc)[2][2][4][2], const pg8::Unit& u, int wr, int wc, int fr, int fq) const {
;     ...
;                     if (R < ROWS_P) { const int b = R / LPAD, t = R - b * LPAD; if (t < LP) fo = p.out + O_PAK + oi * PKV_SZ + ((size_t)b * LP + t) * 512 - seg * 512; }
;                     else fo = p.out + O_SAK + oi * SKV_SZ + (size_t)(R - ROWS_P) * 512 - seg * 512;
;                 }
;                 bf16_t* uo = p.u + (size_t)R * NU;
; #pragma unroll
;                 for (int bj = 0; bj < 2; ++bj) {
;                     const int n = colt + bj * 128 + wc * 32 + 8 * fq;
;                     f32x4 v0 = acc[ai][bj][m][0], v1 = acc[ai][bj][m][1];
;                     if (fo) { *(f32x4*)(fo + n) = v0; *(f32x4*)(fo + n + 4) = v1; }
.Lp1q_kvst_1_0:
	global_store_dwordx4 v188, v[118:121], s[8:9] offset:512
	global_store_dwordx4 v188, v[114:117], s[8:9] offset:528

; DI unsigned pk2(float a, float b) { f32x2 v = {a, b}; bf16x2v r = __builtin_convertvector(v, bf16x2v); return __builtin_bit_cast(unsigned, r); }
;     DI void operator()(const f32x4 (&acc)[2][2][4][2], const pg8::Unit& u, int wr, int wc, int fr, int fq) const {
;     ...
;                 const int R = u.pm * 256 + ai * 128 + wr * 64 + m * 16 + fr;
;                 float* fo = nullptr;
;                 if (iskv) {
;                     if (R < ROWS_P) { const int b = R / LPAD, t = R - b * LPAD; if (t < LP) fo = p.out + O_PAK + oi * PKV_SZ + ((size_t)b * LP + t) * 512 - seg * 512; }
;                     else fo = p.out + O_SAK + oi * SKV_SZ + (size_t)(R - ROWS_P) * 512 - seg * 512;
;                 }
;                 bf16_t* uo = p.u + (size_t)R * NU;
; #pragma unroll
;                 for (int bj = 0; bj < 2; ++bj) {
;                     const int n = colt + bj * 128 + wc * 32 + 8 * fq;
;                     f32x4 v0 = acc[ai][bj][m][0], v1 = acc[ai][bj][m][1];
;                     if (fo) { *(f32x4*)(fo + n) = v0; *(f32x4*)(fo + n + 4) = v1; }
;                     if (isq) { v0 = v0 * QSCALE; v1 = v1 * QSCALE; }
;                     else if (isg) {
; #pragma unroll
;                         for (int j = 0; j < 4; ++j) { v0[j] = v0[j] / (1.0f + __expf(-v0[j])); v1[j] = v1[j] / (1.0f + __expf(-v1[j])); }
;                     }
;                     *(u32x4*)(uo + n) = (u32x4){pk2(v0[0], v0[1]), pk2(v0[2], v0[3]), pk2(v1[0], v1[1]), pk2(v1[2], v1[3])};
;                 }
.Lp1q_nokv_1_0:
	s_cmp_eq_u32 s25, 2
	s_cbranch_scc1 .Lp1q_gate_1_0
	v_pk_mul_f32 v[118:119], v[118:119], s[22:23] op_sel_hi:[1,0]
	v_pk_mul_f32 v[120:121], v[120:121], s[22:23] op_sel_hi:[1,0]
	v_pk_mul_f32 v[114:115], v[114:115], s[22:23] op_sel_hi:[1,0]
	v_pk_mul_f32 v[116:117], v[116:117], s[22:23] op_sel_hi:[1,0]
	s_branch .Lp1q_cvt_1_0
.Lp1q_gate_1_0:
	v_mul_f32_e32 v194, 0xbfb8aa3b, v118
	v_exp_f32_e32 v194, v194
	s_nop 0
	v_add_f32_e32 v194, 1.0, v194
	v_div_scale_f32 v195, s[38:39], v194, v194, v118
	v_rcp_f32_e32 v196, v195
	s_nop 0
	v_fma_f32 v197, -v195, v196, 1.0
	v_fmac_f32_e32 v196, v197, v196
	v_div_scale_f32 v197, vcc, v118, v194, v118
	v_mul_f32_e32 v198, v197, v196
	v_fma_f32 v199, -v195, v198, v197
	v_fmac_f32_e32 v198, v199, v196
	v_fma_f32 v195, -v195, v198, v197
	v_div_fmas_f32 v195, v195, v196, v198
	v_div_fixup_f32 v118, v195, v194, v118
	v_mul_f32_e32 v194, 0xbfb8aa3b, v119
	v_exp_f32_e32 v194, v194
	s_nop 0
	v_add_f32_e32 v194, 1.0, v194
	v_div_scale_f32 v195, s[38:39], v194, v194, v119
	v_rcp_f32_e32 v196, v195
	s_nop 0
	v_fma_f32 v197, -v195, v196, 1.0
	v_fmac_f32_e32 v196, v197, v196
	v_div_scale_f32 v197, vcc, v119, v194, v119
	v_mul_f32_e32 v198, v197, v196
	v_fma_f32 v199, -v195, v198, v197
	v_fmac_f32_e32 v198, v199, v196
	v_fma_f32 v195, -v195, v198, v197
	v_div_fmas_f32 v195, v195, v196, v198
	v_div_fixup_f32 v119, v195, v194, v119
	v_mul_f32_e32 v194, 0xbfb8aa3b, v120
	v_exp_f32_e32 v194, v194
	s_nop 0
	v_add_f32_e32 v194, 1.0, v194
	v_div_scale_f32 v195, s[38:39], v194, v194, v120
	v_rcp_f32_e32 v196, v195
	s_nop 0
	v_fma_f32 v197, -v195, v196, 1.0
	v_fmac_f32_e32 v196, v197, v196
	v_div_scale_f32 v197, vcc, v120, v194, v120
	v_mul_f32_e32 v198, v197, v196
	v_fma_f32 v199, -v195, v198, v197
	v_fmac_f32_e32 v198, v199, v196
	v_fma_f32 v195, -v195, v198, v197
	v_div_fmas_f32 v195, v195, v196, v198
	v_div_fixup_f32 v120, v195, v194, v120
	v_mul_f32_e32 v194, 0xbfb8aa3b, v121
	v_exp_f32_e32 v194, v194
	s_nop 0
	v_add_f32_e32 v194, 1.0, v194
	v_div_scale_f32 v195, s[38:39], v194, v194, v121
	v_rcp_f32_e32 v196, v195
	s_nop 0
	v_fma_f32 v197, -v195, v196, 1.0
	v_fmac_f32_e32 v196, v197, v196
	v_div_scale_f32 v197, vcc, v121, v194, v121
	v_mul_f32_e32 v198, v197, v196
	v_fma_f32 v199, -v195, v198, v197
	v_fmac_f32_e32 v198, v199, v196
	v_fma_f32 v195, -v195, v198, v197
	v_div_fmas_f32 v195, v195, v196, v198
	v_div_fixup_f32 v121, v195, v194, v121
	v_mul_f32_e32 v194, 0xbfb8aa3b, v114
	v_exp_f32_e32 v194, v194
	s_nop 0
	v_add_f32_e32 v194, 1.0, v194
	v_div_scale_f32 v195, s[38:39], v194, v194, v114
	v_rcp_f32_e32 v196, v195
	s_nop 0
	v_fma_f32 v197, -v195, v196, 1.0
	v_fmac_f32_e32 v196, v197, v196
	v_div_scale_f32 v197, vcc, v114, v194, v114
	v_mul_f32_e32 v198, v197, v196
	v_fma_f32 v199, -v195, v198, v197
	v_fmac_f32_e32 v198, v199, v196
	v_fma_f32 v195, -v195, v198, v197
	v_div_fmas_f32 v195, v195, v196, v198
	v_div_fixup_f32 v114, v195, v194, v114
	v_mul_f32_e32 v194, 0xbfb8aa3b, v115
	v_exp_f32_e32 v194, v194
	s_nop 0
	v_add_f32_e32 v194, 1.0, v194
	v_div_scale_f32 v195, s[38:39], v194, v194, v115
	v_rcp_f32_e32 v196, v195
	s_nop 0
	v_fma_f32 v197, -v195, v196, 1.0
	v_fmac_f32_e32 v196, v197, v196
	v_div_scale_f32 v197, vcc, v115, v194, v115
	v_mul_f32_e32 v198, v197, v196
	v_fma_f32 v199, -v195, v198, v197
	v_fmac_f32_e32 v198, v199, v196
	v_fma_f32 v195, -v195, v198, v197
	v_div_fmas_f32 v195, v195, v196, v198
	v_div_fixup_f32 v115, v195, v194, v115
	v_mul_f32_e32 v194, 0xbfb8aa3b, v116
	v_exp_f32_e32 v194, v194
	s_nop 0
	v_add_f32_e32 v194, 1.0, v194
	v_div_scale_f32 v195, s[38:39], v194, v194, v116
	v_rcp_f32_e32 v196, v195
	s_nop 0
	v_fma_f32 v197, -v195, v196, 1.0
	v_fmac_f32_e32 v196, v197, v196
	v_div_scale_f32 v197, vcc, v116, v194, v116
	v_mul_f32_e32 v198, v197, v196
	v_fma_f32 v199, -v195, v198, v197
	v_fmac_f32_e32 v198, v199, v196
	v_fma_f32 v195, -v195, v198, v197
	v_div_fmas_f32 v195, v195, v196, v198
	v_div_fixup_f32 v116, v195, v194, v116
	v_mul_f32_e32 v194, 0xbfb8aa3b, v117
	v_exp_f32_e32 v194, v194
	s_nop 0
	v_add_f32_e32 v194, 1.0, v194
	v_div_scale_f32 v195, s[38:39], v194, v194, v117
	v_rcp_f32_e32 v196, v195
	s_nop 0
	v_fma_f32 v197, -v195, v196, 1.0
	v_fmac_f32_e32 v196, v197, v196
	v_div_scale_f32 v197, vcc, v117, v194, v117
	v_mul_f32_e32 v198, v197, v196
	v_fma_f32 v199, -v195, v198, v197
	v_fmac_f32_e32 v198, v199, v196
	v_fma_f32 v195, -v195, v198, v197
	v_div_fmas_f32 v195, v195, v196, v198
	v_div_fixup_f32 v117, v195, v194, v117
.Lp1q_cvt_1_0:
	v_cvt_pk_bf16_f32 v190, v118, v119
	v_cvt_pk_bf16_f32 v191, v120, v121
	v_cvt_pk_bf16_f32 v192, v114, v115
	v_cvt_pk_bf16_f32 v193, v116, v117
	global_store_dwordx4 v187, v[190:193], s[10:11] offset:256
	s_nop 1
	s_add_i32 s27, s1, 16
	s_lshl_b32 s7, s27, 13
	s_add_u32 s10, s68, s7
	s_addc_u32 s11, s69, 0
	s_cmp_lg_u32 s25, 1
	s_cbranch_scc1 .Lp1q_nokv_1_1
	s_cmp_ge_u32 s27, 0x4100
	s_cbranch_scc1 .Lp1q_smp_1_1
	s_mul_hi_u32 s7, s27, 0x7e07e07f
	s_lshr_b32 s7, s7, 11
	s_mul_i32 s8, s7, 0x1040
	s_sub_i32 s8, s27, s8
	s_cmp_ge_u32 s8, 0x1010
	s_cbranch_scc1 .Lp1q_kvdone_1_1
	s_mul_i32 s7, s7, 0x1010
	s_add_i32 s7, s7, s8
	s_lshl_b32 s7, s7, 11
	s_add_u32 s8, s34, s7
	s_addc_u32 s9, s35, 0
	s_branch .Lp1q_kvst_1_1

;     DI void operator()(const f32x4 (&acc)[2][2][4][2], const pg8::Unit& u, int wr, int wc, int fr, int fq) const {
;     ...
;                     if (R < ROWS_P) { const int b = R / LPAD, t = R - b * LPAD; if (t < LP) fo = p.out + O_PAK + oi * PKV_SZ + ((size_t)b * LP + t) * 512 - seg * 512; }
;                     else fo = p.out + O_SAK + oi * SKV_SZ + (size_t)(R - ROWS_P) * 512 - seg * 512;
;                 }
;                 bf16_t* uo = p.u + (size_t)R * NU;
; #pragma unroll
;                 for (int bj = 0; bj < 2; ++bj) {
;                     const int n = colt + bj * 128 + wc * 32 + 8 * fq;
;                     f32x4 v0 = acc[ai][bj][m][0], v1 = acc[ai][bj][m][1];
;                     if (fo) { *(f32x4*)(fo + n) = v0; *(f32x4*)(fo + n + 4) = v1; }
.Lp1q_kvst_1_1:
	global_store_dwordx4 v188, v[102:105], s[8:9] offset:512
	global_store_dwordx4 v188, v[98:101], s[8:9] offset:528

; DI unsigned pk2(float a, float b) { f32x2 v = {a, b}; bf16x2v r = __builtin_convertvector(v, bf16x2v); return __builtin_bit_cast(unsigned, r); }
;     DI void operator()(const f32x4 (&acc)[2][2][4][2], const pg8::Unit& u, int wr, int wc, int fr, int fq) const {
;     ...
;                 const int R = u.pm * 256 + ai * 128 + wr * 64 + m * 16 + fr;
;                 float* fo = nullptr;
;                 if (iskv) {
;                     if (R < ROWS_P) { const int b = R / LPAD, t = R - b * LPAD; if (t < LP) fo = p.out + O_PAK + oi * PKV_SZ + ((size_t)b * LP + t) * 512 - seg * 512; }
;                     else fo = p.out + O_SAK + oi * SKV_SZ + (size_t)(R - ROWS_P) * 512 - seg * 512;
;                 }
;                 bf16_t* uo = p.u + (size_t)R * NU;
; #pragma unroll
;                 for (int bj = 0; bj < 2; ++bj) {
;                     const int n = colt + bj * 128 + wc * 32 + 8 * fq;
;                     f32x4 v0 = acc[ai][bj][m][0], v1 = acc[ai][bj][m][1];
;                     if (fo) { *(f32x4*)(fo + n) = v0; *(f32x4*)(fo + n + 4) = v1; }
;                     if (isq) { v0 = v0 * QSCALE; v1 = v1 * QSCALE; }
;                     else if (isg) {
; #pragma unroll
;                         for (int j = 0; j < 4; ++j) { v0[j] = v0[j] / (1.0f + __expf(-v0[j])); v1[j] = v1[j] / (1.0f + __expf(-v1[j])); }
;                     }
;                     *(u32x4*)(uo + n) = (u32x4){pk2(v0[0], v0[1]), pk2(v0[2], v0[3]), pk2(v1[0], v1[1]), pk2(v1[2], v1[3])};
;                 }
.Lp1q_nokv_1_1:
	s_cmp_eq_u32 s25, 2
	s_cbranch_scc1 .Lp1q_gate_1_1
	v_pk_mul_f32 v[102:103], v[102:103], s[22:23] op_sel_hi:[1,0]
	v_pk_mul_f32 v[104:105], v[104:105], s[22:23] op_sel_hi:[1,0]
	v_pk_mul_f32 v[98:99], v[98:99], s[22:23] op_sel_hi:[1,0]
	v_pk_mul_f32 v[100:101], v[100:101], s[22:23] op_sel_hi:[1,0]
	s_branch .Lp1q_cvt_1_1
.Lp1q_gate_1_1:
	v_mul_f32_e32 v194, 0xbfb8aa3b, v102
	v_exp_f32_e32 v194, v194
	s_nop 0
	v_add_f32_e32 v194, 1.0, v194
	v_div_scale_f32 v195, s[38:39], v194, v194, v102
	v_rcp_f32_e32 v196, v195
	s_nop 0
	v_fma_f32 v197, -v195, v196, 1.0
	v_fmac_f32_e32 v196, v197, v196
	v_div_scale_f32 v197, vcc, v102, v194, v102
	v_mul_f32_e32 v198, v197, v196
	v_fma_f32 v199, -v195, v198, v197
	v_fmac_f32_e32 v198, v199, v196
	v_fma_f32 v195, -v195, v198, v197
	v_div_fmas_f32 v195, v195, v196, v198
	v_div_fixup_f32 v102, v195, v194, v102
	v_mul_f32_e32 v194, 0xbfb8aa3b, v103
	v_exp_f32_e32 v194, v194
	s_nop 0
	v_add_f32_e32 v194, 1.0, v194
	v_div_scale_f32 v195, s[38:39], v194, v194, v103
	v_rcp_f32_e32 v196, v195
	s_nop 0
	v_fma_f32 v197, -v195, v196, 1.0
	v_fmac_f32_e32 v196, v197, v196
	v_div_scale_f32 v197, vcc, v103, v194, v103
	v_mul_f32_e32 v198, v197, v196
	v_fma_f32 v199, -v195, v198, v197
	v_fmac_f32_e32 v198, v199, v196
	v_fma_f32 v195, -v195, v198, v197
	v_div_fmas_f32 v195, v195, v196, v198
	v_div_fixup_f32 v103, v195, v194, v103
	v_mul_f32_e32 v194, 0xbfb8aa3b, v104
	v_exp_f32_e32 v194, v194
	s_nop 0
	v_add_f32_e32 v194, 1.0, v194
	v_div_scale_f32 v195, s[38:39], v194, v194, v104
	v_rcp_f32_e32 v196, v195
	s_nop 0
	v_fma_f32 v197, -v195, v196, 1.0
	v_fmac_f32_e32 v196, v197, v196
	v_div_scale_f32 v197, vcc, v104, v194, v104
	v_mul_f32_e32 v198, v197, v196
	v_fma_f32 v199, -v195, v198, v197
	v_fmac_f32_e32 v198, v199, v196
	v_fma_f32 v195, -v195, v198, v197
	v_div_fmas_f32 v195, v195, v196, v198
	v_div_fixup_f32 v104, v195, v194, v104
	v_mul_f32_e32 v194, 0xbfb8aa3b, v105
	v_exp_f32_e32 v194, v194
	s_nop 0
	v_add_f32_e32 v194, 1.0, v194
	v_div_scale_f32 v195, s[38:39], v194, v194, v105
	v_rcp_f32_e32 v196, v195
	s_nop 0
	v_fma_f32 v197, -v195, v196, 1.0
	v_fmac_f32_e32 v196, v197, v196
	v_div_scale_f32 v197, vcc, v105, v194, v105
	v_mul_f32_e32 v198, v197, v196
	v_fma_f32 v199, -v195, v198, v197
	v_fmac_f32_e32 v198, v199, v196
	v_fma_f32 v195, -v195, v198, v197
	v_div_fmas_f32 v195, v195, v196, v198
	v_div_fixup_f32 v105, v195, v194, v105
	v_mul_f32_e32 v194, 0xbfb8aa3b, v98
	v_exp_f32_e32 v194, v194
	s_nop 0
	v_add_f32_e32 v194, 1.0, v194
	v_div_scale_f32 v195, s[38:39], v194, v194, v98
	v_rcp_f32_e32 v196, v195
	s_nop 0
	v_fma_f32 v197, -v195, v196, 1.0
	v_fmac_f32_e32 v196, v197, v196
	v_div_scale_f32 v197, vcc, v98, v194, v98
	v_mul_f32_e32 v198, v197, v196
	v_fma_f32 v199, -v195, v198, v197
	v_fmac_f32_e32 v198, v199, v196
	v_fma_f32 v195, -v195, v198, v197
	v_div_fmas_f32 v195, v195, v196, v198
	v_div_fixup_f32 v98, v195, v194, v98
	v_mul_f32_e32 v194, 0xbfb8aa3b, v99
	v_exp_f32_e32 v194, v194
	s_nop 0
	v_add_f32_e32 v194, 1.0, v194
	v_div_scale_f32 v195, s[38:39], v194, v194, v99
	v_rcp_f32_e32 v196, v195
	s_nop 0
	v_fma_f32 v197, -v195, v196, 1.0
	v_fmac_f32_e32 v196, v197, v196
	v_div_scale_f32 v197, vcc, v99, v194, v99
	v_mul_f32_e32 v198, v197, v196
	v_fma_f32 v199, -v195, v198, v197
	v_fmac_f32_e32 v198, v199, v196
	v_fma_f32 v195, -v195, v198, v197
	v_div_fmas_f32 v195, v195, v196, v198
	v_div_fixup_f32 v99, v195, v194, v99
	v_mul_f32_e32 v194, 0xbfb8aa3b, v100
	v_exp_f32_e32 v194, v194
	s_nop 0
	v_add_f32_e32 v194, 1.0, v194
	v_div_scale_f32 v195, s[38:39], v194, v194, v100
	v_rcp_f32_e32 v196, v195
	s_nop 0
	v_fma_f32 v197, -v195, v196, 1.0
	v_fmac_f32_e32 v196, v197, v196
	v_div_scale_f32 v197, vcc, v100, v194, v100
	v_mul_f32_e32 v198, v197, v196
	v_fma_f32 v199, -v195, v198, v197
	v_fmac_f32_e32 v198, v199, v196
	v_fma_f32 v195, -v195, v198, v197
	v_div_fmas_f32 v195, v195, v196, v198
	v_div_fixup_f32 v100, v195, v194, v100
	v_mul_f32_e32 v194, 0xbfb8aa3b, v101
	v_exp_f32_e32 v194, v194
	s_nop 0
	v_add_f32_e32 v194, 1.0, v194
	v_div_scale_f32 v195, s[38:39], v194, v194, v101
	v_rcp_f32_e32 v196, v195
	s_nop 0
	v_fma_f32 v197, -v195, v196, 1.0
	v_fmac_f32_e32 v196, v197, v196
	v_div_scale_f32 v197, vcc, v101, v194, v101
	v_mul_f32_e32 v198, v197, v196
	v_fma_f32 v199, -v195, v198, v197
	v_fmac_f32_e32 v198, v199, v196
	v_fma_f32 v195, -v195, v198, v197
	v_div_fmas_f32 v195, v195, v196, v198
	v_div_fixup_f32 v101, v195, v194, v101
.Lp1q_cvt_1_1:
	v_cvt_pk_bf16_f32 v190, v102, v103
	v_cvt_pk_bf16_f32 v191, v104, v105
	v_cvt_pk_bf16_f32 v192, v98, v99
	v_cvt_pk_bf16_f32 v193, v100, v101
	global_store_dwordx4 v187, v[190:193], s[10:11] offset:256
	s_nop 1
	s_add_i32 s27, s1, 32
	s_lshl_b32 s7, s27, 13
	s_add_u32 s10, s68, s7
	s_addc_u32 s11, s69, 0
	s_cmp_lg_u32 s25, 1
	s_cbranch_scc1 .Lp1q_nokv_1_2
	s_cmp_ge_u32 s27, 0x4100
	s_cbranch_scc1 .Lp1q_smp_1_2
	s_mul_hi_u32 s7, s27, 0x7e07e07f
	s_lshr_b32 s7, s7, 11
	s_mul_i32 s8, s7, 0x1040
	s_sub_i32 s8, s27, s8
	s_cmp_ge_u32 s8, 0x1010
	s_cbranch_scc1 .Lp1q_kvdone_1_2
	s_mul_i32 s7, s7, 0x1010
	s_add_i32 s7, s7, s8
	s_lshl_b32 s7, s7, 11
	s_add_u32 s8, s34, s7
	s_addc_u32 s9, s35, 0
	s_branch .Lp1q_kvst_1_2

;     DI void operator()(const f32x4 (&acc)[2][2][4][2], const pg8::Unit& u, int wr, int wc, int fr, int fq) const {
;     ...
;                     if (R < ROWS_P) { const int b = R / LPAD, t = R - b * LPAD; if (t < LP) fo = p.out + O_PAK + oi * PKV_SZ + ((size_t)b * LP + t) * 512 - seg * 512; }
;                     else fo = p.out + O_SAK + oi * SKV_SZ + (size_t)(R - ROWS_P) * 512 - seg * 512;
;                 }
;                 bf16_t* uo = p.u + (size_t)R * NU;
; #pragma unroll
;                 for (int bj = 0; bj < 2; ++bj) {
;                     const int n = colt + bj * 128 + wc * 32 + 8 * fq;
;                     f32x4 v0 = acc[ai][bj][m][0], v1 = acc[ai][bj][m][1];
;                     if (fo) { *(f32x4*)(fo + n) = v0; *(f32x4*)(fo + n + 4) = v1; }
.Lp1q_kvst_1_2:
	global_store_dwordx4 v188, v[86:89], s[8:9] offset:512
	global_store_dwordx4 v188, v[82:85], s[8:9] offset:528

; DI unsigned pk2(float a, float b) { f32x2 v = {a, b}; bf16x2v r = __builtin_convertvector(v, bf16x2v); return __builtin_bit_cast(unsigned, r); }
;     DI void operator()(const f32x4 (&acc)[2][2][4][2], const pg8::Unit& u, int wr, int wc, int fr, int fq) const {
;     ...
;                 const int R = u.pm * 256 + ai * 128 + wr * 64 + m * 16 + fr;
;                 float* fo = nullptr;
;                 if (iskv) {
;                     if (R < ROWS_P) { const int b = R / LPAD, t = R - b * LPAD; if (t < LP) fo = p.out + O_PAK + oi * PKV_SZ + ((size_t)b * LP + t) * 512 - seg * 512; }
;                     else fo = p.out + O_SAK + oi * SKV_SZ + (size_t)(R - ROWS_P) * 512 - seg * 512;
;                 }
;                 bf16_t* uo = p.u + (size_t)R * NU;
; #pragma unroll
;                 for (int bj = 0; bj < 2; ++bj) {
;                     const int n = colt + bj * 128 + wc * 32 + 8 * fq;
;                     f32x4 v0 = acc[ai][bj][m][0], v1 = acc[ai][bj][m][1];
;                     if (fo) { *(f32x4*)(fo + n) = v0; *(f32x4*)(fo + n + 4) = v1; }
;                     if (isq) { v0 = v0 * QSCALE; v1 = v1 * QSCALE; }
;                     else if (isg) {
; #pragma unroll
;                         for (int j = 0; j < 4; ++j) { v0[j] = v0[j] / (1.0f + __expf(-v0[j])); v1[j] = v1[j] / (1.0f + __expf(-v1[j])); }
;                     }
;                     *(u32x4*)(uo + n) = (u32x4){pk2(v0[0], v0[1]), pk2(v0[2], v0[3]), pk2(v1[0], v1[1]), pk2(v1[2], v1[3])};
;                 }
.Lp1q_nokv_1_2:
	s_cmp_eq_u32 s25, 2
	s_cbranch_scc1 .Lp1q_gate_1_2
	v_pk_mul_f32 v[86:87], v[86:87], s[22:23] op_sel_hi:[1,0]
	v_pk_mul_f32 v[88:89], v[88:89], s[22:23] op_sel_hi:[1,0]
	v_pk_mul_f32 v[82:83], v[82:83], s[22:23] op_sel_hi:[1,0]
	v_pk_mul_f32 v[84:85], v[84:85], s[22:23] op_sel_hi:[1,0]
	s_branch .Lp1q_cvt_1_2
.Lp1q_gate_1_2:
	v_mul_f32_e32 v194, 0xbfb8aa3b, v86
	v_exp_f32_e32 v194, v194
	s_nop 0
	v_add_f32_e32 v194, 1.0, v194
	v_div_scale_f32 v195, s[38:39], v194, v194, v86
	v_rcp_f32_e32 v196, v195
	s_nop 0
	v_fma_f32 v197, -v195, v196, 1.0
	v_fmac_f32_e32 v196, v197, v196
	v_div_scale_f32 v197, vcc, v86, v194, v86
	v_mul_f32_e32 v198, v197, v196
	v_fma_f32 v199, -v195, v198, v197
	v_fmac_f32_e32 v198, v199, v196
	v_fma_f32 v195, -v195, v198, v197
	v_div_fmas_f32 v195, v195, v196, v198
	v_div_fixup_f32 v86, v195, v194, v86
	v_mul_f32_e32 v194, 0xbfb8aa3b, v87
	v_exp_f32_e32 v194, v194
	s_nop 0
	v_add_f32_e32 v194, 1.0, v194
	v_div_scale_f32 v195, s[38:39], v194, v194, v87
	v_rcp_f32_e32 v196, v195
	s_nop 0
	v_fma_f32 v197, -v195, v196, 1.0
	v_fmac_f32_e32 v196, v197, v196
	v_div_scale_f32 v197, vcc, v87, v194, v87
	v_mul_f32_e32 v198, v197, v196
	v_fma_f32 v199, -v195, v198, v197
	v_fmac_f32_e32 v198, v199, v196
	v_fma_f32 v195, -v195, v198, v197
	v_div_fmas_f32 v195, v195, v196, v198
	v_div_fixup_f32 v87, v195, v194, v87
	v_mul_f32_e32 v194, 0xbfb8aa3b, v88
	v_exp_f32_e32 v194, v194
	s_nop 0
	v_add_f32_e32 v194, 1.0, v194
	v_div_scale_f32 v195, s[38:39], v194, v194, v88
	v_rcp_f32_e32 v196, v195
	s_nop 0
	v_fma_f32 v197, -v195, v196, 1.0
	v_fmac_f32_e32 v196, v197, v196
	v_div_scale_f32 v197, vcc, v88, v194, v88
	v_mul_f32_e32 v198, v197, v196
	v_fma_f32 v199, -v195, v198, v197
	v_fmac_f32_e32 v198, v199, v196
	v_fma_f32 v195, -v195, v198, v197
	v_div_fmas_f32 v195, v195, v196, v198
	v_div_fixup_f32 v88, v195, v194, v88
	v_mul_f32_e32 v194, 0xbfb8aa3b, v89
	v_exp_f32_e32 v194, v194
	s_nop 0
	v_add_f32_e32 v194, 1.0, v194
	v_div_scale_f32 v195, s[38:39], v194, v194, v89
	v_rcp_f32_e32 v196, v195
	s_nop 0
	v_fma_f32 v197, -v195, v196, 1.0
	v_fmac_f32_e32 v196, v197, v196
	v_div_scale_f32 v197, vcc, v89, v194, v89
	v_mul_f32_e32 v198, v197, v196
	v_fma_f32 v199, -v195, v198, v197
	v_fmac_f32_e32 v198, v199, v196
	v_fma_f32 v195, -v195, v198, v197
	v_div_fmas_f32 v195, v195, v196, v198
	v_div_fixup_f32 v89, v195, v194, v89
	v_mul_f32_e32 v194, 0xbfb8aa3b, v82
	v_exp_f32_e32 v194, v194
	s_nop 0
	v_add_f32_e32 v194, 1.0, v194
	v_div_scale_f32 v195, s[38:39], v194, v194, v82
	v_rcp_f32_e32 v196, v195
	s_nop 0
	v_fma_f32 v197, -v195, v196, 1.0
	v_fmac_f32_e32 v196, v197, v196
	v_div_scale_f32 v197, vcc, v82, v194, v82
	v_mul_f32_e32 v198, v197, v196
	v_fma_f32 v199, -v195, v198, v197
	v_fmac_f32_e32 v198, v199, v196
	v_fma_f32 v195, -v195, v198, v197
	v_div_fmas_f32 v195, v195, v196, v198
	v_div_fixup_f32 v82, v195, v194, v82
	v_mul_f32_e32 v194, 0xbfb8aa3b, v83
	v_exp_f32_e32 v194, v194
	s_nop 0
	v_add_f32_e32 v194, 1.0, v194
	v_div_scale_f32 v195, s[38:39], v194, v194, v83
	v_rcp_f32_e32 v196, v195
	s_nop 0
	v_fma_f32 v197, -v195, v196, 1.0
	v_fmac_f32_e32 v196, v197, v196
	v_div_scale_f32 v197, vcc, v83, v194, v83
	v_mul_f32_e32 v198, v197, v196
	v_fma_f32 v199, -v195, v198, v197
	v_fmac_f32_e32 v198, v199, v196
	v_fma_f32 v195, -v195, v198, v197
	v_div_fmas_f32 v195, v195, v196, v198
	v_div_fixup_f32 v83, v195, v194, v83
	v_mul_f32_e32 v194, 0xbfb8aa3b, v84
	v_exp_f32_e32 v194, v194
	s_nop 0
	v_add_f32_e32 v194, 1.0, v194
	v_div_scale_f32 v195, s[38:39], v194, v194, v84
	v_rcp_f32_e32 v196, v195
	s_nop 0
	v_fma_f32 v197, -v195, v196, 1.0
	v_fmac_f32_e32 v196, v197, v196
	v_div_scale_f32 v197, vcc, v84, v194, v84
	v_mul_f32_e32 v198, v197, v196
	v_fma_f32 v199, -v195, v198, v197
	v_fmac_f32_e32 v198, v199, v196
	v_fma_f32 v195, -v195, v198, v197
	v_div_fmas_f32 v195, v195, v196, v198
	v_div_fixup_f32 v84, v195, v194, v84
	v_mul_f32_e32 v194, 0xbfb8aa3b, v85
	v_exp_f32_e32 v194, v194
	s_nop 0
	v_add_f32_e32 v194, 1.0, v194
	v_div_scale_f32 v195, s[38:39], v194, v194, v85
	v_rcp_f32_e32 v196, v195
	s_nop 0
	v_fma_f32 v197, -v195, v196, 1.0
	v_fmac_f32_e32 v196, v197, v196
	v_div_scale_f32 v197, vcc, v85, v194, v85
	v_mul_f32_e32 v198, v197, v196
	v_fma_f32 v199, -v195, v198, v197
	v_fmac_f32_e32 v198, v199, v196
	v_fma_f32 v195, -v195, v198, v197
	v_div_fmas_f32 v195, v195, v196, v198
	v_div_fixup_f32 v85, v195, v194, v85
.Lp1q_cvt_1_2:
	v_cvt_pk_bf16_f32 v190, v86, v87
	v_cvt_pk_bf16_f32 v191, v88, v89
	v_cvt_pk_bf16_f32 v192, v82, v83
	v_cvt_pk_bf16_f32 v193, v84, v85
	global_store_dwordx4 v187, v[190:193], s[10:11] offset:256
	s_nop 1
	s_add_i32 s27, s1, 48
	s_lshl_b32 s7, s27, 13
	s_add_u32 s10, s68, s7
	s_addc_u32 s11, s69, 0
	s_cmp_lg_u32 s25, 1
	s_cbranch_scc1 .Lp1q_nokv_1_3
	s_cmp_ge_u32 s27, 0x4100
	s_cbranch_scc1 .Lp1q_smp_1_3
	s_mul_hi_u32 s7, s27, 0x7e07e07f
	s_lshr_b32 s7, s7, 11
	s_mul_i32 s8, s7, 0x1040
	s_sub_i32 s8, s27, s8
	s_cmp_ge_u32 s8, 0x1010
	s_cbranch_scc1 .Lp1q_kvdone_1_3
	s_mul_i32 s7, s7, 0x1010
	s_add_i32 s7, s7, s8
	s_lshl_b32 s7, s7, 11
	s_add_u32 s8, s34, s7
	s_addc_u32 s9, s35, 0
	s_branch .Lp1q_kvst_1_3

;     DI void operator()(const f32x4 (&acc)[2][2][4][2], const pg8::Unit& u, int wr, int wc, int fr, int fq) const {
;     ...
;                     if (R < ROWS_P) { const int b = R / LPAD, t = R - b * LPAD; if (t < LP) fo = p.out + O_PAK + oi * PKV_SZ + ((size_t)b * LP + t) * 512 - seg * 512; }
;                     else fo = p.out + O_SAK + oi * SKV_SZ + (size_t)(R - ROWS_P) * 512 - seg * 512;
;                 }
;                 bf16_t* uo = p.u + (size_t)R * NU;
; #pragma unroll
;                 for (int bj = 0; bj < 2; ++bj) {
;                     const int n = colt + bj * 128 + wc * 32 + 8 * fq;
;                     f32x4 v0 = acc[ai][bj][m][0], v1 = acc[ai][bj][m][1];
;                     if (fo) { *(f32x4*)(fo + n) = v0; *(f32x4*)(fo + n + 4) = v1; }
.Lp1q_kvst_1_3:
	global_store_dwordx4 v188, v[70:73], s[8:9] offset:512
	global_store_dwordx4 v188, v[66:69], s[8:9] offset:528

; DI unsigned pk2(float a, float b) { f32x2 v = {a, b}; bf16x2v r = __builtin_convertvector(v, bf16x2v); return __builtin_bit_cast(unsigned, r); }
;     DI void operator()(const f32x4 (&acc)[2][2][4][2], const pg8::Unit& u, int wr, int wc, int fr, int fq) const {
;     ...
;                 const int R = u.pm * 256 + ai * 128 + wr * 64 + m * 16 + fr;
;                 float* fo = nullptr;
;                 if (iskv) {
;                     if (R < ROWS_P) { const int b = R / LPAD, t = R - b * LPAD; if (t < LP) fo = p.out + O_PAK + oi * PKV_SZ + ((size_t)b * LP + t) * 512 - seg * 512; }
;                     else fo = p.out + O_SAK + oi * SKV_SZ + (size_t)(R - ROWS_P) * 512 - seg * 512;
;                 }
;                 bf16_t* uo = p.u + (size_t)R * NU;
; #pragma unroll
;                 for (int bj = 0; bj < 2; ++bj) {
;                     const int n = colt + bj * 128 + wc * 32 + 8 * fq;
;                     f32x4 v0 = acc[ai][bj][m][0], v1 = acc[ai][bj][m][1];
;                     if (fo) { *(f32x4*)(fo + n) = v0; *(f32x4*)(fo + n + 4) = v1; }
;                     if (isq) { v0 = v0 * QSCALE; v1 = v1 * QSCALE; }
;                     else if (isg) {
; #pragma unroll
;                         for (int j = 0; j < 4; ++j) { v0[j] = v0[j] / (1.0f + __expf(-v0[j])); v1[j] = v1[j] / (1.0f + __expf(-v1[j])); }
;                     }
;                     *(u32x4*)(uo + n) = (u32x4){pk2(v0[0], v0[1]), pk2(v0[2], v0[3]), pk2(v1[0], v1[1]), pk2(v1[2], v1[3])};
;                 }
.Lp1q_nokv_1_3:
	s_cmp_eq_u32 s25, 2
	s_cbranch_scc1 .Lp1q_gate_1_3
	v_pk_mul_f32 v[70:71], v[70:71], s[22:23] op_sel_hi:[1,0]
	v_pk_mul_f32 v[72:73], v[72:73], s[22:23] op_sel_hi:[1,0]
	v_pk_mul_f32 v[66:67], v[66:67], s[22:23] op_sel_hi:[1,0]
	v_pk_mul_f32 v[68:69], v[68:69], s[22:23] op_sel_hi:[1,0]
	s_branch .Lp1q_cvt_1_3
.Lp1q_gate_1_3:
	v_mul_f32_e32 v194, 0xbfb8aa3b, v70
	v_exp_f32_e32 v194, v194
	s_nop 0
	v_add_f32_e32 v194, 1.0, v194
	v_div_scale_f32 v195, s[38:39], v194, v194, v70
	v_rcp_f32_e32 v196, v195
	s_nop 0
	v_fma_f32 v197, -v195, v196, 1.0
	v_fmac_f32_e32 v196, v197, v196
	v_div_scale_f32 v197, vcc, v70, v194, v70
	v_mul_f32_e32 v198, v197, v196
	v_fma_f32 v199, -v195, v198, v197
	v_fmac_f32_e32 v198, v199, v196
	v_fma_f32 v195, -v195, v198, v197
	v_div_fmas_f32 v195, v195, v196, v198
	v_div_fixup_f32 v70, v195, v194, v70
	v_mul_f32_e32 v194, 0xbfb8aa3b, v71
	v_exp_f32_e32 v194, v194
	s_nop 0
	v_add_f32_e32 v194, 1.0, v194
	v_div_scale_f32 v195, s[38:39], v194, v194, v71
	v_rcp_f32_e32 v196, v195
	s_nop 0
	v_fma_f32 v197, -v195, v196, 1.0
	v_fmac_f32_e32 v196, v197, v196
	v_div_scale_f32 v197, vcc, v71, v194, v71
	v_mul_f32_e32 v198, v197, v196
	v_fma_f32 v199, -v195, v198, v197
	v_fmac_f32_e32 v198, v199, v196
	v_fma_f32 v195, -v195, v198, v197
	v_div_fmas_f32 v195, v195, v196, v198
	v_div_fixup_f32 v71, v195, v194, v71
	v_mul_f32_e32 v194, 0xbfb8aa3b, v72
	v_exp_f32_e32 v194, v194
	s_nop 0
	v_add_f32_e32 v194, 1.0, v194
	v_div_scale_f32 v195, s[38:39], v194, v194, v72
	v_rcp_f32_e32 v196, v195
	s_nop 0
	v_fma_f32 v197, -v195, v196, 1.0
	v_fmac_f32_e32 v196, v197, v196
	v_div_scale_f32 v197, vcc, v72, v194, v72
	v_mul_f32_e32 v198, v197, v196
	v_fma_f32 v199, -v195, v198, v197
	v_fmac_f32_e32 v198, v199, v196
	v_fma_f32 v195, -v195, v198, v197
	v_div_fmas_f32 v195, v195, v196, v198
	v_div_fixup_f32 v72, v195, v194, v72
	v_mul_f32_e32 v194, 0xbfb8aa3b, v73
	v_exp_f32_e32 v194, v194
	s_nop 0
	v_add_f32_e32 v194, 1.0, v194
	v_div_scale_f32 v195, s[38:39], v194, v194, v73
	v_rcp_f32_e32 v196, v195
	s_nop 0
	v_fma_f32 v197, -v195, v196, 1.0
	v_fmac_f32_e32 v196, v197, v196
	v_div_scale_f32 v197, vcc, v73, v194, v73
	v_mul_f32_e32 v198, v197, v196
	v_fma_f32 v199, -v195, v198, v197
	v_fmac_f32_e32 v198, v199, v196
	v_fma_f32 v195, -v195, v198, v197
	v_div_fmas_f32 v195, v195, v196, v198
	v_div_fixup_f32 v73, v195, v194, v73
	v_mul_f32_e32 v194, 0xbfb8aa3b, v66
	v_exp_f32_e32 v194, v194
	s_nop 0
	v_add_f32_e32 v194, 1.0, v194
	v_div_scale_f32 v195, s[38:39], v194, v194, v66
	v_rcp_f32_e32 v196, v195
	s_nop 0
	v_fma_f32 v197, -v195, v196, 1.0
	v_fmac_f32_e32 v196, v197, v196
	v_div_scale_f32 v197, vcc, v66, v194, v66
	v_mul_f32_e32 v198, v197, v196
	v_fma_f32 v199, -v195, v198, v197
	v_fmac_f32_e32 v198, v199, v196
	v_fma_f32 v195, -v195, v198, v197
	v_div_fmas_f32 v195, v195, v196, v198
	v_div_fixup_f32 v66, v195, v194, v66
	v_mul_f32_e32 v194, 0xbfb8aa3b, v67
	v_exp_f32_e32 v194, v194
	s_nop 0
	v_add_f32_e32 v194, 1.0, v194
	v_div_scale_f32 v195, s[38:39], v194, v194, v67
	v_rcp_f32_e32 v196, v195
	s_nop 0
	v_fma_f32 v197, -v195, v196, 1.0
	v_fmac_f32_e32 v196, v197, v196
	v_div_scale_f32 v197, vcc, v67, v194, v67
	v_mul_f32_e32 v198, v197, v196
	v_fma_f32 v199, -v195, v198, v197
	v_fmac_f32_e32 v198, v199, v196
	v_fma_f32 v195, -v195, v198, v197
	v_div_fmas_f32 v195, v195, v196, v198
	v_div_fixup_f32 v67, v195, v194, v67
	v_mul_f32_e32 v194, 0xbfb8aa3b, v68
	v_exp_f32_e32 v194, v194
	s_nop 0
	v_add_f32_e32 v194, 1.0, v194
	v_div_scale_f32 v195, s[38:39], v194, v194, v68
	v_rcp_f32_e32 v196, v195
	s_nop 0
	v_fma_f32 v197, -v195, v196, 1.0
	v_fmac_f32_e32 v196, v197, v196
	v_div_scale_f32 v197, vcc, v68, v194, v68
	v_mul_f32_e32 v198, v197, v196
	v_fma_f32 v199, -v195, v198, v197
	v_fmac_f32_e32 v198, v199, v196
	v_fma_f32 v195, -v195, v198, v197
	v_div_fmas_f32 v195, v195, v196, v198
	v_div_fixup_f32 v68, v195, v194, v68
	v_mul_f32_e32 v194, 0xbfb8aa3b, v69
	v_exp_f32_e32 v194, v194
	s_nop 0
	v_add_f32_e32 v194, 1.0, v194
	v_div_scale_f32 v195, s[38:39], v194, v194, v69
	v_rcp_f32_e32 v196, v195
	s_nop 0
	v_fma_f32 v197, -v195, v196, 1.0
	v_fmac_f32_e32 v196, v197, v196
	v_div_scale_f32 v197, vcc, v69, v194, v69
	v_mul_f32_e32 v198, v197, v196
	v_fma_f32 v199, -v195, v198, v197
	v_fmac_f32_e32 v198, v199, v196
	v_fma_f32 v195, -v195, v198, v197
	v_div_fmas_f32 v195, v195, v196, v198
	v_div_fixup_f32 v69, v195, v194, v69
.Lp1q_cvt_1_3:
	v_cvt_pk_bf16_f32 v190, v70, v71
	v_cvt_pk_bf16_f32 v191, v72, v73
	v_cvt_pk_bf16_f32 v192, v66, v67
	v_cvt_pk_bf16_f32 v193, v68, v69
	global_store_dwordx4 v187, v[190:193], s[10:11] offset:256
	s_nop 1
	s_branch .Lp1q_tail
.Lp1q_v2:
	s_add_i32 s27, s1, 128
	s_lshl_b32 s7, s27, 13
	s_add_u32 s10, s68, s7
	s_addc_u32 s11, s69, 0
	s_cmp_lg_u32 s25, 1
	s_cbranch_scc1 .Lp1q_nokv_2_0
	s_cmp_ge_u32 s27, 0x4100
	s_cbranch_scc1 .Lp1q_smp_2_0
	s_mul_hi_u32 s7, s27, 0x7e07e07f
	s_lshr_b32 s7, s7, 11
	s_mul_i32 s8, s7, 0x1040
	s_sub_i32 s8, s27, s8
	s_cmp_ge_u32 s8, 0x1010
	s_cbranch_scc1 .Lp1q_kvdone_2_0
	s_mul_i32 s7, s7, 0x1010
	s_add_i32 s7, s7, s8
	s_lshl_b32 s7, s7, 11
	s_add_u32 s8, s34, s7
	s_addc_u32 s9, s35, 0
	s_branch .Lp1q_kvst_2_0

;     DI void operator()(const f32x4 (&acc)[2][2][4][2], const pg8::Unit& u, int wr, int wc, int fr, int fq) const {
;     ...
;                     if (R < ROWS_P) { const int b = R / LPAD, t = R - b * LPAD; if (t < LP) fo = p.out + O_PAK + oi * PKV_SZ + ((size_t)b * LP + t) * 512 - seg * 512; }
;                     else fo = p.out + O_SAK + oi * SKV_SZ + (size_t)(R - ROWS_P) * 512 - seg * 512;
;                 }
;                 bf16_t* uo = p.u + (size_t)R * NU;
; #pragma unroll
;                 for (int bj = 0; bj < 2; ++bj) {
;                     const int n = colt + bj * 128 + wc * 32 + 8 * fq;
;                     f32x4 v0 = acc[ai][bj][m][0], v1 = acc[ai][bj][m][1];
;                     if (fo) { *(f32x4*)(fo + n) = v0; *(f32x4*)(fo + n + 4) = v1; }
.Lp1q_kvst_2_0:
	global_store_dwordx4 v188, v[62:65], s[8:9]
	global_store_dwordx4 v188, v[58:61], s[8:9] offset:16

; DI unsigned pk2(float a, float b) { f32x2 v = {a, b}; bf16x2v r = __builtin_convertvector(v, bf16x2v); return __builtin_bit_cast(unsigned, r); }
;     DI void operator()(const f32x4 (&acc)[2][2][4][2], const pg8::Unit& u, int wr, int wc, int fr, int fq) const {
;     ...
;                 const int R = u.pm * 256 + ai * 128 + wr * 64 + m * 16 + fr;
;                 float* fo = nullptr;
;                 if (iskv) {
;                     if (R < ROWS_P) { const int b = R / LPAD, t = R - b * LPAD; if (t < LP) fo = p.out + O_PAK + oi * PKV_SZ + ((size_t)b * LP + t) * 512 - seg * 512; }
;                     else fo = p.out + O_SAK + oi * SKV_SZ + (size_t)(R - ROWS_P) * 512 - seg * 512;
;                 }
;                 bf16_t* uo = p.u + (size_t)R * NU;
; #pragma unroll
;                 for (int bj = 0; bj < 2; ++bj) {
;                     const int n = colt + bj * 128 + wc * 32 + 8 * fq;
;                     f32x4 v0 = acc[ai][bj][m][0], v1 = acc[ai][bj][m][1];
;                     if (fo) { *(f32x4*)(fo + n) = v0; *(f32x4*)(fo + n + 4) = v1; }
;                     if (isq) { v0 = v0 * QSCALE; v1 = v1 * QSCALE; }
;                     else if (isg) {
; #pragma unroll
;                         for (int j = 0; j < 4; ++j) { v0[j] = v0[j] / (1.0f + __expf(-v0[j])); v1[j] = v1[j] / (1.0f + __expf(-v1[j])); }
;                     }
;                     *(u32x4*)(uo + n) = (u32x4){pk2(v0[0], v0[1]), pk2(v0[2], v0[3]), pk2(v1[0], v1[1]), pk2(v1[2], v1[3])};
;                 }
.Lp1q_nokv_2_0:
	s_cmp_eq_u32 s25, 2
	s_cbranch_scc1 .Lp1q_gate_2_0
	v_pk_mul_f32 v[62:63], v[62:63], s[22:23] op_sel_hi:[1,0]
	v_pk_mul_f32 v[64:65], v[64:65], s[22:23] op_sel_hi:[1,0]
	v_pk_mul_f32 v[58:59], v[58:59], s[22:23] op_sel_hi:[1,0]
	v_pk_mul_f32 v[60:61], v[60:61], s[22:23] op_sel_hi:[1,0]
	s_branch .Lp1q_cvt_2_0
.Lp1q_gate_2_0:
	v_mul_f32_e32 v194, 0xbfb8aa3b, v62
	v_exp_f32_e32 v194, v194
	s_nop 0
	v_add_f32_e32 v194, 1.0, v194
	v_div_scale_f32 v195, s[38:39], v194, v194, v62
	v_rcp_f32_e32 v196, v195
	s_nop 0
	v_fma_f32 v197, -v195, v196, 1.0
	v_fmac_f32_e32 v196, v197, v196
	v_div_scale_f32 v197, vcc, v62, v194, v62
	v_mul_f32_e32 v198, v197, v196
	v_fma_f32 v199, -v195, v198, v197
	v_fmac_f32_e32 v198, v199, v196
	v_fma_f32 v195, -v195, v198, v197
	v_div_fmas_f32 v195, v195, v196, v198
	v_div_fixup_f32 v62, v195, v194, v62
	v_mul_f32_e32 v194, 0xbfb8aa3b, v63
	v_exp_f32_e32 v194, v194
	s_nop 0
	v_add_f32_e32 v194, 1.0, v194
	v_div_scale_f32 v195, s[38:39], v194, v194, v63
	v_rcp_f32_e32 v196, v195
	s_nop 0
	v_fma_f32 v197, -v195, v196, 1.0
	v_fmac_f32_e32 v196, v197, v196
	v_div_scale_f32 v197, vcc, v63, v194, v63
	v_mul_f32_e32 v198, v197, v196
	v_fma_f32 v199, -v195, v198, v197
	v_fmac_f32_e32 v198, v199, v196
	v_fma_f32 v195, -v195, v198, v197
	v_div_fmas_f32 v195, v195, v196, v198
	v_div_fixup_f32 v63, v195, v194, v63
	v_mul_f32_e32 v194, 0xbfb8aa3b, v64
	v_exp_f32_e32 v194, v194
	s_nop 0
	v_add_f32_e32 v194, 1.0, v194
	v_div_scale_f32 v195, s[38:39], v194, v194, v64
	v_rcp_f32_e32 v196, v195
	s_nop 0
	v_fma_f32 v197, -v195, v196, 1.0
	v_fmac_f32_e32 v196, v197, v196
	v_div_scale_f32 v197, vcc, v64, v194, v64
	v_mul_f32_e32 v198, v197, v196
	v_fma_f32 v199, -v195, v198, v197
	v_fmac_f32_e32 v198, v199, v196
	v_fma_f32 v195, -v195, v198, v197
	v_div_fmas_f32 v195, v195, v196, v198
	v_div_fixup_f32 v64, v195, v194, v64
	v_mul_f32_e32 v194, 0xbfb8aa3b, v65
	v_exp_f32_e32 v194, v194
	s_nop 0
	v_add_f32_e32 v194, 1.0, v194
	v_div_scale_f32 v195, s[38:39], v194, v194, v65
	v_rcp_f32_e32 v196, v195
	s_nop 0
	v_fma_f32 v197, -v195, v196, 1.0
	v_fmac_f32_e32 v196, v197, v196
	v_div_scale_f32 v197, vcc, v65, v194, v65
	v_mul_f32_e32 v198, v197, v196
	v_fma_f32 v199, -v195, v198, v197
	v_fmac_f32_e32 v198, v199, v196
	v_fma_f32 v195, -v195, v198, v197
	v_div_fmas_f32 v195, v195, v196, v198
	v_div_fixup_f32 v65, v195, v194, v65
	v_mul_f32_e32 v194, 0xbfb8aa3b, v58
	v_exp_f32_e32 v194, v194
	s_nop 0
	v_add_f32_e32 v194, 1.0, v194
	v_div_scale_f32 v195, s[38:39], v194, v194, v58
	v_rcp_f32_e32 v196, v195
	s_nop 0
	v_fma_f32 v197, -v195, v196, 1.0
	v_fmac_f32_e32 v196, v197, v196
	v_div_scale_f32 v197, vcc, v58, v194, v58
	v_mul_f32_e32 v198, v197, v196
	v_fma_f32 v199, -v195, v198, v197
	v_fmac_f32_e32 v198, v199, v196
	v_fma_f32 v195, -v195, v198, v197
	v_div_fmas_f32 v195, v195, v196, v198
	v_div_fixup_f32 v58, v195, v194, v58
	v_mul_f32_e32 v194, 0xbfb8aa3b, v59
	v_exp_f32_e32 v194, v194
	s_nop 0
	v_add_f32_e32 v194, 1.0, v194
	v_div_scale_f32 v195, s[38:39], v194, v194, v59
	v_rcp_f32_e32 v196, v195
	s_nop 0
	v_fma_f32 v197, -v195, v196, 1.0
	v_fmac_f32_e32 v196, v197, v196
	v_div_scale_f32 v197, vcc, v59, v194, v59
	v_mul_f32_e32 v198, v197, v196
	v_fma_f32 v199, -v195, v198, v197
	v_fmac_f32_e32 v198, v199, v196
	v_fma_f32 v195, -v195, v198, v197
	v_div_fmas_f32 v195, v195, v196, v198
	v_div_fixup_f32 v59, v195, v194, v59
	v_mul_f32_e32 v194, 0xbfb8aa3b, v60
	v_exp_f32_e32 v194, v194
	s_nop 0
	v_add_f32_e32 v194, 1.0, v194
	v_div_scale_f32 v195, s[38:39], v194, v194, v60
	v_rcp_f32_e32 v196, v195
	s_nop 0
	v_fma_f32 v197, -v195, v196, 1.0
	v_fmac_f32_e32 v196, v197, v196
	v_div_scale_f32 v197, vcc, v60, v194, v60
	v_mul_f32_e32 v198, v197, v196
	v_fma_f32 v199, -v195, v198, v197
	v_fmac_f32_e32 v198, v199, v196
	v_fma_f32 v195, -v195, v198, v197
	v_div_fmas_f32 v195, v195, v196, v198
	v_div_fixup_f32 v60, v195, v194, v60
	v_mul_f32_e32 v194, 0xbfb8aa3b, v61
	v_exp_f32_e32 v194, v194
	s_nop 0
	v_add_f32_e32 v194, 1.0, v194
	v_div_scale_f32 v195, s[38:39], v194, v194, v61
	v_rcp_f32_e32 v196, v195
	s_nop 0
	v_fma_f32 v197, -v195, v196, 1.0
	v_fmac_f32_e32 v196, v197, v196
	v_div_scale_f32 v197, vcc, v61, v194, v61
	v_mul_f32_e32 v198, v197, v196
	v_fma_f32 v199, -v195, v198, v197
	v_fmac_f32_e32 v198, v199, v196
	v_fma_f32 v195, -v195, v198, v197
	v_div_fmas_f32 v195, v195, v196, v198
	v_div_fixup_f32 v61, v195, v194, v61
.Lp1q_cvt_2_0:
	v_cvt_pk_bf16_f32 v190, v62, v63
	v_cvt_pk_bf16_f32 v191, v64, v65
	v_cvt_pk_bf16_f32 v192, v58, v59
	v_cvt_pk_bf16_f32 v193, v60, v61
	global_store_dwordx4 v187, v[190:193], s[10:11]
	s_nop 1
	s_add_i32 s27, s1, 144
	s_lshl_b32 s7, s27, 13
	s_add_u32 s10, s68, s7
	s_addc_u32 s11, s69, 0
	s_cmp_lg_u32 s25, 1
	s_cbranch_scc1 .Lp1q_nokv_2_1
	s_cmp_ge_u32 s27, 0x4100
	s_cbranch_scc1 .Lp1q_smp_2_1
	s_mul_hi_u32 s7, s27, 0x7e07e07f
	s_lshr_b32 s7, s7, 11
	s_mul_i32 s8, s7, 0x1040
	s_sub_i32 s8, s27, s8
	s_cmp_ge_u32 s8, 0x1010
	s_cbranch_scc1 .Lp1q_kvdone_2_1
	s_mul_i32 s7, s7, 0x1010
	s_add_i32 s7, s7, s8
	s_lshl_b32 s7, s7, 11
	s_add_u32 s8, s34, s7
	s_addc_u32 s9, s35, 0
	s_branch .Lp1q_kvst_2_1

;     DI void operator()(const f32x4 (&acc)[2][2][4][2], const pg8::Unit& u, int wr, int wc, int fr, int fq) const {
;     ...
;                     if (R < ROWS_P) { const int b = R / LPAD, t = R - b * LPAD; if (t < LP) fo = p.out + O_PAK + oi * PKV_SZ + ((size_t)b * LP + t) * 512 - seg * 512; }
;                     else fo = p.out + O_SAK + oi * SKV_SZ + (size_t)(R - ROWS_P) * 512 - seg * 512;
;                 }
;                 bf16_t* uo = p.u + (size_t)R * NU;
; #pragma unroll
;                 for (int bj = 0; bj < 2; ++bj) {
;                     const int n = colt + bj * 128 + wc * 32 + 8 * fq;
;                     f32x4 v0 = acc[ai][bj][m][0], v1 = acc[ai][bj][m][1];
;                     if (fo) { *(f32x4*)(fo + n) = v0; *(f32x4*)(fo + n + 4) = v1; }
.Lp1q_kvst_2_1:
	global_store_dwordx4 v188, v[46:49], s[8:9]
	global_store_dwordx4 v188, v[42:45], s[8:9] offset:16

; DI unsigned pk2(float a, float b) { f32x2 v = {a, b}; bf16x2v r = __builtin_convertvector(v, bf16x2v); return __builtin_bit_cast(unsigned, r); }
;     DI void operator()(const f32x4 (&acc)[2][2][4][2], const pg8::Unit& u, int wr, int wc, int fr, int fq) const {
;     ...
;                 const int R = u.pm * 256 + ai * 128 + wr * 64 + m * 16 + fr;
;                 float* fo = nullptr;
;                 if (iskv) {
;                     if (R < ROWS_P) { const int b = R / LPAD, t = R - b * LPAD; if (t < LP) fo = p.out + O_PAK + oi * PKV_SZ + ((size_t)b * LP + t) * 512 - seg * 512; }
;                     else fo = p.out + O_SAK + oi * SKV_SZ + (size_t)(R - ROWS_P) * 512 - seg * 512;
;                 }
;                 bf16_t* uo = p.u + (size_t)R * NU;
; #pragma unroll
;                 for (int bj = 0; bj < 2; ++bj) {
;                     const int n = colt + bj * 128 + wc * 32 + 8 * fq;
;                     f32x4 v0 = acc[ai][bj][m][0], v1 = acc[ai][bj][m][1];
;                     if (fo) { *(f32x4*)(fo + n) = v0; *(f32x4*)(fo + n + 4) = v1; }
;                     if (isq) { v0 = v0 * QSCALE; v1 = v1 * QSCALE; }
;                     else if (isg) {
; #pragma unroll
;                         for (int j = 0; j < 4; ++j) { v0[j] = v0[j] / (1.0f + __expf(-v0[j])); v1[j] = v1[j] / (1.0f + __expf(-v1[j])); }
;                     }
;                     *(u32x4*)(uo + n) = (u32x4){pk2(v0[0], v0[1]), pk2(v0[2], v0[3]), pk2(v1[0], v1[1]), pk2(v1[2], v1[3])};
;                 }
.Lp1q_nokv_2_1:
	s_cmp_eq_u32 s25, 2
	s_cbranch_scc1 .Lp1q_gate_2_1
	v_pk_mul_f32 v[46:47], v[46:47], s[22:23] op_sel_hi:[1,0]
	v_pk_mul_f32 v[48:49], v[48:49], s[22:23] op_sel_hi:[1,0]
	v_pk_mul_f32 v[42:43], v[42:43], s[22:23] op_sel_hi:[1,0]
	v_pk_mul_f32 v[44:45], v[44:45], s[22:23] op_sel_hi:[1,0]
	s_branch .Lp1q_cvt_2_1
.Lp1q_gate_2_1:
	v_mul_f32_e32 v194, 0xbfb8aa3b, v46
	v_exp_f32_e32 v194, v194
	s_nop 0
	v_add_f32_e32 v194, 1.0, v194
	v_div_scale_f32 v195, s[38:39], v194, v194, v46
	v_rcp_f32_e32 v196, v195
	s_nop 0
	v_fma_f32 v197, -v195, v196, 1.0
	v_fmac_f32_e32 v196, v197, v196
	v_div_scale_f32 v197, vcc, v46, v194, v46
	v_mul_f32_e32 v198, v197, v196
	v_fma_f32 v199, -v195, v198, v197
	v_fmac_f32_e32 v198, v199, v196
	v_fma_f32 v195, -v195, v198, v197
	v_div_fmas_f32 v195, v195, v196, v198
	v_div_fixup_f32 v46, v195, v194, v46
	v_mul_f32_e32 v194, 0xbfb8aa3b, v47
	v_exp_f32_e32 v194, v194
	s_nop 0
	v_add_f32_e32 v194, 1.0, v194
	v_div_scale_f32 v195, s[38:39], v194, v194, v47
	v_rcp_f32_e32 v196, v195
	s_nop 0
	v_fma_f32 v197, -v195, v196, 1.0
	v_fmac_f32_e32 v196, v197, v196
	v_div_scale_f32 v197, vcc, v47, v194, v47
	v_mul_f32_e32 v198, v197, v196
	v_fma_f32 v199, -v195, v198, v197
	v_fmac_f32_e32 v198, v199, v196
	v_fma_f32 v195, -v195, v198, v197
	v_div_fmas_f32 v195, v195, v196, v198
	v_div_fixup_f32 v47, v195, v194, v47
	v_mul_f32_e32 v194, 0xbfb8aa3b, v48
	v_exp_f32_e32 v194, v194
	s_nop 0
	v_add_f32_e32 v194, 1.0, v194
	v_div_scale_f32 v195, s[38:39], v194, v194, v48
	v_rcp_f32_e32 v196, v195
	s_nop 0
	v_fma_f32 v197, -v195, v196, 1.0
	v_fmac_f32_e32 v196, v197, v196
	v_div_scale_f32 v197, vcc, v48, v194, v48
	v_mul_f32_e32 v198, v197, v196
	v_fma_f32 v199, -v195, v198, v197
	v_fmac_f32_e32 v198, v199, v196
	v_fma_f32 v195, -v195, v198, v197
	v_div_fmas_f32 v195, v195, v196, v198
	v_div_fixup_f32 v48, v195, v194, v48
	v_mul_f32_e32 v194, 0xbfb8aa3b, v49
	v_exp_f32_e32 v194, v194
	s_nop 0
	v_add_f32_e32 v194, 1.0, v194
	v_div_scale_f32 v195, s[38:39], v194, v194, v49
	v_rcp_f32_e32 v196, v195
	s_nop 0
	v_fma_f32 v197, -v195, v196, 1.0
	v_fmac_f32_e32 v196, v197, v196
	v_div_scale_f32 v197, vcc, v49, v194, v49
	v_mul_f32_e32 v198, v197, v196
	v_fma_f32 v199, -v195, v198, v197
	v_fmac_f32_e32 v198, v199, v196
	v_fma_f32 v195, -v195, v198, v197
	v_div_fmas_f32 v195, v195, v196, v198
	v_div_fixup_f32 v49, v195, v194, v49
	v_mul_f32_e32 v194, 0xbfb8aa3b, v42
	v_exp_f32_e32 v194, v194
	s_nop 0
	v_add_f32_e32 v194, 1.0, v194
	v_div_scale_f32 v195, s[38:39], v194, v194, v42
	v_rcp_f32_e32 v196, v195
	s_nop 0
	v_fma_f32 v197, -v195, v196, 1.0
	v_fmac_f32_e32 v196, v197, v196
	v_div_scale_f32 v197, vcc, v42, v194, v42
	v_mul_f32_e32 v198, v197, v196
	v_fma_f32 v199, -v195, v198, v197
	v_fmac_f32_e32 v198, v199, v196
	v_fma_f32 v195, -v195, v198, v197
	v_div_fmas_f32 v195, v195, v196, v198
	v_div_fixup_f32 v42, v195, v194, v42
	v_mul_f32_e32 v194, 0xbfb8aa3b, v43
	v_exp_f32_e32 v194, v194
	s_nop 0
	v_add_f32_e32 v194, 1.0, v194
	v_div_scale_f32 v195, s[38:39], v194, v194, v43
	v_rcp_f32_e32 v196, v195
	s_nop 0
	v_fma_f32 v197, -v195, v196, 1.0
	v_fmac_f32_e32 v196, v197, v196
	v_div_scale_f32 v197, vcc, v43, v194, v43
	v_mul_f32_e32 v198, v197, v196
	v_fma_f32 v199, -v195, v198, v197
	v_fmac_f32_e32 v198, v199, v196
	v_fma_f32 v195, -v195, v198, v197
	v_div_fmas_f32 v195, v195, v196, v198
	v_div_fixup_f32 v43, v195, v194, v43
	v_mul_f32_e32 v194, 0xbfb8aa3b, v44
	v_exp_f32_e32 v194, v194
	s_nop 0
	v_add_f32_e32 v194, 1.0, v194
	v_div_scale_f32 v195, s[38:39], v194, v194, v44
	v_rcp_f32_e32 v196, v195
	s_nop 0
	v_fma_f32 v197, -v195, v196, 1.0
	v_fmac_f32_e32 v196, v197, v196
	v_div_scale_f32 v197, vcc, v44, v194, v44
	v_mul_f32_e32 v198, v197, v196
	v_fma_f32 v199, -v195, v198, v197
	v_fmac_f32_e32 v198, v199, v196
	v_fma_f32 v195, -v195, v198, v197
	v_div_fmas_f32 v195, v195, v196, v198
	v_div_fixup_f32 v44, v195, v194, v44
	v_mul_f32_e32 v194, 0xbfb8aa3b, v45
	v_exp_f32_e32 v194, v194
	s_nop 0
	v_add_f32_e32 v194, 1.0, v194
	v_div_scale_f32 v195, s[38:39], v194, v194, v45
	v_rcp_f32_e32 v196, v195
	s_nop 0
	v_fma_f32 v197, -v195, v196, 1.0
	v_fmac_f32_e32 v196, v197, v196
	v_div_scale_f32 v197, vcc, v45, v194, v45
	v_mul_f32_e32 v198, v197, v196
	v_fma_f32 v199, -v195, v198, v197
	v_fmac_f32_e32 v198, v199, v196
	v_fma_f32 v195, -v195, v198, v197
	v_div_fmas_f32 v195, v195, v196, v198
	v_div_fixup_f32 v45, v195, v194, v45
.Lp1q_cvt_2_1:
	v_cvt_pk_bf16_f32 v190, v46, v47
	v_cvt_pk_bf16_f32 v191, v48, v49
	v_cvt_pk_bf16_f32 v192, v42, v43
	v_cvt_pk_bf16_f32 v193, v44, v45
	global_store_dwordx4 v187, v[190:193], s[10:11]
	s_nop 1
	s_add_i32 s27, s1, 160
	s_lshl_b32 s7, s27, 13
	s_add_u32 s10, s68, s7
	s_addc_u32 s11, s69, 0
	s_cmp_lg_u32 s25, 1
	s_cbranch_scc1 .Lp1q_nokv_2_2
	s_cmp_ge_u32 s27, 0x4100
	s_cbranch_scc1 .Lp1q_smp_2_2
	s_mul_hi_u32 s7, s27, 0x7e07e07f
	s_lshr_b32 s7, s7, 11
	s_mul_i32 s8, s7, 0x1040
	s_sub_i32 s8, s27, s8
	s_cmp_ge_u32 s8, 0x1010
	s_cbranch_scc1 .Lp1q_kvdone_2_2
	s_mul_i32 s7, s7, 0x1010
	s_add_i32 s7, s7, s8
	s_lshl_b32 s7, s7, 11
	s_add_u32 s8, s34, s7
	s_addc_u32 s9, s35, 0
	s_branch .Lp1q_kvst_2_2

;     DI void operator()(const f32x4 (&acc)[2][2][4][2], const pg8::Unit& u, int wr, int wc, int fr, int fq) const {
;     ...
;                     if (R < ROWS_P) { const int b = R / LPAD, t = R - b * LPAD; if (t < LP) fo = p.out + O_PAK + oi * PKV_SZ + ((size_t)b * LP + t) * 512 - seg * 512; }
;                     else fo = p.out + O_SAK + oi * SKV_SZ + (size_t)(R - ROWS_P) * 512 - seg * 512;
;                 }
;                 bf16_t* uo = p.u + (size_t)R * NU;
; #pragma unroll
;                 for (int bj = 0; bj < 2; ++bj) {
;                     const int n = colt + bj * 128 + wc * 32 + 8 * fq;
;                     f32x4 v0 = acc[ai][bj][m][0], v1 = acc[ai][bj][m][1];
;                     if (fo) { *(f32x4*)(fo + n) = v0; *(f32x4*)(fo + n + 4) = v1; }
.Lp1q_kvst_2_2:
	global_store_dwordx4 v188, v[30:33], s[8:9]
	global_store_dwordx4 v188, v[26:29], s[8:9] offset:16

; DI unsigned pk2(float a, float b) { f32x2 v = {a, b}; bf16x2v r = __builtin_convertvector(v, bf16x2v); return __builtin_bit_cast(unsigned, r); }
;     DI void operator()(const f32x4 (&acc)[2][2][4][2], const pg8::Unit& u, int wr, int wc, int fr, int fq) const {
;     ...
;                 const int R = u.pm * 256 + ai * 128 + wr * 64 + m * 16 + fr;
;                 float* fo = nullptr;
;                 if (iskv) {
;                     if (R < ROWS_P) { const int b = R / LPAD, t = R - b * LPAD; if (t < LP) fo = p.out + O_PAK + oi * PKV_SZ + ((size_t)b * LP + t) * 512 - seg * 512; }
;                     else fo = p.out + O_SAK + oi * SKV_SZ + (size_t)(R - ROWS_P) * 512 - seg * 512;
;                 }
;                 bf16_t* uo = p.u + (size_t)R * NU;
; #pragma unroll
;                 for (int bj = 0; bj < 2; ++bj) {
;                     const int n = colt + bj * 128 + wc * 32 + 8 * fq;
;                     f32x4 v0 = acc[ai][bj][m][0], v1 = acc[ai][bj][m][1];
;                     if (fo) { *(f32x4*)(fo + n) = v0; *(f32x4*)(fo + n + 4) = v1; }
;                     if (isq) { v0 = v0 * QSCALE; v1 = v1 * QSCALE; }
;                     else if (isg) {
; #pragma unroll
;                         for (int j = 0; j < 4; ++j) { v0[j] = v0[j] / (1.0f + __expf(-v0[j])); v1[j] = v1[j] / (1.0f + __expf(-v1[j])); }
;                     }
;                     *(u32x4*)(uo + n) = (u32x4){pk2(v0[0], v0[1]), pk2(v0[2], v0[3]), pk2(v1[0], v1[1]), pk2(v1[2], v1[3])};
;                 }
.Lp1q_nokv_2_2:
	s_cmp_eq_u32 s25, 2
	s_cbranch_scc1 .Lp1q_gate_2_2
	v_pk_mul_f32 v[30:31], v[30:31], s[22:23] op_sel_hi:[1,0]
	v_pk_mul_f32 v[32:33], v[32:33], s[22:23] op_sel_hi:[1,0]
	v_pk_mul_f32 v[26:27], v[26:27], s[22:23] op_sel_hi:[1,0]
	v_pk_mul_f32 v[28:29], v[28:29], s[22:23] op_sel_hi:[1,0]
	s_branch .Lp1q_cvt_2_2
.Lp1q_gate_2_2:
	v_mul_f32_e32 v194, 0xbfb8aa3b, v30
	v_exp_f32_e32 v194, v194
	s_nop 0
	v_add_f32_e32 v194, 1.0, v194
	v_div_scale_f32 v195, s[38:39], v194, v194, v30
	v_rcp_f32_e32 v196, v195
	s_nop 0
	v_fma_f32 v197, -v195, v196, 1.0
	v_fmac_f32_e32 v196, v197, v196
	v_div_scale_f32 v197, vcc, v30, v194, v30
	v_mul_f32_e32 v198, v197, v196
	v_fma_f32 v199, -v195, v198, v197
	v_fmac_f32_e32 v198, v199, v196
	v_fma_f32 v195, -v195, v198, v197
	v_div_fmas_f32 v195, v195, v196, v198
	v_div_fixup_f32 v30, v195, v194, v30
	v_mul_f32_e32 v194, 0xbfb8aa3b, v31
	v_exp_f32_e32 v194, v194
	s_nop 0
	v_add_f32_e32 v194, 1.0, v194
	v_div_scale_f32 v195, s[38:39], v194, v194, v31
	v_rcp_f32_e32 v196, v195
	s_nop 0
	v_fma_f32 v197, -v195, v196, 1.0
	v_fmac_f32_e32 v196, v197, v196
	v_div_scale_f32 v197, vcc, v31, v194, v31
	v_mul_f32_e32 v198, v197, v196
	v_fma_f32 v199, -v195, v198, v197
	v_fmac_f32_e32 v198, v199, v196
	v_fma_f32 v195, -v195, v198, v197
	v_div_fmas_f32 v195, v195, v196, v198
	v_div_fixup_f32 v31, v195, v194, v31
	v_mul_f32_e32 v194, 0xbfb8aa3b, v32
	v_exp_f32_e32 v194, v194
	s_nop 0
	v_add_f32_e32 v194, 1.0, v194
	v_div_scale_f32 v195, s[38:39], v194, v194, v32
	v_rcp_f32_e32 v196, v195
	s_nop 0
	v_fma_f32 v197, -v195, v196, 1.0
	v_fmac_f32_e32 v196, v197, v196
	v_div_scale_f32 v197, vcc, v32, v194, v32
	v_mul_f32_e32 v198, v197, v196
	v_fma_f32 v199, -v195, v198, v197
	v_fmac_f32_e32 v198, v199, v196
	v_fma_f32 v195, -v195, v198, v197
	v_div_fmas_f32 v195, v195, v196, v198
	v_div_fixup_f32 v32, v195, v194, v32
	v_mul_f32_e32 v194, 0xbfb8aa3b, v33
	v_exp_f32_e32 v194, v194
	s_nop 0
	v_add_f32_e32 v194, 1.0, v194
	v_div_scale_f32 v195, s[38:39], v194, v194, v33
	v_rcp_f32_e32 v196, v195
	s_nop 0
	v_fma_f32 v197, -v195, v196, 1.0
	v_fmac_f32_e32 v196, v197, v196
	v_div_scale_f32 v197, vcc, v33, v194, v33
	v_mul_f32_e32 v198, v197, v196
	v_fma_f32 v199, -v195, v198, v197
	v_fmac_f32_e32 v198, v199, v196
	v_fma_f32 v195, -v195, v198, v197
	v_div_fmas_f32 v195, v195, v196, v198
	v_div_fixup_f32 v33, v195, v194, v33
	v_mul_f32_e32 v194, 0xbfb8aa3b, v26
	v_exp_f32_e32 v194, v194
	s_nop 0
	v_add_f32_e32 v194, 1.0, v194
	v_div_scale_f32 v195, s[38:39], v194, v194, v26
	v_rcp_f32_e32 v196, v195
	s_nop 0
	v_fma_f32 v197, -v195, v196, 1.0
	v_fmac_f32_e32 v196, v197, v196
	v_div_scale_f32 v197, vcc, v26, v194, v26
	v_mul_f32_e32 v198, v197, v196
	v_fma_f32 v199, -v195, v198, v197
	v_fmac_f32_e32 v198, v199, v196
	v_fma_f32 v195, -v195, v198, v197
	v_div_fmas_f32 v195, v195, v196, v198
	v_div_fixup_f32 v26, v195, v194, v26
	v_mul_f32_e32 v194, 0xbfb8aa3b, v27
	v_exp_f32_e32 v194, v194
	s_nop 0
	v_add_f32_e32 v194, 1.0, v194
	v_div_scale_f32 v195, s[38:39], v194, v194, v27
	v_rcp_f32_e32 v196, v195
	s_nop 0
	v_fma_f32 v197, -v195, v196, 1.0
	v_fmac_f32_e32 v196, v197, v196
	v_div_scale_f32 v197, vcc, v27, v194, v27
	v_mul_f32_e32 v198, v197, v196
	v_fma_f32 v199, -v195, v198, v197
	v_fmac_f32_e32 v198, v199, v196
	v_fma_f32 v195, -v195, v198, v197
	v_div_fmas_f32 v195, v195, v196, v198
	v_div_fixup_f32 v27, v195, v194, v27
	v_mul_f32_e32 v194, 0xbfb8aa3b, v28
	v_exp_f32_e32 v194, v194
	s_nop 0
	v_add_f32_e32 v194, 1.0, v194
	v_div_scale_f32 v195, s[38:39], v194, v194, v28
	v_rcp_f32_e32 v196, v195
	s_nop 0
	v_fma_f32 v197, -v195, v196, 1.0
	v_fmac_f32_e32 v196, v197, v196
	v_div_scale_f32 v197, vcc, v28, v194, v28
	v_mul_f32_e32 v198, v197, v196
	v_fma_f32 v199, -v195, v198, v197
	v_fmac_f32_e32 v198, v199, v196
	v_fma_f32 v195, -v195, v198, v197
	v_div_fmas_f32 v195, v195, v196, v198
	v_div_fixup_f32 v28, v195, v194, v28
	v_mul_f32_e32 v194, 0xbfb8aa3b, v29
	v_exp_f32_e32 v194, v194
	s_nop 0
	v_add_f32_e32 v194, 1.0, v194
	v_div_scale_f32 v195, s[38:39], v194, v194, v29
	v_rcp_f32_e32 v196, v195
	s_nop 0
	v_fma_f32 v197, -v195, v196, 1.0
	v_fmac_f32_e32 v196, v197, v196
	v_div_scale_f32 v197, vcc, v29, v194, v29
	v_mul_f32_e32 v198, v197, v196
	v_fma_f32 v199, -v195, v198, v197
	v_fmac_f32_e32 v198, v199, v196
	v_fma_f32 v195, -v195, v198, v197
	v_div_fmas_f32 v195, v195, v196, v198
	v_div_fixup_f32 v29, v195, v194, v29
.Lp1q_cvt_2_2:
	v_cvt_pk_bf16_f32 v190, v30, v31
	v_cvt_pk_bf16_f32 v191, v32, v33
	v_cvt_pk_bf16_f32 v192, v26, v27
	v_cvt_pk_bf16_f32 v193, v28, v29
	global_store_dwordx4 v187, v[190:193], s[10:11]
	s_nop 1
	s_add_i32 s27, s1, 176
	s_lshl_b32 s7, s27, 13
	s_add_u32 s10, s68, s7
	s_addc_u32 s11, s69, 0
	s_cmp_lg_u32 s25, 1
	s_cbranch_scc1 .Lp1q_nokv_2_3
	s_cmp_ge_u32 s27, 0x4100
	s_cbranch_scc1 .Lp1q_smp_2_3
	s_mul_hi_u32 s7, s27, 0x7e07e07f
	s_lshr_b32 s7, s7, 11
	s_mul_i32 s8, s7, 0x1040
	s_sub_i32 s8, s27, s8
	s_cmp_ge_u32 s8, 0x1010
	s_cbranch_scc1 .Lp1q_kvdone_2_3
	s_mul_i32 s7, s7, 0x1010
	s_add_i32 s7, s7, s8
	s_lshl_b32 s7, s7, 11
	s_add_u32 s8, s34, s7
	s_addc_u32 s9, s35, 0
	s_branch .Lp1q_kvst_2_3

;     DI void operator()(const f32x4 (&acc)[2][2][4][2], const pg8::Unit& u, int wr, int wc, int fr, int fq) const {
;     ...
;                     if (R < ROWS_P) { const int b = R / LPAD, t = R - b * LPAD; if (t < LP) fo = p.out + O_PAK + oi * PKV_SZ + ((size_t)b * LP + t) * 512 - seg * 512; }
;                     else fo = p.out + O_SAK + oi * SKV_SZ + (size_t)(R - ROWS_P) * 512 - seg * 512;
;                 }
;                 bf16_t* uo = p.u + (size_t)R * NU;
; #pragma unroll
;                 for (int bj = 0; bj < 2; ++bj) {
;                     const int n = colt + bj * 128 + wc * 32 + 8 * fq;
;                     f32x4 v0 = acc[ai][bj][m][0], v1 = acc[ai][bj][m][1];
;                     if (fo) { *(f32x4*)(fo + n) = v0; *(f32x4*)(fo + n + 4) = v1; }
.Lp1q_kvst_2_3:
	global_store_dwordx4 v188, v[14:17], s[8:9]
	global_store_dwordx4 v188, v[10:13], s[8:9] offset:16

; DI unsigned pk2(float a, float b) { f32x2 v = {a, b}; bf16x2v r = __builtin_convertvector(v, bf16x2v); return __builtin_bit_cast(unsigned, r); }
;     DI void operator()(const f32x4 (&acc)[2][2][4][2], const pg8::Unit& u, int wr, int wc, int fr, int fq) const {
;     ...
;                     if (isq) { v0 = v0 * QSCALE; v1 = v1 * QSCALE; }
;                     else if (isg) {
; #pragma unroll
;                         for (int j = 0; j < 4; ++j) { v0[j] = v0[j] / (1.0f + __expf(-v0[j])); v1[j] = v1[j] / (1.0f + __expf(-v1[j])); }
;                     }
;                     *(u32x4*)(uo + n) = (u32x4){pk2(v0[0], v0[1]), pk2(v0[2], v0[3]), pk2(v1[0], v1[1]), pk2(v1[2], v1[3])};
;                 }
.Lp1q_nokv_2_3:
	s_cmp_eq_u32 s25, 2
	s_cbranch_scc1 .Lp1q_gate_2_3
	v_pk_mul_f32 v[14:15], v[14:15], s[22:23] op_sel_hi:[1,0]
	v_pk_mul_f32 v[16:17], v[16:17], s[22:23] op_sel_hi:[1,0]
	v_pk_mul_f32 v[10:11], v[10:11], s[22:23] op_sel_hi:[1,0]
	v_pk_mul_f32 v[12:13], v[12:13], s[22:23] op_sel_hi:[1,0]
	s_branch .Lp1q_cvt_2_3
.Lp1q_gate_2_3:
	v_mul_f32_e32 v194, 0xbfb8aa3b, v14
	v_exp_f32_e32 v194, v194
	s_nop 0
	v_add_f32_e32 v194, 1.0, v194
	v_div_scale_f32 v195, s[38:39], v194, v194, v14
	v_rcp_f32_e32 v196, v195
	s_nop 0
	v_fma_f32 v197, -v195, v196, 1.0
	v_fmac_f32_e32 v196, v197, v196
	v_div_scale_f32 v197, vcc, v14, v194, v14
	v_mul_f32_e32 v198, v197, v196
	v_fma_f32 v199, -v195, v198, v197
	v_fmac_f32_e32 v198, v199, v196
	v_fma_f32 v195, -v195, v198, v197
	v_div_fmas_f32 v195, v195, v196, v198
	v_div_fixup_f32 v14, v195, v194, v14
	v_mul_f32_e32 v194, 0xbfb8aa3b, v15
	v_exp_f32_e32 v194, v194
	s_nop 0
	v_add_f32_e32 v194, 1.0, v194
	v_div_scale_f32 v195, s[38:39], v194, v194, v15
	v_rcp_f32_e32 v196, v195
	s_nop 0
	v_fma_f32 v197, -v195, v196, 1.0
	v_fmac_f32_e32 v196, v197, v196
	v_div_scale_f32 v197, vcc, v15, v194, v15
	v_mul_f32_e32 v198, v197, v196
	v_fma_f32 v199, -v195, v198, v197
	v_fmac_f32_e32 v198, v199, v196
	v_fma_f32 v195, -v195, v198, v197
	v_div_fmas_f32 v195, v195, v196, v198
	v_div_fixup_f32 v15, v195, v194, v15
	v_mul_f32_e32 v194, 0xbfb8aa3b, v16
	v_exp_f32_e32 v194, v194
	s_nop 0
	v_add_f32_e32 v194, 1.0, v194
	v_div_scale_f32 v195, s[38:39], v194, v194, v16
	v_rcp_f32_e32 v196, v195
	s_nop 0
	v_fma_f32 v197, -v195, v196, 1.0
	v_fmac_f32_e32 v196, v197, v196
	v_div_scale_f32 v197, vcc, v16, v194, v16
	v_mul_f32_e32 v198, v197, v196
	v_fma_f32 v199, -v195, v198, v197
	v_fmac_f32_e32 v198, v199, v196
	v_fma_f32 v195, -v195, v198, v197
	v_div_fmas_f32 v195, v195, v196, v198
	v_div_fixup_f32 v16, v195, v194, v16
	v_mul_f32_e32 v194, 0xbfb8aa3b, v17
	v_exp_f32_e32 v194, v194
	s_nop 0
	v_add_f32_e32 v194, 1.0, v194
	v_div_scale_f32 v195, s[38:39], v194, v194, v17
	v_rcp_f32_e32 v196, v195
	s_nop 0
	v_fma_f32 v197, -v195, v196, 1.0
	v_fmac_f32_e32 v196, v197, v196
	v_div_scale_f32 v197, vcc, v17, v194, v17
	v_mul_f32_e32 v198, v197, v196
	v_fma_f32 v199, -v195, v198, v197
	v_fmac_f32_e32 v198, v199, v196
	v_fma_f32 v195, -v195, v198, v197
	v_div_fmas_f32 v195, v195, v196, v198
	v_div_fixup_f32 v17, v195, v194, v17
	v_mul_f32_e32 v194, 0xbfb8aa3b, v10
	v_exp_f32_e32 v194, v194
	s_nop 0
	v_add_f32_e32 v194, 1.0, v194
	v_div_scale_f32 v195, s[38:39], v194, v194, v10
	v_rcp_f32_e32 v196, v195
	s_nop 0
	v_fma_f32 v197, -v195, v196, 1.0
	v_fmac_f32_e32 v196, v197, v196
	v_div_scale_f32 v197, vcc, v10, v194, v10
	v_mul_f32_e32 v198, v197, v196
	v_fma_f32 v199, -v195, v198, v197
	v_fmac_f32_e32 v198, v199, v196
	v_fma_f32 v195, -v195, v198, v197
	v_div_fmas_f32 v195, v195, v196, v198
	v_div_fixup_f32 v10, v195, v194, v10
	v_mul_f32_e32 v194, 0xbfb8aa3b, v11
	v_exp_f32_e32 v194, v194
	s_nop 0
	v_add_f32_e32 v194, 1.0, v194
	v_div_scale_f32 v195, s[38:39], v194, v194, v11
	v_rcp_f32_e32 v196, v195
	s_nop 0
	v_fma_f32 v197, -v195, v196, 1.0
	v_fmac_f32_e32 v196, v197, v196
	v_div_scale_f32 v197, vcc, v11, v194, v11
	v_mul_f32_e32 v198, v197, v196
	v_fma_f32 v199, -v195, v198, v197
	v_fmac_f32_e32 v198, v199, v196
	v_fma_f32 v195, -v195, v198, v197
	v_div_fmas_f32 v195, v195, v196, v198
	v_div_fixup_f32 v11, v195, v194, v11
	v_mul_f32_e32 v194, 0xbfb8aa3b, v12
	v_exp_f32_e32 v194, v194
	s_nop 0
	v_add_f32_e32 v194, 1.0, v194
	v_div_scale_f32 v195, s[38:39], v194, v194, v12
	v_rcp_f32_e32 v196, v195
	s_nop 0
	v_fma_f32 v197, -v195, v196, 1.0
	v_fmac_f32_e32 v196, v197, v196
	v_div_scale_f32 v197, vcc, v12, v194, v12
	v_mul_f32_e32 v198, v197, v196
	v_fma_f32 v199, -v195, v198, v197
	v_fmac_f32_e32 v198, v199, v196
	v_fma_f32 v195, -v195, v198, v197
	v_div_fmas_f32 v195, v195, v196, v198
	v_div_fixup_f32 v12, v195, v194, v12
	v_mul_f32_e32 v194, 0xbfb8aa3b, v13
	v_exp_f32_e32 v194, v194
	s_nop 0
	v_add_f32_e32 v194, 1.0, v194
	v_div_scale_f32 v195, s[38:39], v194, v194, v13
	v_rcp_f32_e32 v196, v195
	s_nop 0
	v_fma_f32 v197, -v195, v196, 1.0
	v_fmac_f32_e32 v196, v197, v196
	v_div_scale_f32 v197, vcc, v13, v194, v13
	v_mul_f32_e32 v198, v197, v196
	v_fma_f32 v199, -v195, v198, v197
	v_fmac_f32_e32 v198, v199, v196
	v_fma_f32 v195, -v195, v198, v197
	v_div_fmas_f32 v195, v195, v196, v198
	v_div_fixup_f32 v13, v195, v194, v13
.Lp1q_cvt_2_3:
	v_cvt_pk_bf16_f32 v190, v14, v15
	v_cvt_pk_bf16_f32 v191, v16, v17
	v_cvt_pk_bf16_f32 v192, v10, v11
	v_cvt_pk_bf16_f32 v193, v12, v13
	global_store_dwordx4 v187, v[190:193], s[10:11]
	s_nop 1
	s_branch .Lp1q_tail

;     DI void operator()(const f32x4 (&acc)[2][2][4][2], const pg8::Unit& u, int wr, int wc, int fr, int fq) const {
;     ...
;                     if (R < ROWS_P) { const int b = R / LPAD, t = R - b * LPAD; if (t < LP) fo = p.out + O_PAK + oi * PKV_SZ + ((size_t)b * LP + t) * 512 - seg * 512; }
;                     else fo = p.out + O_SAK + oi * SKV_SZ + (size_t)(R - ROWS_P) * 512 - seg * 512;
;                 }
;                 bf16_t* uo = p.u + (size_t)R * NU;
; #pragma unroll
;                 for (int bj = 0; bj < 2; ++bj) {
;                     const int n = colt + bj * 128 + wc * 32 + 8 * fq;
;                     f32x4 v0 = acc[ai][bj][m][0], v1 = acc[ai][bj][m][1];
;                     if (fo) { *(f32x4*)(fo + n) = v0; *(f32x4*)(fo + n + 4) = v1; }
.Lp1q_kvst_3_0:
	global_store_dwordx4 v188, v[54:57], s[8:9] offset:512
	global_store_dwordx4 v188, v[50:53], s[8:9] offset:528

; DI unsigned pk2(float a, float b) { f32x2 v = {a, b}; bf16x2v r = __builtin_convertvector(v, bf16x2v); return __builtin_bit_cast(unsigned, r); }
;     DI void operator()(const f32x4 (&acc)[2][2][4][2], const pg8::Unit& u, int wr, int wc, int fr, int fq) const {
;     ...
;                 const int R = u.pm * 256 + ai * 128 + wr * 64 + m * 16 + fr;
;                 float* fo = nullptr;
;                 if (iskv) {
;                     if (R < ROWS_P) { const int b = R / LPAD, t = R - b * LPAD; if (t < LP) fo = p.out + O_PAK + oi * PKV_SZ + ((size_t)b * LP + t) * 512 - seg * 512; }
;                     else fo = p.out + O_SAK + oi * SKV_SZ + (size_t)(R - ROWS_P) * 512 - seg * 512;
;                 }
;                 bf16_t* uo = p.u + (size_t)R * NU;
; #pragma unroll
;                 for (int bj = 0; bj < 2; ++bj) {
;                     const int n = colt + bj * 128 + wc * 32 + 8 * fq;
;                     f32x4 v0 = acc[ai][bj][m][0], v1 = acc[ai][bj][m][1];
;                     if (fo) { *(f32x4*)(fo + n) = v0; *(f32x4*)(fo + n + 4) = v1; }
;                     if (isq) { v0 = v0 * QSCALE; v1 = v1 * QSCALE; }
;                     else if (isg) {
; #pragma unroll
;                         for (int j = 0; j < 4; ++j) { v0[j] = v0[j] / (1.0f + __expf(-v0[j])); v1[j] = v1[j] / (1.0f + __expf(-v1[j])); }
;                     }
;                     *(u32x4*)(uo + n) = (u32x4){pk2(v0[0], v0[1]), pk2(v0[2], v0[3]), pk2(v1[0], v1[1]), pk2(v1[2], v1[3])};
;                 }
.Lp1q_nokv_3_0:
	s_cmp_eq_u32 s25, 2
	s_cbranch_scc1 .Lp1q_gate_3_0
	v_pk_mul_f32 v[54:55], v[54:55], s[22:23] op_sel_hi:[1,0]
	v_pk_mul_f32 v[56:57], v[56:57], s[22:23] op_sel_hi:[1,0]
	v_pk_mul_f32 v[50:51], v[50:51], s[22:23] op_sel_hi:[1,0]
	v_pk_mul_f32 v[52:53], v[52:53], s[22:23] op_sel_hi:[1,0]
	s_branch .Lp1q_cvt_3_0
.Lp1q_gate_3_0:
	v_mul_f32_e32 v194, 0xbfb8aa3b, v54
	v_exp_f32_e32 v194, v194
	s_nop 0
	v_add_f32_e32 v194, 1.0, v194
	v_div_scale_f32 v195, s[38:39], v194, v194, v54
	v_rcp_f32_e32 v196, v195
	s_nop 0
	v_fma_f32 v197, -v195, v196, 1.0
	v_fmac_f32_e32 v196, v197, v196
	v_div_scale_f32 v197, vcc, v54, v194, v54
	v_mul_f32_e32 v198, v197, v196
	v_fma_f32 v199, -v195, v198, v197
	v_fmac_f32_e32 v198, v199, v196
	v_fma_f32 v195, -v195, v198, v197
	v_div_fmas_f32 v195, v195, v196, v198
	v_div_fixup_f32 v54, v195, v194, v54
	v_mul_f32_e32 v194, 0xbfb8aa3b, v55
	v_exp_f32_e32 v194, v194
	s_nop 0
	v_add_f32_e32 v194, 1.0, v194
	v_div_scale_f32 v195, s[38:39], v194, v194, v55
	v_rcp_f32_e32 v196, v195
	s_nop 0
	v_fma_f32 v197, -v195, v196, 1.0
	v_fmac_f32_e32 v196, v197, v196
	v_div_scale_f32 v197, vcc, v55, v194, v55
	v_mul_f32_e32 v198, v197, v196
	v_fma_f32 v199, -v195, v198, v197
	v_fmac_f32_e32 v198, v199, v196
	v_fma_f32 v195, -v195, v198, v197
	v_div_fmas_f32 v195, v195, v196, v198
	v_div_fixup_f32 v55, v195, v194, v55
	v_mul_f32_e32 v194, 0xbfb8aa3b, v56
	v_exp_f32_e32 v194, v194
	s_nop 0
	v_add_f32_e32 v194, 1.0, v194
	v_div_scale_f32 v195, s[38:39], v194, v194, v56
	v_rcp_f32_e32 v196, v195
	s_nop 0
	v_fma_f32 v197, -v195, v196, 1.0
	v_fmac_f32_e32 v196, v197, v196
	v_div_scale_f32 v197, vcc, v56, v194, v56
	v_mul_f32_e32 v198, v197, v196
	v_fma_f32 v199, -v195, v198, v197
	v_fmac_f32_e32 v198, v199, v196
	v_fma_f32 v195, -v195, v198, v197
	v_div_fmas_f32 v195, v195, v196, v198
	v_div_fixup_f32 v56, v195, v194, v56
	v_mul_f32_e32 v194, 0xbfb8aa3b, v57
	v_exp_f32_e32 v194, v194
	s_nop 0
	v_add_f32_e32 v194, 1.0, v194
	v_div_scale_f32 v195, s[38:39], v194, v194, v57
	v_rcp_f32_e32 v196, v195
	s_nop 0
	v_fma_f32 v197, -v195, v196, 1.0
	v_fmac_f32_e32 v196, v197, v196
	v_div_scale_f32 v197, vcc, v57, v194, v57
	v_mul_f32_e32 v198, v197, v196
	v_fma_f32 v199, -v195, v198, v197
	v_fmac_f32_e32 v198, v199, v196
	v_fma_f32 v195, -v195, v198, v197
	v_div_fmas_f32 v195, v195, v196, v198
	v_div_fixup_f32 v57, v195, v194, v57
	v_mul_f32_e32 v194, 0xbfb8aa3b, v50
	v_exp_f32_e32 v194, v194
	s_nop 0
	v_add_f32_e32 v194, 1.0, v194
	v_div_scale_f32 v195, s[38:39], v194, v194, v50
	v_rcp_f32_e32 v196, v195
	s_nop 0
	v_fma_f32 v197, -v195, v196, 1.0
	v_fmac_f32_e32 v196, v197, v196
	v_div_scale_f32 v197, vcc, v50, v194, v50
	v_mul_f32_e32 v198, v197, v196
	v_fma_f32 v199, -v195, v198, v197
	v_fmac_f32_e32 v198, v199, v196
	v_fma_f32 v195, -v195, v198, v197
	v_div_fmas_f32 v195, v195, v196, v198
	v_div_fixup_f32 v50, v195, v194, v50
	v_mul_f32_e32 v194, 0xbfb8aa3b, v51
	v_exp_f32_e32 v194, v194
	s_nop 0
	v_add_f32_e32 v194, 1.0, v194
	v_div_scale_f32 v195, s[38:39], v194, v194, v51
	v_rcp_f32_e32 v196, v195
	s_nop 0
	v_fma_f32 v197, -v195, v196, 1.0
	v_fmac_f32_e32 v196, v197, v196
	v_div_scale_f32 v197, vcc, v51, v194, v51
	v_mul_f32_e32 v198, v197, v196
	v_fma_f32 v199, -v195, v198, v197
	v_fmac_f32_e32 v198, v199, v196
	v_fma_f32 v195, -v195, v198, v197
	v_div_fmas_f32 v195, v195, v196, v198
	v_div_fixup_f32 v51, v195, v194, v51
	v_mul_f32_e32 v194, 0xbfb8aa3b, v52
	v_exp_f32_e32 v194, v194
	s_nop 0
	v_add_f32_e32 v194, 1.0, v194
	v_div_scale_f32 v195, s[38:39], v194, v194, v52
	v_rcp_f32_e32 v196, v195
	s_nop 0
	v_fma_f32 v197, -v195, v196, 1.0
	v_fmac_f32_e32 v196, v197, v196
	v_div_scale_f32 v197, vcc, v52, v194, v52
	v_mul_f32_e32 v198, v197, v196
	v_fma_f32 v199, -v195, v198, v197
	v_fmac_f32_e32 v198, v199, v196
	v_fma_f32 v195, -v195, v198, v197
	v_div_fmas_f32 v195, v195, v196, v198
	v_div_fixup_f32 v52, v195, v194, v52
	v_mul_f32_e32 v194, 0xbfb8aa3b, v53
	v_exp_f32_e32 v194, v194
	s_nop 0
	v_add_f32_e32 v194, 1.0, v194
	v_div_scale_f32 v195, s[38:39], v194, v194, v53
	v_rcp_f32_e32 v196, v195
	s_nop 0
	v_fma_f32 v197, -v195, v196, 1.0
	v_fmac_f32_e32 v196, v197, v196
	v_div_scale_f32 v197, vcc, v53, v194, v53
	v_mul_f32_e32 v198, v197, v196
	v_fma_f32 v199, -v195, v198, v197
	v_fmac_f32_e32 v198, v199, v196
	v_fma_f32 v195, -v195, v198, v197
	v_div_fmas_f32 v195, v195, v196, v198
	v_div_fixup_f32 v53, v195, v194, v53
.Lp1q_cvt_3_0:
	v_cvt_pk_bf16_f32 v190, v54, v55
	v_cvt_pk_bf16_f32 v191, v56, v57
	v_cvt_pk_bf16_f32 v192, v50, v51
	v_cvt_pk_bf16_f32 v193, v52, v53
	global_store_dwordx4 v187, v[190:193], s[10:11] offset:256
	s_nop 1
	s_add_i32 s27, s1, 144
	s_lshl_b32 s7, s27, 13
	s_add_u32 s10, s68, s7
	s_addc_u32 s11, s69, 0
	s_cmp_lg_u32 s25, 1
	s_cbranch_scc1 .Lp1q_nokv_3_1
	s_cmp_ge_u32 s27, 0x4100
	s_cbranch_scc1 .Lp1q_smp_3_1
	s_mul_hi_u32 s7, s27, 0x7e07e07f
	s_lshr_b32 s7, s7, 11
	s_mul_i32 s8, s7, 0x1040
	s_sub_i32 s8, s27, s8
	s_cmp_ge_u32 s8, 0x1010
	s_cbranch_scc1 .Lp1q_kvdone_3_1
	s_mul_i32 s7, s7, 0x1010
	s_add_i32 s7, s7, s8
	s_lshl_b32 s7, s7, 11
	s_add_u32 s8, s34, s7
	s_addc_u32 s9, s35, 0
	s_branch .Lp1q_kvst_3_1

;     DI void operator()(const f32x4 (&acc)[2][2][4][2], const pg8::Unit& u, int wr, int wc, int fr, int fq) const {
;     ...
;                     if (R < ROWS_P) { const int b = R / LPAD, t = R - b * LPAD; if (t < LP) fo = p.out + O_PAK + oi * PKV_SZ + ((size_t)b * LP + t) * 512 - seg * 512; }
;                     else fo = p.out + O_SAK + oi * SKV_SZ + (size_t)(R - ROWS_P) * 512 - seg * 512;
;                 }
;                 bf16_t* uo = p.u + (size_t)R * NU;
; #pragma unroll
;                 for (int bj = 0; bj < 2; ++bj) {
;                     const int n = colt + bj * 128 + wc * 32 + 8 * fq;
;                     f32x4 v0 = acc[ai][bj][m][0], v1 = acc[ai][bj][m][1];
;                     if (fo) { *(f32x4*)(fo + n) = v0; *(f32x4*)(fo + n + 4) = v1; }
.Lp1q_kvst_3_1:
	global_store_dwordx4 v188, v[38:41], s[8:9] offset:512
	global_store_dwordx4 v188, v[34:37], s[8:9] offset:528

; DI unsigned pk2(float a, float b) { f32x2 v = {a, b}; bf16x2v r = __builtin_convertvector(v, bf16x2v); return __builtin_bit_cast(unsigned, r); }
;     DI void operator()(const f32x4 (&acc)[2][2][4][2], const pg8::Unit& u, int wr, int wc, int fr, int fq) const {
;     ...
;                     if (R < ROWS_P) { const int b = R / LPAD, t = R - b * LPAD; if (t < LP) fo = p.out + O_PAK + oi * PKV_SZ + ((size_t)b * LP + t) * 512 - seg * 512; }
;                     else fo = p.out + O_SAK + oi * SKV_SZ + (size_t)(R - ROWS_P) * 512 - seg * 512;
;                 }
;                 bf16_t* uo = p.u + (size_t)R * NU;
; #pragma unroll
;                 for (int bj = 0; bj < 2; ++bj) {
;                     const int n = colt + bj * 128 + wc * 32 + 8 * fq;
;                     f32x4 v0 = acc[ai][bj][m][0], v1 = acc[ai][bj][m][1];
;                     if (fo) { *(f32x4*)(fo + n) = v0; *(f32x4*)(fo + n + 4) = v1; }
;                     if (isq) { v0 = v0 * QSCALE; v1 = v1 * QSCALE; }
;                     else if (isg) {
; #pragma unroll
;                         for (int j = 0; j < 4; ++j) { v0[j] = v0[j] / (1.0f + __expf(-v0[j])); v1[j] = v1[j] / (1.0f + __expf(-v1[j])); }
;                     }
;                     *(u32x4*)(uo + n) = (u32x4){pk2(v0[0], v0[1]), pk2(v0[2], v0[3]), pk2(v1[0], v1[1]), pk2(v1[2], v1[3])};
;                 }
.Lp1q_nokv_3_1:
	s_cmp_eq_u32 s25, 2
	s_cbranch_scc1 .Lp1q_gate_3_1
	v_pk_mul_f32 v[38:39], v[38:39], s[22:23] op_sel_hi:[1,0]
	v_pk_mul_f32 v[40:41], v[40:41], s[22:23] op_sel_hi:[1,0]
	v_pk_mul_f32 v[34:35], v[34:35], s[22:23] op_sel_hi:[1,0]
	v_pk_mul_f32 v[36:37], v[36:37], s[22:23] op_sel_hi:[1,0]
	s_branch .Lp1q_cvt_3_1
.Lp1q_gate_3_1:
	v_mul_f32_e32 v194, 0xbfb8aa3b, v38
	v_exp_f32_e32 v194, v194
	s_nop 0
	v_add_f32_e32 v194, 1.0, v194
	v_div_scale_f32 v195, s[38:39], v194, v194, v38
	v_rcp_f32_e32 v196, v195
	s_nop 0
	v_fma_f32 v197, -v195, v196, 1.0
	v_fmac_f32_e32 v196, v197, v196
	v_div_scale_f32 v197, vcc, v38, v194, v38
	v_mul_f32_e32 v198, v197, v196
	v_fma_f32 v199, -v195, v198, v197
	v_fmac_f32_e32 v198, v199, v196
	v_fma_f32 v195, -v195, v198, v197
	v_div_fmas_f32 v195, v195, v196, v198
	v_div_fixup_f32 v38, v195, v194, v38
	v_mul_f32_e32 v194, 0xbfb8aa3b, v39
	v_exp_f32_e32 v194, v194
	s_nop 0
	v_add_f32_e32 v194, 1.0, v194
	v_div_scale_f32 v195, s[38:39], v194, v194, v39
	v_rcp_f32_e32 v196, v195
	s_nop 0
	v_fma_f32 v197, -v195, v196, 1.0
	v_fmac_f32_e32 v196, v197, v196
	v_div_scale_f32 v197, vcc, v39, v194, v39
	v_mul_f32_e32 v198, v197, v196
	v_fma_f32 v199, -v195, v198, v197
	v_fmac_f32_e32 v198, v199, v196
	v_fma_f32 v195, -v195, v198, v197
	v_div_fmas_f32 v195, v195, v196, v198
	v_div_fixup_f32 v39, v195, v194, v39
	v_mul_f32_e32 v194, 0xbfb8aa3b, v40
	v_exp_f32_e32 v194, v194
	s_nop 0
	v_add_f32_e32 v194, 1.0, v194
	v_div_scale_f32 v195, s[38:39], v194, v194, v40
	v_rcp_f32_e32 v196, v195
	s_nop 0
	v_fma_f32 v197, -v195, v196, 1.0
	v_fmac_f32_e32 v196, v197, v196
	v_div_scale_f32 v197, vcc, v40, v194, v40
	v_mul_f32_e32 v198, v197, v196
	v_fma_f32 v199, -v195, v198, v197
	v_fmac_f32_e32 v198, v199, v196
	v_fma_f32 v195, -v195, v198, v197
	v_div_fmas_f32 v195, v195, v196, v198
	v_div_fixup_f32 v40, v195, v194, v40
	v_mul_f32_e32 v194, 0xbfb8aa3b, v41
	v_exp_f32_e32 v194, v194
	s_nop 0
	v_add_f32_e32 v194, 1.0, v194
	v_div_scale_f32 v195, s[38:39], v194, v194, v41
	v_rcp_f32_e32 v196, v195
	s_nop 0
	v_fma_f32 v197, -v195, v196, 1.0
	v_fmac_f32_e32 v196, v197, v196
	v_div_scale_f32 v197, vcc, v41, v194, v41
	v_mul_f32_e32 v198, v197, v196
	v_fma_f32 v199, -v195, v198, v197
	v_fmac_f32_e32 v198, v199, v196
	v_fma_f32 v195, -v195, v198, v197
	v_div_fmas_f32 v195, v195, v196, v198
	v_div_fixup_f32 v41, v195, v194, v41
	v_mul_f32_e32 v194, 0xbfb8aa3b, v34
	v_exp_f32_e32 v194, v194
	s_nop 0
	v_add_f32_e32 v194, 1.0, v194
	v_div_scale_f32 v195, s[38:39], v194, v194, v34
	v_rcp_f32_e32 v196, v195
	s_nop 0
	v_fma_f32 v197, -v195, v196, 1.0
	v_fmac_f32_e32 v196, v197, v196
	v_div_scale_f32 v197, vcc, v34, v194, v34
	v_mul_f32_e32 v198, v197, v196
	v_fma_f32 v199, -v195, v198, v197
	v_fmac_f32_e32 v198, v199, v196
	v_fma_f32 v195, -v195, v198, v197
	v_div_fmas_f32 v195, v195, v196, v198
	v_div_fixup_f32 v34, v195, v194, v34
	v_mul_f32_e32 v194, 0xbfb8aa3b, v35
	v_exp_f32_e32 v194, v194
	s_nop 0
	v_add_f32_e32 v194, 1.0, v194
	v_div_scale_f32 v195, s[38:39], v194, v194, v35
	v_rcp_f32_e32 v196, v195
	s_nop 0
	v_fma_f32 v197, -v195, v196, 1.0
	v_fmac_f32_e32 v196, v197, v196
	v_div_scale_f32 v197, vcc, v35, v194, v35
	v_mul_f32_e32 v198, v197, v196
	v_fma_f32 v199, -v195, v198, v197
	v_fmac_f32_e32 v198, v199, v196
	v_fma_f32 v195, -v195, v198, v197
	v_div_fmas_f32 v195, v195, v196, v198
	v_div_fixup_f32 v35, v195, v194, v35
	v_mul_f32_e32 v194, 0xbfb8aa3b, v36
	v_exp_f32_e32 v194, v194
	s_nop 0
	v_add_f32_e32 v194, 1.0, v194
	v_div_scale_f32 v195, s[38:39], v194, v194, v36
	v_rcp_f32_e32 v196, v195
	s_nop 0
	v_fma_f32 v197, -v195, v196, 1.0
	v_fmac_f32_e32 v196, v197, v196
	v_div_scale_f32 v197, vcc, v36, v194, v36
	v_mul_f32_e32 v198, v197, v196
	v_fma_f32 v199, -v195, v198, v197
	v_fmac_f32_e32 v198, v199, v196
	v_fma_f32 v195, -v195, v198, v197
	v_div_fmas_f32 v195, v195, v196, v198
	v_div_fixup_f32 v36, v195, v194, v36
	v_mul_f32_e32 v194, 0xbfb8aa3b, v37
	v_exp_f32_e32 v194, v194
	s_nop 0
	v_add_f32_e32 v194, 1.0, v194
	v_div_scale_f32 v195, s[38:39], v194, v194, v37
	v_rcp_f32_e32 v196, v195
	s_nop 0
	v_fma_f32 v197, -v195, v196, 1.0
	v_fmac_f32_e32 v196, v197, v196
	v_div_scale_f32 v197, vcc, v37, v194, v37
	v_mul_f32_e32 v198, v197, v196
	v_fma_f32 v199, -v195, v198, v197
	v_fmac_f32_e32 v198, v199, v196
	v_fma_f32 v195, -v195, v198, v197
	v_div_fmas_f32 v195, v195, v196, v198
	v_div_fixup_f32 v37, v195, v194, v37
.Lp1q_cvt_3_1:
	v_cvt_pk_bf16_f32 v190, v38, v39
	v_cvt_pk_bf16_f32 v191, v40, v41
	v_cvt_pk_bf16_f32 v192, v34, v35
	v_cvt_pk_bf16_f32 v193, v36, v37
	global_store_dwordx4 v187, v[190:193], s[10:11] offset:256
	s_nop 1
	s_add_i32 s27, s1, 160
	s_lshl_b32 s7, s27, 13
	s_add_u32 s10, s68, s7
	s_addc_u32 s11, s69, 0
	s_cmp_lg_u32 s25, 1
	s_cbranch_scc1 .Lp1q_nokv_3_2
	s_cmp_ge_u32 s27, 0x4100
	s_cbranch_scc1 .Lp1q_smp_3_2
	s_mul_hi_u32 s7, s27, 0x7e07e07f
	s_lshr_b32 s7, s7, 11
	s_mul_i32 s8, s7, 0x1040
	s_sub_i32 s8, s27, s8
	s_cmp_ge_u32 s8, 0x1010
	s_cbranch_scc1 .Lp1q_kvdone_3_2
	s_mul_i32 s7, s7, 0x1010
	s_add_i32 s7, s7, s8
	s_lshl_b32 s7, s7, 11
	s_add_u32 s8, s34, s7
	s_addc_u32 s9, s35, 0
	s_branch .Lp1q_kvst_3_2

;     DI void operator()(const f32x4 (&acc)[2][2][4][2], const pg8::Unit& u, int wr, int wc, int fr, int fq) const {
;     ...
;                     if (R < ROWS_P) { const int b = R / LPAD, t = R - b * LPAD; if (t < LP) fo = p.out + O_PAK + oi * PKV_SZ + ((size_t)b * LP + t) * 512 - seg * 512; }
;                     else fo = p.out + O_SAK + oi * SKV_SZ + (size_t)(R - ROWS_P) * 512 - seg * 512;
;                 }
;                 bf16_t* uo = p.u + (size_t)R * NU;
; #pragma unroll
;                 for (int bj = 0; bj < 2; ++bj) {
;                     const int n = colt + bj * 128 + wc * 32 + 8 * fq;
;                     f32x4 v0 = acc[ai][bj][m][0], v1 = acc[ai][bj][m][1];
;                     if (fo) { *(f32x4*)(fo + n) = v0; *(f32x4*)(fo + n + 4) = v1; }
.Lp1q_kvst_3_2:
	global_store_dwordx4 v188, v[22:25], s[8:9] offset:512
	global_store_dwordx4 v188, v[18:21], s[8:9] offset:528

; DI unsigned pk2(float a, float b) { f32x2 v = {a, b}; bf16x2v r = __builtin_convertvector(v, bf16x2v); return __builtin_bit_cast(unsigned, r); }
;     DI void operator()(const f32x4 (&acc)[2][2][4][2], const pg8::Unit& u, int wr, int wc, int fr, int fq) const {
;     ...
;                     if (R < ROWS_P) { const int b = R / LPAD, t = R - b * LPAD; if (t < LP) fo = p.out + O_PAK + oi * PKV_SZ + ((size_t)b * LP + t) * 512 - seg * 512; }
;                     else fo = p.out + O_SAK + oi * SKV_SZ + (size_t)(R - ROWS_P) * 512 - seg * 512;
;                 }
;                 bf16_t* uo = p.u + (size_t)R * NU;
; #pragma unroll
;                 for (int bj = 0; bj < 2; ++bj) {
;                     const int n = colt + bj * 128 + wc * 32 + 8 * fq;
;                     f32x4 v0 = acc[ai][bj][m][0], v1 = acc[ai][bj][m][1];
;                     if (fo) { *(f32x4*)(fo + n) = v0; *(f32x4*)(fo + n + 4) = v1; }
;                     if (isq) { v0 = v0 * QSCALE; v1 = v1 * QSCALE; }
;                     else if (isg) {
; #pragma unroll
;                         for (int j = 0; j < 4; ++j) { v0[j] = v0[j] / (1.0f + __expf(-v0[j])); v1[j] = v1[j] / (1.0f + __expf(-v1[j])); }
;                     }
;                     *(u32x4*)(uo + n) = (u32x4){pk2(v0[0], v0[1]), pk2(v0[2], v0[3]), pk2(v1[0], v1[1]), pk2(v1[2], v1[3])};
;                 }
.Lp1q_nokv_3_2:
	s_cmp_eq_u32 s25, 2
	s_cbranch_scc1 .Lp1q_gate_3_2
	v_pk_mul_f32 v[22:23], v[22:23], s[22:23] op_sel_hi:[1,0]
	v_pk_mul_f32 v[24:25], v[24:25], s[22:23] op_sel_hi:[1,0]
	v_pk_mul_f32 v[18:19], v[18:19], s[22:23] op_sel_hi:[1,0]
	v_pk_mul_f32 v[20:21], v[20:21], s[22:23] op_sel_hi:[1,0]
	s_branch .Lp1q_cvt_3_2
.Lp1q_gate_3_2:
	v_mul_f32_e32 v194, 0xbfb8aa3b, v22
	v_exp_f32_e32 v194, v194
	s_nop 0
	v_add_f32_e32 v194, 1.0, v194
	v_div_scale_f32 v195, s[38:39], v194, v194, v22
	v_rcp_f32_e32 v196, v195
	s_nop 0
	v_fma_f32 v197, -v195, v196, 1.0
	v_fmac_f32_e32 v196, v197, v196
	v_div_scale_f32 v197, vcc, v22, v194, v22
	v_mul_f32_e32 v198, v197, v196
	v_fma_f32 v199, -v195, v198, v197
	v_fmac_f32_e32 v198, v199, v196
	v_fma_f32 v195, -v195, v198, v197
	v_div_fmas_f32 v195, v195, v196, v198
	v_div_fixup_f32 v22, v195, v194, v22
	v_mul_f32_e32 v194, 0xbfb8aa3b, v23
	v_exp_f32_e32 v194, v194
	s_nop 0
	v_add_f32_e32 v194, 1.0, v194
	v_div_scale_f32 v195, s[38:39], v194, v194, v23
	v_rcp_f32_e32 v196, v195
	s_nop 0
	v_fma_f32 v197, -v195, v196, 1.0
	v_fmac_f32_e32 v196, v197, v196
	v_div_scale_f32 v197, vcc, v23, v194, v23
	v_mul_f32_e32 v198, v197, v196
	v_fma_f32 v199, -v195, v198, v197
	v_fmac_f32_e32 v198, v199, v196
	v_fma_f32 v195, -v195, v198, v197
	v_div_fmas_f32 v195, v195, v196, v198
	v_div_fixup_f32 v23, v195, v194, v23
	v_mul_f32_e32 v194, 0xbfb8aa3b, v24
	v_exp_f32_e32 v194, v194
	s_nop 0
	v_add_f32_e32 v194, 1.0, v194
	v_div_scale_f32 v195, s[38:39], v194, v194, v24
	v_rcp_f32_e32 v196, v195
	s_nop 0
	v_fma_f32 v197, -v195, v196, 1.0
	v_fmac_f32_e32 v196, v197, v196
	v_div_scale_f32 v197, vcc, v24, v194, v24
	v_mul_f32_e32 v198, v197, v196
	v_fma_f32 v199, -v195, v198, v197
	v_fmac_f32_e32 v198, v199, v196
	v_fma_f32 v195, -v195, v198, v197
	v_div_fmas_f32 v195, v195, v196, v198
	v_div_fixup_f32 v24, v195, v194, v24
	v_mul_f32_e32 v194, 0xbfb8aa3b, v25
	v_exp_f32_e32 v194, v194
	s_nop 0
	v_add_f32_e32 v194, 1.0, v194
	v_div_scale_f32 v195, s[38:39], v194, v194, v25
	v_rcp_f32_e32 v196, v195
	s_nop 0
	v_fma_f32 v197, -v195, v196, 1.0
	v_fmac_f32_e32 v196, v197, v196
	v_div_scale_f32 v197, vcc, v25, v194, v25
	v_mul_f32_e32 v198, v197, v196
	v_fma_f32 v199, -v195, v198, v197
	v_fmac_f32_e32 v198, v199, v196
	v_fma_f32 v195, -v195, v198, v197
	v_div_fmas_f32 v195, v195, v196, v198
	v_div_fixup_f32 v25, v195, v194, v25
	v_mul_f32_e32 v194, 0xbfb8aa3b, v18
	v_exp_f32_e32 v194, v194
	s_nop 0
	v_add_f32_e32 v194, 1.0, v194
	v_div_scale_f32 v195, s[38:39], v194, v194, v18
	v_rcp_f32_e32 v196, v195
	s_nop 0
	v_fma_f32 v197, -v195, v196, 1.0
	v_fmac_f32_e32 v196, v197, v196
	v_div_scale_f32 v197, vcc, v18, v194, v18
	v_mul_f32_e32 v198, v197, v196
	v_fma_f32 v199, -v195, v198, v197
	v_fmac_f32_e32 v198, v199, v196
	v_fma_f32 v195, -v195, v198, v197
	v_div_fmas_f32 v195, v195, v196, v198
	v_div_fixup_f32 v18, v195, v194, v18
	v_mul_f32_e32 v194, 0xbfb8aa3b, v19
	v_exp_f32_e32 v194, v194
	s_nop 0
	v_add_f32_e32 v194, 1.0, v194
	v_div_scale_f32 v195, s[38:39], v194, v194, v19
	v_rcp_f32_e32 v196, v195
	s_nop 0
	v_fma_f32 v197, -v195, v196, 1.0
	v_fmac_f32_e32 v196, v197, v196
	v_div_scale_f32 v197, vcc, v19, v194, v19
	v_mul_f32_e32 v198, v197, v196
	v_fma_f32 v199, -v195, v198, v197
	v_fmac_f32_e32 v198, v199, v196
	v_fma_f32 v195, -v195, v198, v197
	v_div_fmas_f32 v195, v195, v196, v198
	v_div_fixup_f32 v19, v195, v194, v19
	v_mul_f32_e32 v194, 0xbfb8aa3b, v20
	v_exp_f32_e32 v194, v194
	s_nop 0
	v_add_f32_e32 v194, 1.0, v194
	v_div_scale_f32 v195, s[38:39], v194, v194, v20
	v_rcp_f32_e32 v196, v195
	s_nop 0
	v_fma_f32 v197, -v195, v196, 1.0
	v_fmac_f32_e32 v196, v197, v196
	v_div_scale_f32 v197, vcc, v20, v194, v20
	v_mul_f32_e32 v198, v197, v196
	v_fma_f32 v199, -v195, v198, v197
	v_fmac_f32_e32 v198, v199, v196
	v_fma_f32 v195, -v195, v198, v197
	v_div_fmas_f32 v195, v195, v196, v198
	v_div_fixup_f32 v20, v195, v194, v20
	v_mul_f32_e32 v194, 0xbfb8aa3b, v21
	v_exp_f32_e32 v194, v194
	s_nop 0
	v_add_f32_e32 v194, 1.0, v194
	v_div_scale_f32 v195, s[38:39], v194, v194, v21
	v_rcp_f32_e32 v196, v195
	s_nop 0
	v_fma_f32 v197, -v195, v196, 1.0
	v_fmac_f32_e32 v196, v197, v196
	v_div_scale_f32 v197, vcc, v21, v194, v21
	v_mul_f32_e32 v198, v197, v196
	v_fma_f32 v199, -v195, v198, v197
	v_fmac_f32_e32 v198, v199, v196
	v_fma_f32 v195, -v195, v198, v197
	v_div_fmas_f32 v195, v195, v196, v198
	v_div_fixup_f32 v21, v195, v194, v21
.Lp1q_cvt_3_2:
	v_cvt_pk_bf16_f32 v190, v22, v23
	v_cvt_pk_bf16_f32 v191, v24, v25
	v_cvt_pk_bf16_f32 v192, v18, v19
	v_cvt_pk_bf16_f32 v193, v20, v21
	global_store_dwordx4 v187, v[190:193], s[10:11] offset:256
	s_nop 1
	s_add_i32 s27, s1, 176
	s_lshl_b32 s7, s27, 13
	s_add_u32 s10, s68, s7
	s_addc_u32 s11, s69, 0
	s_cmp_lg_u32 s25, 1
	s_cbranch_scc1 .Lp1q_nokv_3_3
	s_cmp_ge_u32 s27, 0x4100
	s_cbranch_scc1 .Lp1q_smp_3_3
	s_mul_hi_u32 s7, s27, 0x7e07e07f
	s_lshr_b32 s7, s7, 11
	s_mul_i32 s8, s7, 0x1040
	s_sub_i32 s8, s27, s8
	s_cmp_ge_u32 s8, 0x1010
	s_cbranch_scc1 .Lp1q_kvdone_3_3
	s_mul_i32 s7, s7, 0x1010
	s_add_i32 s7, s7, s8
	s_lshl_b32 s7, s7, 11
	s_add_u32 s8, s34, s7
	s_addc_u32 s9, s35, 0
	s_branch .Lp1q_kvst_3_3

;     DI void operator()(const f32x4 (&acc)[2][2][4][2], const pg8::Unit& u, int wr, int wc, int fr, int fq) const {
;     ...
;                     if (R < ROWS_P) { const int b = R / LPAD, t = R - b * LPAD; if (t < LP) fo = p.out + O_PAK + oi * PKV_SZ + ((size_t)b * LP + t) * 512 - seg * 512; }
;                     else fo = p.out + O_SAK + oi * SKV_SZ + (size_t)(R - ROWS_P) * 512 - seg * 512;
;                 }
;                 bf16_t* uo = p.u + (size_t)R * NU;
; #pragma unroll
;                 for (int bj = 0; bj < 2; ++bj) {
;                     const int n = colt + bj * 128 + wc * 32 + 8 * fq;
;                     f32x4 v0 = acc[ai][bj][m][0], v1 = acc[ai][bj][m][1];
;                     if (fo) { *(f32x4*)(fo + n) = v0; *(f32x4*)(fo + n + 4) = v1; }
.Lp1q_kvst_3_3:
	global_store_dwordx4 v188, v[6:9], s[8:9] offset:512
	global_store_dwordx4 v188, v[2:5], s[8:9] offset:528

; DI unsigned pk2(float a, float b) { f32x2 v = {a, b}; bf16x2v r = __builtin_convertvector(v, bf16x2v); return __builtin_bit_cast(unsigned, r); }
; #define PG8_BAR __builtin_amdgcn_s_barrier()
; template <class Epi, class Sched, bool ALIGN_EPI = false, bool SP2 = false>
; __device__ __forceinline__ void gemm_phase(PG8_LAS unsigned char* lds, const Gemm g, const Sched& S, const Epi& E) {
;     ...
;         cur = nxt; cA = nA; cB = nB; ++ui;
;         if constexpr (ALIGN_EPI) { if (wr == 1) PG8_BAR; }
;     }
;     DI void operator()(const f32x4 (&acc)[2][2][4][2], const pg8::Unit& u, int wr, int wc, int fr, int fq) const {
;     ...
;                     if (isq) { v0 = v0 * QSCALE; v1 = v1 * QSCALE; }
;                     else if (isg) {
; #pragma unroll
;                         for (int j = 0; j < 4; ++j) { v0[j] = v0[j] / (1.0f + __expf(-v0[j])); v1[j] = v1[j] / (1.0f + __expf(-v1[j])); }
;                     }
;                     *(u32x4*)(uo + n) = (u32x4){pk2(v0[0], v0[1]), pk2(v0[2], v0[3]), pk2(v1[0], v1[1]), pk2(v1[2], v1[3])};
;                 }
.Lp1q_nokv_3_3:
	s_cmp_eq_u32 s25, 2
	s_cbranch_scc1 .Lp1q_gate_3_3
	v_pk_mul_f32 v[6:7], v[6:7], s[22:23] op_sel_hi:[1,0]
	v_pk_mul_f32 v[8:9], v[8:9], s[22:23] op_sel_hi:[1,0]
	v_pk_mul_f32 v[2:3], v[2:3], s[22:23] op_sel_hi:[1,0]
	v_pk_mul_f32 v[4:5], v[4:5], s[22:23] op_sel_hi:[1,0]
	s_branch .Lp1q_cvt_3_3
.Lp1q_gate_3_3:
	v_mul_f32_e32 v194, 0xbfb8aa3b, v6
	v_exp_f32_e32 v194, v194
	s_nop 0
	v_add_f32_e32 v194, 1.0, v194
	v_div_scale_f32 v195, s[38:39], v194, v194, v6
	v_rcp_f32_e32 v196, v195
	s_nop 0
	v_fma_f32 v197, -v195, v196, 1.0
	v_fmac_f32_e32 v196, v197, v196
	v_div_scale_f32 v197, vcc, v6, v194, v6
	v_mul_f32_e32 v198, v197, v196
	v_fma_f32 v199, -v195, v198, v197
	v_fmac_f32_e32 v198, v199, v196
	v_fma_f32 v195, -v195, v198, v197
	v_div_fmas_f32 v195, v195, v196, v198
	v_div_fixup_f32 v6, v195, v194, v6
	v_mul_f32_e32 v194, 0xbfb8aa3b, v7
	v_exp_f32_e32 v194, v194
	s_nop 0
	v_add_f32_e32 v194, 1.0, v194
	v_div_scale_f32 v195, s[38:39], v194, v194, v7
	v_rcp_f32_e32 v196, v195
	s_nop 0
	v_fma_f32 v197, -v195, v196, 1.0
	v_fmac_f32_e32 v196, v197, v196
	v_div_scale_f32 v197, vcc, v7, v194, v7
	v_mul_f32_e32 v198, v197, v196
	v_fma_f32 v199, -v195, v198, v197
	v_fmac_f32_e32 v198, v199, v196
	v_fma_f32 v195, -v195, v198, v197
	v_div_fmas_f32 v195, v195, v196, v198
	v_div_fixup_f32 v7, v195, v194, v7
	v_mul_f32_e32 v194, 0xbfb8aa3b, v8
	v_exp_f32_e32 v194, v194
	s_nop 0
	v_add_f32_e32 v194, 1.0, v194
	v_div_scale_f32 v195, s[38:39], v194, v194, v8
	v_rcp_f32_e32 v196, v195
	s_nop 0
	v_fma_f32 v197, -v195, v196, 1.0
	v_fmac_f32_e32 v196, v197, v196
	v_div_scale_f32 v197, vcc, v8, v194, v8
	v_mul_f32_e32 v198, v197, v196
	v_fma_f32 v199, -v195, v198, v197
	v_fmac_f32_e32 v198, v199, v196
	v_fma_f32 v195, -v195, v198, v197
	v_div_fmas_f32 v195, v195, v196, v198
	v_div_fixup_f32 v8, v195, v194, v8
	v_mul_f32_e32 v194, 0xbfb8aa3b, v9
	v_exp_f32_e32 v194, v194
	s_nop 0
	v_add_f32_e32 v194, 1.0, v194
	v_div_scale_f32 v195, s[38:39], v194, v194, v9
	v_rcp_f32_e32 v196, v195
	s_nop 0
	v_fma_f32 v197, -v195, v196, 1.0
	v_fmac_f32_e32 v196, v197, v196
	v_div_scale_f32 v197, vcc, v9, v194, v9
	v_mul_f32_e32 v198, v197, v196
	v_fma_f32 v199, -v195, v198, v197
	v_fmac_f32_e32 v198, v199, v196
	v_fma_f32 v195, -v195, v198, v197
	v_div_fmas_f32 v195, v195, v196, v198
	v_div_fixup_f32 v9, v195, v194, v9
	v_mul_f32_e32 v194, 0xbfb8aa3b, v2
	v_exp_f32_e32 v194, v194
	s_nop 0
	v_add_f32_e32 v194, 1.0, v194
	v_div_scale_f32 v195, s[38:39], v194, v194, v2
	v_rcp_f32_e32 v196, v195
	s_nop 0
	v_fma_f32 v197, -v195, v196, 1.0
	v_fmac_f32_e32 v196, v197, v196
	v_div_scale_f32 v197, vcc, v2, v194, v2
	v_mul_f32_e32 v198, v197, v196
	v_fma_f32 v199, -v195, v198, v197
	v_fmac_f32_e32 v198, v199, v196
	v_fma_f32 v195, -v195, v198, v197
	v_div_fmas_f32 v195, v195, v196, v198
	v_div_fixup_f32 v2, v195, v194, v2
	v_mul_f32_e32 v194, 0xbfb8aa3b, v3
	v_exp_f32_e32 v194, v194
	s_nop 0
	v_add_f32_e32 v194, 1.0, v194
	v_div_scale_f32 v195, s[38:39], v194, v194, v3
	v_rcp_f32_e32 v196, v195
	s_nop 0
	v_fma_f32 v197, -v195, v196, 1.0
	v_fmac_f32_e32 v196, v197, v196
	v_div_scale_f32 v197, vcc, v3, v194, v3
	v_mul_f32_e32 v198, v197, v196
	v_fma_f32 v199, -v195, v198, v197
	v_fmac_f32_e32 v198, v199, v196
	v_fma_f32 v195, -v195, v198, v197
	v_div_fmas_f32 v195, v195, v196, v198
	v_div_fixup_f32 v3, v195, v194, v3
	v_mul_f32_e32 v194, 0xbfb8aa3b, v4
	v_exp_f32_e32 v194, v194
	s_nop 0
	v_add_f32_e32 v194, 1.0, v194
	v_div_scale_f32 v195, s[38:39], v194, v194, v4
	v_rcp_f32_e32 v196, v195
	s_nop 0
	v_fma_f32 v197, -v195, v196, 1.0
	v_fmac_f32_e32 v196, v197, v196
	v_div_scale_f32 v197, vcc, v4, v194, v4
	v_mul_f32_e32 v198, v197, v196
	v_fma_f32 v199, -v195, v198, v197
	v_fmac_f32_e32 v198, v199, v196
	v_fma_f32 v195, -v195, v198, v197
	v_div_fmas_f32 v195, v195, v196, v198
	v_div_fixup_f32 v4, v195, v194, v4
	v_mul_f32_e32 v194, 0xbfb8aa3b, v5
	v_exp_f32_e32 v194, v194
	s_nop 0
	v_add_f32_e32 v194, 1.0, v194
	v_div_scale_f32 v195, s[38:39], v194, v194, v5
	v_rcp_f32_e32 v196, v195
	s_nop 0
	v_fma_f32 v197, -v195, v196, 1.0
	v_fmac_f32_e32 v196, v197, v196
	v_div_scale_f32 v197, vcc, v5, v194, v5
	v_mul_f32_e32 v198, v197, v196
	v_fma_f32 v199, -v195, v198, v197
	v_fmac_f32_e32 v198, v199, v196
	v_fma_f32 v195, -v195, v198, v197
	v_div_fmas_f32 v195, v195, v196, v198
	v_div_fixup_f32 v5, v195, v194, v5
.Lp1q_cvt_3_3:
	v_cvt_pk_bf16_f32 v190, v6, v7
	v_cvt_pk_bf16_f32 v191, v8, v9
	v_cvt_pk_bf16_f32 v192, v2, v3
	v_cvt_pk_bf16_f32 v193, v4, v5
	global_store_dwordx4 v187, v[190:193], s[10:11] offset:256
	s_nop 1
	s_branch .Lp1q_tail
.Lp1q_tail:
	s_andn2_b64 vcc, exec, s[4:5]
	s_mov_b64 s[0:1], -1
	s_cbranch_vccnz .LBB0_134
	s_andn2_b64 vcc, exec, s[12:13]
	s_cbranch_vccnz .LBB0_133
	s_barrier
	s_branch .LBB0_133
; #define PG8_STAGE(bufoff, gbase, voff) do { _Pragma("unroll") for (int _i = 0; _i < 2; ++_i) \
;         __builtin_amdgcn_global_load_lds((const unsigned*)((const char*)(gbase) + (voff)[_i]), (PG8_LAS unsigned*)(lds + (bufoff) + ldsw + _i * 8192), 16, 0, 0); } while (0)
; #define PG8_LDA(dst, b, h) do { _Pragma("unroll") for (int m = 0; m < 4; ++m) _Pragma("unroll") for (int k = 0; k < 2; ++k) dst[m][k] = *(const PG8_LAS bf16x8*)(lds + PG8_SA(b, h) + aoff + m * 2048 + k * 1024); } while (0)
; #define PG8_LDB(dst, b, h) do { _Pragma("unroll") for (int n = 0; n < 2; ++n) _Pragma("unroll") for (int k = 0; k < 2; ++k) dst[n][k] = *(const PG8_LAS bf16x8*)(lds + PG8_SB(b, h) + boff + n * 2048 + k * 1024); } while (0)
; #define PG8_MMA(ai, bj, At, Bt) do { __builtin_amdgcn_s_setprio(1); _Pragma("unroll") for (int m = 0; m < 4; ++m) _Pragma("unroll") for (int n = 0; n < 2; ++n) _Pragma("unroll") for (int k = 0; k < 2; ++k) \
;         acc[ai][bj][m][n] = __builtin_amdgcn_mfma_f32_16x16x32_bf16(Bt[n][k], At[m][k], acc[ai][bj][m][n], 0, 0, 0); __builtin_amdgcn_s_setprio(0); } while (0)
; #define PG8_WAIT_V(n) asm volatile("s_waitcnt vmcnt(" #n ")" ::: "memory")
; #define PG8_WAIT_L(n) asm volatile("s_waitcnt lgkmcnt(" #n ")" ::: "memory")
; #define PG8_BAR __builtin_amdgcn_s_barrier()
; #define PG8_SCHED __builtin_amdgcn_sched_barrier(0)
; template <class Epi, class Sched, bool ALIGN_EPI = false, bool SP2 = false>
; __device__ __forceinline__ void gemm_phase(PG8_LAS unsigned char* lds, const Gemm g, const Sched& S, const Epi& E) {
;     ...
;             PG8_LDB(B0, 0, 0); PG8_LDB(B1, 0, 1); PG8_SCHED; PG8_LDA(At, 0, 0); PG8_STAGE(PG8_SA(1, 1), a1 + hstep, voffA);
;             PG8_WAIT_V(8); PG8_WAIT_L(0); PG8_BAR; PG8_MMA(0, 0, At, B0); PG8_MMA(0, 1, At, B1); PG8_BAR; PG8_SCHED;
.Lp1q_kloop:
	ds_read_b128 v[130:133], v180
	ds_read_b128 v[134:137], v180 offset:1024
	ds_read_b128 v[158:161], v180 offset:2048
	ds_read_b128 v[186:189], v180 offset:3072
	ds_read_b128 v[190:193], v181
	ds_read_b128 v[194:197], v181 offset:1024
	ds_read_b128 v[198:201], v181 offset:2048
	ds_read_b128 v[202:205], v181 offset:3072
	s_add_u32 s10, s8, 0xfffc0080
	s_addc_u32 s11, s9, -1
	s_cmp_eq_u32 s37, 12
	s_cselect_b32 s35, s1, s11
	s_cselect_b32 s34, s7, s10
	s_cselect_b32 s11, s15, s36
	s_cselect_b32 s10, s25, s27
	v_lshl_add_u64 v[162:163], s[8:9], 0, v[150:151]
	s_add_i32 m0, s42, 0xc000
	ds_read_b128 v[206:209], v182
	ds_read_b128 v[210:213], v182 offset:1024
	ds_read_b128 v[214:217], v182 offset:2048
	ds_read_b128 v[218:221], v182 offset:3072
	ds_read_b128 v[222:225], v182 offset:4096
	ds_read_b128 v[226:229], v182 offset:5120
	ds_read_b128 v[230:233], v182 offset:6144
	ds_read_b128 v[234:237], v182 offset:7168
	global_load_lds_dwordx4 v[162:163], off
	v_lshl_add_u64 v[162:163], s[8:9], 0, v[152:153]
	s_add_i32 m0, s42, 0xe000
	s_nop 0
	global_load_lds_dwordx4 v[162:163], off
	s_waitcnt vmcnt(8)
	s_waitcnt lgkmcnt(0)
	s_barrier
	s_setprio 1
	s_waitcnt lgkmcnt(0)
	s_bitcmp1_b32 s100, 0
	s_cbranch_scc0 .Lp1q_skip_0
	v_mfma_f32_16x16x32_bf16 v[126:129], v[130:133], v[206:209], v[126:129]
	v_mfma_f32_16x16x32_bf16 v[122:125], v[158:161], v[206:209], v[122:125]
	v_mfma_f32_16x16x32_bf16 v[110:113], v[130:133], v[214:217], v[110:113]
	v_mfma_f32_16x16x32_bf16 v[106:109], v[158:161], v[214:217], v[106:109]
	v_mfma_f32_16x16x32_bf16 v[94:97], v[130:133], v[222:225], v[94:97]
	v_mfma_f32_16x16x32_bf16 v[90:93], v[158:161], v[222:225], v[90:93]
	v_mfma_f32_16x16x32_bf16 v[78:81], v[130:133], v[230:233], v[78:81]
	v_mfma_f32_16x16x32_bf16 v[74:77], v[158:161], v[230:233], v[74:77]
	v_mfma_f32_16x16x32_bf16 v[126:129], v[134:137], v[210:213], v[126:129]
	v_mfma_f32_16x16x32_bf16 v[122:125], v[186:189], v[210:213], v[122:125]
	v_mfma_f32_16x16x32_bf16 v[110:113], v[134:137], v[218:221], v[110:113]
	v_mfma_f32_16x16x32_bf16 v[106:109], v[186:189], v[218:221], v[106:109]
	v_mfma_f32_16x16x32_bf16 v[94:97], v[134:137], v[226:229], v[94:97]
	v_mfma_f32_16x16x32_bf16 v[90:93], v[186:189], v[226:229], v[90:93]
	v_mfma_f32_16x16x32_bf16 v[78:81], v[134:137], v[234:237], v[78:81]
	v_mfma_f32_16x16x32_bf16 v[74:77], v[186:189], v[234:237], v[74:77]
.Lp1q_skip_0:
	s_setprio 0
	s_setprio 1
	s_bitcmp1_b32 s100, 1
	s_cbranch_scc0 .Lp1q_skip_1
	v_mfma_f32_16x16x32_bf16 v[118:121], v[190:193], v[206:209], v[118:121]
	v_mfma_f32_16x16x32_bf16 v[114:117], v[198:201], v[206:209], v[114:117]
	v_mfma_f32_16x16x32_bf16 v[102:105], v[190:193], v[214:217], v[102:105]
	v_mfma_f32_16x16x32_bf16 v[98:101], v[198:201], v[214:217], v[98:101]
	v_mfma_f32_16x16x32_bf16 v[86:89], v[190:193], v[222:225], v[86:89]
	v_mfma_f32_16x16x32_bf16 v[82:85], v[198:201], v[222:225], v[82:85]
	v_mfma_f32_16x16x32_bf16 v[70:73], v[190:193], v[230:233], v[70:73]
	v_mfma_f32_16x16x32_bf16 v[66:69], v[198:201], v[230:233], v[66:69]
	v_mfma_f32_16x16x32_bf16 v[118:121], v[194:197], v[210:213], v[118:121]
	v_mfma_f32_16x16x32_bf16 v[114:117], v[202:205], v[210:213], v[114:117]
	v_mfma_f32_16x16x32_bf16 v[102:105], v[194:197], v[218:221], v[102:105]
	v_mfma_f32_16x16x32_bf16 v[98:101], v[202:205], v[218:221], v[98:101]
	v_mfma_f32_16x16x32_bf16 v[86:89], v[194:197], v[226:229], v[86:89]
	v_mfma_f32_16x16x32_bf16 v[82:85], v[202:205], v[226:229], v[82:85]
	v_mfma_f32_16x16x32_bf16 v[70:73], v[194:197], v[234:237], v[70:73]
	v_mfma_f32_16x16x32_bf16 v[66:69], v[202:205], v[234:237], v[66:69]
; #define PG8_STAGE(bufoff, gbase, voff) do { _Pragma("unroll") for (int _i = 0; _i < 2; ++_i) \
;         __builtin_amdgcn_global_load_lds((const unsigned*)((const char*)(gbase) + (voff)[_i]), (PG8_LAS unsigned*)(lds + (bufoff) + ldsw + _i * 8192), 16, 0, 0); } while (0)
; #define PG8_LDA(dst, b, h) do { _Pragma("unroll") for (int m = 0; m < 4; ++m) _Pragma("unroll") for (int k = 0; k < 2; ++k) dst[m][k] = *(const PG8_LAS bf16x8*)(lds + PG8_SA(b, h) + aoff + m * 2048 + k * 1024); } while (0)
; #define PG8_LDB(dst, b, h) do { _Pragma("unroll") for (int n = 0; n < 2; ++n) _Pragma("unroll") for (int k = 0; k < 2; ++k) dst[n][k] = *(const PG8_LAS bf16x8*)(lds + PG8_SB(b, h) + boff + n * 2048 + k * 1024); } while (0)
; #define PG8_MMA(ai, bj, At, Bt) do { __builtin_amdgcn_s_setprio(1); _Pragma("unroll") for (int m = 0; m < 4; ++m) _Pragma("unroll") for (int n = 0; n < 2; ++n) _Pragma("unroll") for (int k = 0; k < 2; ++k) \
;         acc[ai][bj][m][n] = __builtin_amdgcn_mfma_f32_16x16x32_bf16(Bt[n][k], At[m][k], acc[ai][bj][m][n], 0, 0, 0); __builtin_amdgcn_s_setprio(0); } while (0)
; #define PG8_WAIT_V(n) asm volatile("s_waitcnt vmcnt(" #n ")" ::: "memory")
; #define PG8_WAIT_L(n) asm volatile("s_waitcnt lgkmcnt(" #n ")" ::: "memory")
; #define PG8_BAR __builtin_amdgcn_s_barrier()
; #define PG8_SCHED __builtin_amdgcn_sched_barrier(0)
; template <class Epi, class Sched, bool ALIGN_EPI = false, bool SP2 = false>
; __device__ __forceinline__ void gemm_phase(PG8_LAS unsigned char* lds, const Gemm g, const Sched& S, const Epi& E) {
;     ...
;             PG8_LDA(At, 0, 1); PG8_STAGE(PG8_SB(0, 0), b2, voffB); PG8_STAGE(PG8_SB(0, 1), b2 + hstep, voffB); PG8_STAGE(PG8_SA(0, 0), a2, voffA);
;             PG8_WAIT_V(8); PG8_WAIT_L(0); PG8_BAR; PG8_MMA(1, 0, At, B0); PG8_MMA(1, 1, At, B1); PG8_BAR; PG8_SCHED;
;             PG8_LDB(B0, 1, 0); PG8_LDB(B1, 1, 1); PG8_SCHED; PG8_LDA(At, 1, 0); PG8_STAGE(PG8_SA(0, 1), a2 + hstep, voffA);
;             PG8_WAIT_V(8); PG8_WAIT_L(0); PG8_BAR; PG8_MMA(0, 0, At, B0); PG8_MMA(0, 1, At, B1); PG8_BAR; PG8_SCHED;
.Lp1q_skip_1:
	s_setprio 0
	s_barrier
	s_add_i32 s38, s93, s23
	v_lshl_add_u64 v[162:163], s[10:11], 0, v[142:143]
	s_mov_b32 m0, s38
	ds_read_b128 v[206:209], v182 offset:16384
	ds_read_b128 v[210:213], v182 offset:17408
	ds_read_b128 v[214:217], v182 offset:18432
	ds_read_b128 v[218:221], v182 offset:19456
	ds_read_b128 v[222:225], v182 offset:20480
	ds_read_b128 v[226:229], v182 offset:21504
	ds_read_b128 v[230:233], v182 offset:22528
	ds_read_b128 v[234:237], v182 offset:23552
	global_load_lds_dwordx4 v[162:163], off
	s_add_i32 m0, s38, 0x2000
	s_add_u32 s38, s10, 0x40000
	v_lshl_add_u64 v[238:239], s[10:11], 0, v[146:147]
	s_addc_u32 s39, s11, 0
	s_add_i32 vcc_lo, s94, s23
	global_load_lds_dwordx4 v[238:239], off
	v_lshl_add_u64 v[240:241], s[38:39], 0, v[142:143]
	s_mov_b32 m0, vcc_lo
	v_lshl_add_u64 v[242:243], s[34:35], 0, v[144:145]
	global_load_lds_dwordx4 v[240:241], off
	v_lshl_add_u64 v[240:241], s[38:39], 0, v[146:147]
	s_add_i32 m0, vcc_lo, 0x2000
	s_nop 0
	global_load_lds_dwordx4 v[240:241], off
	v_lshl_add_u64 v[240:241], s[34:35], 0, v[140:141]
	s_mov_b32 m0, s42
	s_nop 0
	global_load_lds_dwordx4 v[240:241], off
	s_mov_b32 m0, s43
	s_nop 0
	global_load_lds_dwordx4 v[242:243], off
	s_waitcnt vmcnt(8)
	s_waitcnt lgkmcnt(0)
	s_barrier
	s_setprio 1
	s_waitcnt lgkmcnt(0)
	s_bitcmp1_b32 s100, 2
	s_cbranch_scc0 .Lp1q_skip_2
	v_mfma_f32_16x16x32_bf16 v[62:65], v[130:133], v[206:209], v[62:65]
	v_mfma_f32_16x16x32_bf16 v[58:61], v[158:161], v[206:209], v[58:61]
	v_mfma_f32_16x16x32_bf16 v[46:49], v[130:133], v[214:217], v[46:49]
	v_mfma_f32_16x16x32_bf16 v[42:45], v[158:161], v[214:217], v[42:45]
	v_mfma_f32_16x16x32_bf16 v[30:33], v[130:133], v[222:225], v[30:33]
	v_mfma_f32_16x16x32_bf16 v[26:29], v[158:161], v[222:225], v[26:29]
	v_mfma_f32_16x16x32_bf16 v[14:17], v[130:133], v[230:233], v[14:17]
	v_mfma_f32_16x16x32_bf16 v[10:13], v[158:161], v[230:233], v[10:13]
	v_mfma_f32_16x16x32_bf16 v[62:65], v[134:137], v[210:213], v[62:65]
	v_mfma_f32_16x16x32_bf16 v[58:61], v[186:189], v[210:213], v[58:61]
	v_mfma_f32_16x16x32_bf16 v[46:49], v[134:137], v[218:221], v[46:49]
	v_mfma_f32_16x16x32_bf16 v[42:45], v[186:189], v[218:221], v[42:45]
	v_mfma_f32_16x16x32_bf16 v[30:33], v[134:137], v[226:229], v[30:33]
	v_mfma_f32_16x16x32_bf16 v[26:29], v[186:189], v[226:229], v[26:29]
	v_mfma_f32_16x16x32_bf16 v[14:17], v[134:137], v[234:237], v[14:17]
	v_mfma_f32_16x16x32_bf16 v[10:13], v[186:189], v[234:237], v[10:13]
.Lp1q_skip_2:
	s_setprio 0
	s_setprio 1
	s_bitcmp1_b32 s100, 3
	s_cbranch_scc0 .Lp1q_skip_3
	v_mfma_f32_16x16x32_bf16 v[54:57], v[190:193], v[206:209], v[54:57]
	v_mfma_f32_16x16x32_bf16 v[50:53], v[198:201], v[206:209], v[50:53]
	v_mfma_f32_16x16x32_bf16 v[38:41], v[190:193], v[214:217], v[38:41]
	v_mfma_f32_16x16x32_bf16 v[34:37], v[198:201], v[214:217], v[34:37]
	v_mfma_f32_16x16x32_bf16 v[22:25], v[190:193], v[222:225], v[22:25]
	v_mfma_f32_16x16x32_bf16 v[18:21], v[198:201], v[222:225], v[18:21]
	v_mfma_f32_16x16x32_bf16 v[6:9], v[190:193], v[230:233], v[6:9]
	v_mfma_f32_16x16x32_bf16 v[2:5], v[198:201], v[230:233], v[2:5]
	v_mfma_f32_16x16x32_bf16 v[54:57], v[194:197], v[210:213], v[54:57]
	v_mfma_f32_16x16x32_bf16 v[50:53], v[202:205], v[210:213], v[50:53]
	v_mfma_f32_16x16x32_bf16 v[38:41], v[194:197], v[218:221], v[38:41]
	v_mfma_f32_16x16x32_bf16 v[34:37], v[202:205], v[218:221], v[34:37]
	v_mfma_f32_16x16x32_bf16 v[22:25], v[194:197], v[226:229], v[22:25]
	v_mfma_f32_16x16x32_bf16 v[18:21], v[202:205], v[226:229], v[18:21]
	v_mfma_f32_16x16x32_bf16 v[6:9], v[194:197], v[234:237], v[6:9]
	v_mfma_f32_16x16x32_bf16 v[2:5], v[202:205], v[234:237], v[2:5]
.Lp1q_skip_3:
	s_setprio 0
	s_barrier
	ds_read_b128 v[130:133], v183
	ds_read_b128 v[134:137], v183 offset:1024
	ds_read_b128 v[158:161], v183 offset:2048
	ds_read_b128 v[186:189], v183 offset:3072
	ds_read_b128 v[190:193], v184
	ds_read_b128 v[194:197], v184 offset:1024
	ds_read_b128 v[198:201], v184 offset:2048
	ds_read_b128 v[202:205], v184 offset:3072
	s_add_u32 s34, s34, 0x40000
	s_addc_u32 s35, s35, 0
	s_mov_b32 m0, s46
	v_lshl_add_u64 v[244:245], s[34:35], 0, v[140:141]
	ds_read_b128 v[206:209], v182 offset:32768
	ds_read_b128 v[210:213], v182 offset:33792
	ds_read_b128 v[214:217], v182 offset:34816
	ds_read_b128 v[218:221], v182 offset:35840
	ds_read_b128 v[222:225], v182 offset:36864
	ds_read_b128 v[226:229], v182 offset:37888
	ds_read_b128 v[230:233], v182 offset:38912
	ds_read_b128 v[234:237], v182 offset:39936
	global_load_lds_dwordx4 v[244:245], off
	v_lshl_add_u64 v[244:245], s[34:35], 0, v[144:145]
	s_mov_b32 m0, s47
	s_nop 0
	global_load_lds_dwordx4 v[244:245], off
	s_waitcnt vmcnt(8)
	s_waitcnt lgkmcnt(0)
	s_barrier
	s_setprio 1
	s_waitcnt lgkmcnt(0)
	s_bitcmp1_b32 s100, 0
	s_cbranch_scc0 .Lp1q_skip_4
	v_mfma_f32_16x16x32_bf16 v[126:129], v[130:133], v[206:209], v[126:129]
	v_mfma_f32_16x16x32_bf16 v[122:125], v[158:161], v[206:209], v[122:125]
	v_mfma_f32_16x16x32_bf16 v[110:113], v[130:133], v[214:217], v[110:113]
	v_mfma_f32_16x16x32_bf16 v[106:109], v[158:161], v[214:217], v[106:109]
	v_mfma_f32_16x16x32_bf16 v[94:97], v[130:133], v[222:225], v[94:97]
	v_mfma_f32_16x16x32_bf16 v[90:93], v[158:161], v[222:225], v[90:93]
	v_mfma_f32_16x16x32_bf16 v[78:81], v[130:133], v[230:233], v[78:81]
	v_mfma_f32_16x16x32_bf16 v[74:77], v[158:161], v[230:233], v[74:77]
	v_mfma_f32_16x16x32_bf16 v[126:129], v[134:137], v[210:213], v[126:129]
	v_mfma_f32_16x16x32_bf16 v[122:125], v[186:189], v[210:213], v[122:125]
	v_mfma_f32_16x16x32_bf16 v[110:113], v[134:137], v[218:221], v[110:113]
	v_mfma_f32_16x16x32_bf16 v[106:109], v[186:189], v[218:221], v[106:109]
	v_mfma_f32_16x16x32_bf16 v[94:97], v[134:137], v[226:229], v[94:97]
	v_mfma_f32_16x16x32_bf16 v[90:93], v[186:189], v[226:229], v[90:93]
	v_mfma_f32_16x16x32_bf16 v[78:81], v[134:137], v[234:237], v[78:81]
	v_mfma_f32_16x16x32_bf16 v[74:77], v[186:189], v[234:237], v[74:77]

; #define PG8_STAGE(bufoff, gbase, voff) do { _Pragma("unroll") for (int _i = 0; _i < 2; ++_i) \
;         __builtin_amdgcn_global_load_lds((const unsigned*)((const char*)(gbase) + (voff)[_i]), (PG8_LAS unsigned*)(lds + (bufoff) + ldsw + _i * 8192), 16, 0, 0); } while (0)
; #define PG8_LDA(dst, b, h) do { _Pragma("unroll") for (int m = 0; m < 4; ++m) _Pragma("unroll") for (int k = 0; k < 2; ++k) dst[m][k] = *(const PG8_LAS bf16x8*)(lds + PG8_SA(b, h) + aoff + m * 2048 + k * 1024); } while (0)
; #define PG8_MMA(ai, bj, At, Bt) do { __builtin_amdgcn_s_setprio(1); _Pragma("unroll") for (int m = 0; m < 4; ++m) _Pragma("unroll") for (int n = 0; n < 2; ++n) _Pragma("unroll") for (int k = 0; k < 2; ++k) \
;         acc[ai][bj][m][n] = __builtin_amdgcn_mfma_f32_16x16x32_bf16(Bt[n][k], At[m][k], acc[ai][bj][m][n], 0, 0, 0); __builtin_amdgcn_s_setprio(0); } while (0)
; #define PG8_WAIT_V(n) asm volatile("s_waitcnt vmcnt(" #n ")" ::: "memory")
; #define PG8_WAIT_L(n) asm volatile("s_waitcnt lgkmcnt(" #n ")" ::: "memory")
; #define PG8_BAR __builtin_amdgcn_s_barrier()
; #define PG8_SCHED __builtin_amdgcn_sched_barrier(0)
; template <class Epi, class Sched, bool ALIGN_EPI = false, bool SP2 = false>
; __device__ __forceinline__ void gemm_phase(PG8_LAS unsigned char* lds, const Gemm g, const Sched& S, const Epi& E) {
;     ...
;             PG8_LDA(At, 1, 1); PG8_STAGE(PG8_SB(1, 0), b3, voffB); PG8_STAGE(PG8_SB(1, 1), b3 + hstep, voffB); PG8_STAGE(PG8_SA(1, 0), a3, voffA);
;             PG8_WAIT_V(8); PG8_WAIT_L(0); PG8_BAR; PG8_MMA(1, 0, At, B0); PG8_MMA(1, 1, At, B1); PG8_BAR; PG8_SCHED;
.Lp1q_skip_5:
	s_setprio 0
	s_barrier
	s_add_i32 s34, s99, s23
	v_lshl_add_u64 v[162:163], v[162:163], 0, s[16:17]
	s_mov_b32 m0, s34
	ds_read_b128 v[206:209], v182 offset:49152
	ds_read_b128 v[210:213], v182 offset:50176
	ds_read_b128 v[214:217], v182 offset:51200
	ds_read_b128 v[218:221], v182 offset:52224
	ds_read_b128 v[222:225], v182 offset:53248
	ds_read_b128 v[226:229], v182 offset:54272
	ds_read_b128 v[230:233], v182 offset:55296
	ds_read_b128 v[234:237], v182 offset:56320
	global_load_lds_dwordx4 v[162:163], off
	s_add_i32 m0, s34, 0x2000
	s_add_u32 s10, s10, 0x40080
	v_lshl_add_u64 v[162:163], v[238:239], 0, s[16:17]
	s_addc_u32 s11, s11, 0
	s_add_i32 s34, s14, s23
	global_load_lds_dwordx4 v[162:163], off
	v_lshl_add_u64 v[162:163], s[10:11], 0, v[142:143]
	s_mov_b32 m0, s34
	s_nop 0
	global_load_lds_dwordx4 v[162:163], off
	v_lshl_add_u64 v[162:163], s[10:11], 0, v[146:147]
	s_add_i32 m0, s34, 0x2000
	s_nop 0
	global_load_lds_dwordx4 v[162:163], off
	v_lshl_add_u64 v[162:163], v[240:241], 0, s[16:17]
	s_mov_b32 m0, s48
	s_nop 0
	global_load_lds_dwordx4 v[162:163], off
	v_lshl_add_u64 v[162:163], v[242:243], 0, s[16:17]
	s_mov_b32 m0, s49
	s_nop 0
	global_load_lds_dwordx4 v[162:163], off
	s_waitcnt vmcnt(8)
	s_waitcnt lgkmcnt(0)
	s_barrier
	s_setprio 1
	s_waitcnt lgkmcnt(0)
	s_bitcmp1_b32 s100, 2
	s_cbranch_scc0 .Lp1q_skip_6
	v_mfma_f32_16x16x32_bf16 v[62:65], v[130:133], v[206:209], v[62:65]
	v_mfma_f32_16x16x32_bf16 v[58:61], v[158:161], v[206:209], v[58:61]
	v_mfma_f32_16x16x32_bf16 v[46:49], v[130:133], v[214:217], v[46:49]
	v_mfma_f32_16x16x32_bf16 v[42:45], v[158:161], v[214:217], v[42:45]
	v_mfma_f32_16x16x32_bf16 v[30:33], v[130:133], v[222:225], v[30:33]
	v_mfma_f32_16x16x32_bf16 v[26:29], v[158:161], v[222:225], v[26:29]
	v_mfma_f32_16x16x32_bf16 v[14:17], v[130:133], v[230:233], v[14:17]
	v_mfma_f32_16x16x32_bf16 v[10:13], v[158:161], v[230:233], v[10:13]
	v_mfma_f32_16x16x32_bf16 v[62:65], v[134:137], v[210:213], v[62:65]
	v_mfma_f32_16x16x32_bf16 v[58:61], v[186:189], v[210:213], v[58:61]
	v_mfma_f32_16x16x32_bf16 v[46:49], v[134:137], v[218:221], v[46:49]
	v_mfma_f32_16x16x32_bf16 v[42:45], v[186:189], v[218:221], v[42:45]
	v_mfma_f32_16x16x32_bf16 v[30:33], v[134:137], v[226:229], v[30:33]
	v_mfma_f32_16x16x32_bf16 v[26:29], v[186:189], v[226:229], v[26:29]
	v_mfma_f32_16x16x32_bf16 v[14:17], v[134:137], v[234:237], v[14:17]
	v_mfma_f32_16x16x32_bf16 v[10:13], v[186:189], v[234:237], v[10:13]

; template <class Epi, class Sched, bool ALIGN_EPI = false, bool SP2 = false>
; __device__ __forceinline__ void gemm_phase(PG8_LAS unsigned char* lds, const Gemm g, const Sched& S, const Epi& E) {
;     ...
;         for (int t = 0; t < nt; t += 2) {
;             const bool last = (t == nt - 2);
;             const char* a1 = cA + (size_t)(t + 1) * kstep;
;             const char* a2 = last ? nA : cA + (size_t)(t + 2) * kstep; const char* b2 = last ? nB : cB + (size_t)(t + 2) * kstep;
;             const char* a3 = a2 + kstep; const char* b3 = b2 + kstep;
.Lp1q_skip_7:
	s_setprio 0
	s_barrier
	s_add_i32 s37, s37, 2
	s_add_u32 s8, s8, 0x100
	s_addc_u32 s9, s9, 0
	s_add_u32 s27, s27, 0x100
	s_addc_u32 s36, s36, 0
	s_cmp_gt_u32 s37, 13
	s_cbranch_scc0 .Lp1q_kloop
	s_branch .Lp1q_kexit
